# phase-0 tail rewritten by hand: wsm fill with 6 wide loads per thread, all 9 rows x loads + g issued up front (counted vmcnt), SMALL reductions 3 columns interleaved, one SMALL store per row
# speedup vs baseline: 1.0159x; 1.0100x over previous
.LBB0_25:
	s_waitcnt lgkmcnt(0)
	s_barrier
	s_load_dwordx2 s[2:3], s[92:93], 0x48
	s_load_dwordx2 s[8:9], s[92:93], 0xe8
	s_load_dwordx2 s[10:11], s[92:93], 0xb0
	s_load_dwordx2 s[20:21], s[92:93], 0x0
	s_load_dwordx2 s[22:23], s[92:93], 0x8
	s_load_dwordx2 s[24:25], s[92:93], 0x40
	v_readlane_b32 s6, v254, 0
	v_readlane_b32 s7, v254, 4
	v_and_b32_e32 v17, 63, v4
	s_lshr_b32 s6, s6, 6
	s_lshl_b32 s7, s7, 3
	s_add_u32 s6, s6, s7
	v_lshlrev_b32_e32 v22, 4, v17
	v_lshlrev_b32_e32 v2, 3, v17
	v_lshlrev_b32_e32 v25, 2, v17
	v_mov_b32_e32 v23, 0x358637bd
	v_mov_b32_e32 v24, 0x3a800000
	s_mov_b32 s5, 0x800000
	s_movk_i32 s12, 0x3830
	v_mul_u32_u24_e32 v0, s12, v4
	v_add_u32_e32 v1, 0x200, v4
	v_mul_u32_u24_e32 v1, s12, v1
	v_add_u32_e32 v0, 0x2810, v0
	v_add_u32_e32 v1, 0x2810, v1
	s_waitcnt lgkmcnt(0)
	global_load_dwordx4 v[26:29], v0, s[2:3] offset:-2064
	global_load_dwordx4 v[30:33], v0, s[2:3] offset:-2048
	global_load_dwordx4 v[34:37], v0, s[2:3] offset:2064
	global_load_dwordx4 v[38:41], v1, s[2:3] offset:-2064
	global_load_dwordx4 v[42:45], v1, s[2:3] offset:-2048
	global_load_dwordx4 v[46:49], v1, s[2:3] offset:2064
	global_load_dwordx4 v[80:83], v22, s[10:11] offset:0
	global_load_dwordx4 v[84:87], v22, s[10:11] offset:1024
	global_load_dwordx4 v[88:91], v22, s[10:11] offset:2048
	global_load_dwordx4 v[92:95], v22, s[10:11] offset:3072
	s_lshl_b32 s13, s6, 12
	s_add_u32 s44, s20, s13
	s_addc_u32 s45, s21, 0
	global_load_dwordx4 v[96:99], v22, s[44:45] offset:0
	global_load_dwordx4 v[100:103], v22, s[44:45] offset:1024
	global_load_dwordx4 v[104:107], v22, s[44:45] offset:2048
	global_load_dwordx4 v[108:111], v22, s[44:45] offset:3072
	s_add_u32 s44, s44, 0x800000
	s_addc_u32 s45, s45, 0
	global_load_dwordx4 v[112:115], v22, s[44:45] offset:0
	global_load_dwordx4 v[116:119], v22, s[44:45] offset:1024
	global_load_dwordx4 v[120:123], v22, s[44:45] offset:2048
	global_load_dwordx4 v[124:127], v22, s[44:45] offset:3072
	s_add_u32 s44, s44, 0x800000
	s_addc_u32 s45, s45, 0
	global_load_dwordx4 v[128:131], v22, s[44:45] offset:0
	global_load_dwordx4 v[132:135], v22, s[44:45] offset:1024
	global_load_dwordx4 v[136:139], v22, s[44:45] offset:2048
	global_load_dwordx4 v[140:143], v22, s[44:45] offset:3072
	s_add_u32 s44, s44, 0x800000
	s_addc_u32 s45, s45, 0
	global_load_dwordx4 v[144:147], v22, s[44:45] offset:0
	global_load_dwordx4 v[148:151], v22, s[44:45] offset:1024
	global_load_dwordx4 v[152:155], v22, s[44:45] offset:2048
	global_load_dwordx4 v[156:159], v22, s[44:45] offset:3072
	s_add_u32 s44, s44, 0x800000
	s_addc_u32 s45, s45, 0
	global_load_dwordx4 v[160:163], v22, s[44:45] offset:0
	global_load_dwordx4 v[164:167], v22, s[44:45] offset:1024
	global_load_dwordx4 v[168:171], v22, s[44:45] offset:2048
	global_load_dwordx4 v[172:175], v22, s[44:45] offset:3072
	s_add_u32 s44, s44, 0x800000
	s_addc_u32 s45, s45, 0
	global_load_dwordx4 v[176:179], v22, s[44:45] offset:0
	global_load_dwordx4 v[180:183], v22, s[44:45] offset:1024
	global_load_dwordx4 v[184:187], v22, s[44:45] offset:2048
	global_load_dwordx4 v[188:191], v22, s[44:45] offset:3072
	s_add_u32 s44, s44, 0x800000
	s_addc_u32 s45, s45, 0
	global_load_dwordx4 v[192:195], v22, s[44:45] offset:0
	global_load_dwordx4 v[196:199], v22, s[44:45] offset:1024
	global_load_dwordx4 v[200:203], v22, s[44:45] offset:2048
	global_load_dwordx4 v[204:207], v22, s[44:45] offset:3072
	s_add_u32 s44, s44, 0x800000
	s_addc_u32 s45, s45, 0
	global_load_dwordx4 v[208:211], v22, s[44:45] offset:0
	global_load_dwordx4 v[212:215], v22, s[44:45] offset:1024
	global_load_dwordx4 v[216:219], v22, s[44:45] offset:2048
	global_load_dwordx4 v[220:223], v22, s[44:45] offset:3072
	s_and_b32 s14, s6, 15
	s_lshl_b32 s14, s14, 12
	s_cmp_lt_u32 s6, 0x400
	s_cselect_b64 s[44:45], s[22:23], s[24:25]
	s_cselect_b32 s14, s13, s14
	s_add_u32 s44, s44, s14
	s_addc_u32 s45, s45, 0
	global_load_dwordx4 v[224:227], v22, s[44:45] offset:0
	global_load_dwordx4 v[228:231], v22, s[44:45] offset:1024
	global_load_dwordx4 v[232:235], v22, s[44:45] offset:2048
	global_load_dwordx4 v[236:239], v22, s[44:45] offset:3072
	s_lshl_b32 s14, s6, 11
	s_add_u32 s40, s8, s14
	s_addc_u32 s41, s9, 0
	s_add_u32 s40, s40, 0xa700000
	s_addc_u32 s41, s41, 0
	s_lshl_b32 s14, s6, 6
	s_add_u32 s42, s8, s14
	s_addc_u32 s43, s9, 0
	s_add_u32 s42, s42, 0x100000
	s_addc_u32 s43, s43, 0
	v_lshlrev_b32_e32 v3, 2, v4
	v_mov_b32_e32 v5, v22
	s_waitcnt vmcnt(40)
	ds_write_b32 v3, v26 offset:0
	ds_write_b32 v3, v27 offset:4096
	ds_write_b32 v3, v28 offset:8192
	ds_write_b32 v3, v29 offset:12288
	ds_write_b32 v3, v30 offset:16384
	ds_write_b32 v3, v31 offset:20480
	ds_write_b32 v3, v32 offset:24576
	ds_write_b32 v3, v33 offset:28672
	ds_write_b32 v3, v34 offset:32768
	ds_write_b32 v3, v35 offset:36864
	ds_write_b32 v3, v36 offset:40960
	ds_write_b32 v3, v37 offset:45056
	ds_write_b32 v3, v38 offset:2048
	ds_write_b32 v3, v39 offset:6144
	ds_write_b32 v3, v40 offset:10240
	ds_write_b32 v3, v41 offset:14336
	ds_write_b32 v3, v42 offset:18432
	ds_write_b32 v3, v43 offset:22528
	ds_write_b32 v3, v44 offset:26624
	ds_write_b32 v3, v45 offset:30720
	ds_write_b32 v3, v46 offset:34816
	ds_write_b32 v3, v47 offset:38912
	ds_write_b32 v3, v48 offset:43008
	ds_write_b32 v3, v49 offset:47104
	s_waitcnt lgkmcnt(0)
	s_barrier
	s_waitcnt vmcnt(32)
	v_pk_mul_f32 v[50:51], v[98:99], v[98:99]
	v_pk_mul_f32 v[52:53], v[96:97], v[96:97]
	v_pk_mul_f32 v[54:55], v[102:103], v[102:103]
	v_pk_mul_f32 v[56:57], v[100:101], v[100:101]
	v_mul_f32_e32 v58, v105, v105
	v_mul_f32_e32 v60, v107, v107
	v_pk_mul_f32 v[64:65], v[108:109], v[108:109]
	v_pk_mul_f32 v[66:67], v[110:111], v[110:111]
	v_add_f32_e32 v52, v53, v52
	v_add_f32_e32 v50, v50, v51
	v_add_f32_e32 v56, v57, v56
	v_add_f32_e32 v54, v54, v55
	v_fma_f32 v58, v104, v104, v58
	v_fma_f32 v60, v106, v106, v60
	v_add_f32_e32 v64, v64, v65
	v_add_f32_e32 v66, v66, v67
	v_add_f32_e32 v52, v52, v50
	v_add_f32_e32 v56, v56, v54
	v_add_f32_e32 v58, v58, v60
	v_add_f32_e32 v64, v64, v66
	v_add_f32_e32 v50, v52, v56
	v_mov_b32_e32 v61, 0
	v_mov_b32_e32 v62, 0
	v_add_f32_e32 v50, v50, v58
	s_nop 0
	v_add_f32_e32 v50, v50, v64
	s_nop 1
	v_add_f32_dpp v50, v50, v50 quad_perm:[1,0,3,2] row_mask:0xf bank_mask:0xf bound_ctrl:1
	s_nop 1
	v_add_f32_dpp v50, v50, v50 quad_perm:[2,3,0,1] row_mask:0xf bank_mask:0xf bound_ctrl:1
	s_nop 1
	v_add_f32_dpp v50, v50, v50 row_half_mirror row_mask:0xf bank_mask:0xf bound_ctrl:1
	s_nop 1
	v_add_f32_dpp v50, v50, v50 row_mirror row_mask:0xf bank_mask:0xf bound_ctrl:1
	s_nop 1
	v_mov_b32_dpp v61, v50 row_bcast:15 row_mask:0xa bank_mask:0xf
	s_nop 1
	v_add_f32_e32 v50, v50, v61
	s_nop 1
	v_mov_b32_dpp v62, v50 row_bcast:31 row_mask:0xc bank_mask:0xf
	s_nop 1
	v_add_f32_e32 v50, v50, v62
	s_nop 0
	v_readlane_b32 s15, v50, 63
	s_nop 1
	v_fma_f32 v50, s15, v24, v23
	v_mul_f32_e32 v51, 0x4b800000, v50
	v_cmp_gt_f32_e32 vcc, s5, v50
	s_nop 1
	v_cndmask_b32_e32 v50, v50, v51, vcc
	v_rsq_f32_e32 v52, v50
	s_nop 0
	v_mul_f32_e32 v53, 0x45800000, v52
	v_cndmask_b32_e32 v52, v52, v53, vcc
	v_pk_mul_f32 v[6:7], v[96:97], v[52:53] op_sel_hi:[1,0]
	v_pk_mul_f32 v[8:9], v[98:99], v[52:53] op_sel_hi:[1,0]
	v_pk_mul_f32 v[10:11], v[100:101], v[52:53] op_sel_hi:[1,0]
	v_pk_mul_f32 v[12:13], v[102:103], v[52:53] op_sel_hi:[1,0]
	v_pk_mul_f32 v[14:15], v[104:105], v[52:53] op_sel_hi:[1,0]
	v_pk_mul_f32 v[16:17], v[106:107], v[52:53] op_sel_hi:[1,0]
	v_pk_mul_f32 v[18:19], v[108:109], v[52:53] op_sel_hi:[1,0]
	v_pk_mul_f32 v[20:21], v[110:111], v[52:53] op_sel_hi:[1,0]
	v_pk_mul_f32 v[6:7], v[80:81], v[6:7]
	v_pk_mul_f32 v[8:9], v[82:83], v[8:9]
	v_pk_mul_f32 v[10:11], v[84:85], v[10:11]
	v_pk_mul_f32 v[12:13], v[86:87], v[12:13]
	v_pk_mul_f32 v[14:15], v[88:89], v[14:15]
	v_pk_mul_f32 v[16:17], v[90:91], v[16:17]
	v_pk_mul_f32 v[18:19], v[92:93], v[18:19]
	v_pk_mul_f32 v[20:21], v[94:95], v[20:21]
	v_cvt_pk_bf16_f32 v240, v6, v7
	v_cvt_pk_bf16_f32 v241, v8, v9
	v_cvt_pk_bf16_f32 v242, v10, v11
	v_cvt_pk_bf16_f32 v243, v12, v13
	v_cvt_pk_bf16_f32 v244, v14, v15
	v_cvt_pk_bf16_f32 v245, v16, v17
	v_cvt_pk_bf16_f32 v246, v18, v19
	v_cvt_pk_bf16_f32 v247, v20, v21
	global_store_dwordx2 v2, v[240:241], s[40:41] offset:0
	global_store_dwordx2 v2, v[242:243], s[40:41] offset:512
	global_store_dwordx2 v2, v[244:245], s[40:41] offset:1024
	global_store_dwordx2 v2, v[246:247], s[40:41] offset:1536
	ds_read_b128 v[26:29], v5 offset:0
	ds_read_b128 v[30:33], v5 offset:1024
	ds_read_b128 v[34:37], v5 offset:2048
	ds_read_b128 v[38:41], v5 offset:3072
	ds_read_b128 v[42:45], v5 offset:4096
	ds_read_b128 v[46:49], v5 offset:5120
	ds_read_b128 v[50:53], v5 offset:6144
	ds_read_b128 v[54:57], v5 offset:7168
	ds_read_b128 v[58:61], v5 offset:8192
	ds_read_b128 v[62:65], v5 offset:9216
	ds_read_b128 v[66:69], v5 offset:10240
	ds_read_b128 v[70:73], v5 offset:11264
	s_waitcnt lgkmcnt(8)
	v_pk_fma_f32 v[28:29], v[8:9], v[28:29], 0 op_sel_hi:[1,1,0]
	v_pk_fma_f32 v[26:27], v[6:7], v[26:27], 0 op_sel_hi:[1,1,0]
	v_pk_fma_f32 v[28:29], v[12:13], v[32:33], v[28:29]
	v_pk_fma_f32 v[26:27], v[10:11], v[30:31], v[26:27]
	v_pk_fma_f32 v[28:29], v[16:17], v[36:37], v[28:29]
	v_pk_fma_f32 v[26:27], v[14:15], v[34:35], v[26:27]
	v_pk_fma_f32 v[28:29], v[20:21], v[40:41], v[28:29]
	v_pk_fma_f32 v[26:27], v[18:19], v[38:39], v[26:27]
	s_waitcnt lgkmcnt(4)
	v_pk_fma_f32 v[44:45], v[8:9], v[44:45], 0 op_sel_hi:[1,1,0]
	v_pk_fma_f32 v[42:43], v[6:7], v[42:43], 0 op_sel_hi:[1,1,0]
	v_pk_fma_f32 v[44:45], v[12:13], v[48:49], v[44:45]
	v_pk_fma_f32 v[42:43], v[10:11], v[46:47], v[42:43]
	v_pk_fma_f32 v[44:45], v[16:17], v[52:53], v[44:45]
	v_pk_fma_f32 v[42:43], v[14:15], v[50:51], v[42:43]
	v_pk_fma_f32 v[44:45], v[20:21], v[56:57], v[44:45]
	v_pk_fma_f32 v[42:43], v[18:19], v[54:55], v[42:43]
	s_waitcnt lgkmcnt(0)
	v_pk_fma_f32 v[60:61], v[8:9], v[60:61], 0 op_sel_hi:[1,1,0]
	v_pk_fma_f32 v[58:59], v[6:7], v[58:59], 0 op_sel_hi:[1,1,0]
	v_pk_fma_f32 v[60:61], v[12:13], v[64:65], v[60:61]
	v_pk_fma_f32 v[58:59], v[10:11], v[62:63], v[58:59]
	v_pk_fma_f32 v[60:61], v[16:17], v[68:69], v[60:61]
	v_pk_fma_f32 v[58:59], v[14:15], v[66:67], v[58:59]
	v_pk_fma_f32 v[60:61], v[20:21], v[72:73], v[60:61]
	v_pk_fma_f32 v[58:59], v[18:19], v[70:71], v[58:59]
	v_add_f32_e32 v30, v28, v29
	v_add_f32_e32 v46, v44, v45
	v_add_f32_e32 v62, v60, v61
	v_add_f32_e32 v26, v26, v27
	v_add_f32_e32 v42, v42, v43
	v_add_f32_e32 v58, v58, v59
	v_mov_b32_e32 v31, 0
	v_mov_b32_e32 v47, 0
	v_mov_b32_e32 v63, 0
	v_add_f32_e32 v26, v26, v30
	v_add_f32_e32 v42, v42, v46
	v_add_f32_e32 v58, v58, v62
	v_mov_b32_e32 v32, 0
	v_mov_b32_e32 v48, 0
	v_mov_b32_e32 v64, 0
	v_add_f32_dpp v26, v26, v26 quad_perm:[1,0,3,2] row_mask:0xf bank_mask:0xf bound_ctrl:1
	v_add_f32_dpp v42, v42, v42 quad_perm:[1,0,3,2] row_mask:0xf bank_mask:0xf bound_ctrl:1
	v_add_f32_dpp v58, v58, v58 quad_perm:[1,0,3,2] row_mask:0xf bank_mask:0xf bound_ctrl:1
	v_add_f32_dpp v26, v26, v26 quad_perm:[2,3,0,1] row_mask:0xf bank_mask:0xf bound_ctrl:1
	v_add_f32_dpp v42, v42, v42 quad_perm:[2,3,0,1] row_mask:0xf bank_mask:0xf bound_ctrl:1
	v_add_f32_dpp v58, v58, v58 quad_perm:[2,3,0,1] row_mask:0xf bank_mask:0xf bound_ctrl:1
	v_add_f32_dpp v26, v26, v26 row_half_mirror row_mask:0xf bank_mask:0xf bound_ctrl:1
	v_add_f32_dpp v42, v42, v42 row_half_mirror row_mask:0xf bank_mask:0xf bound_ctrl:1
	v_add_f32_dpp v58, v58, v58 row_half_mirror row_mask:0xf bank_mask:0xf bound_ctrl:1
	v_add_f32_dpp v26, v26, v26 row_mirror row_mask:0xf bank_mask:0xf bound_ctrl:1
	v_add_f32_dpp v42, v42, v42 row_mirror row_mask:0xf bank_mask:0xf bound_ctrl:1
	v_add_f32_dpp v58, v58, v58 row_mirror row_mask:0xf bank_mask:0xf bound_ctrl:1
	v_mov_b32_dpp v31, v26 row_bcast:15 row_mask:0xa bank_mask:0xf
	v_mov_b32_dpp v47, v42 row_bcast:15 row_mask:0xa bank_mask:0xf
	v_mov_b32_dpp v63, v58 row_bcast:15 row_mask:0xa bank_mask:0xf
	v_add_f32_e32 v26, v26, v31
	v_add_f32_e32 v42, v42, v47
	v_add_f32_e32 v58, v58, v63
	v_mov_b32_dpp v32, v26 row_bcast:31 row_mask:0xc bank_mask:0xf
	v_mov_b32_dpp v48, v42 row_bcast:31 row_mask:0xc bank_mask:0xf
	v_mov_b32_dpp v64, v58 row_bcast:31 row_mask:0xc bank_mask:0xf
	v_add_f32_e32 v26, v26, v32
	v_add_f32_e32 v42, v42, v48
	v_add_f32_e32 v58, v58, v64
	s_nop 0
	v_readlane_b32 s16, v26, 63
	v_readlane_b32 s17, v42, 63
	v_readlane_b32 s18, v58, 63
	v_writelane_b32 v1, s16, 0
	v_writelane_b32 v1, s17, 1
	v_writelane_b32 v1, s18, 2
	ds_read_b128 v[26:29], v5 offset:12288
	ds_read_b128 v[30:33], v5 offset:13312
	ds_read_b128 v[34:37], v5 offset:14336
	ds_read_b128 v[38:41], v5 offset:15360
	ds_read_b128 v[42:45], v5 offset:16384
	ds_read_b128 v[46:49], v5 offset:17408
	ds_read_b128 v[50:53], v5 offset:18432
	ds_read_b128 v[54:57], v5 offset:19456
	ds_read_b128 v[58:61], v5 offset:20480
	ds_read_b128 v[62:65], v5 offset:21504
	ds_read_b128 v[66:69], v5 offset:22528
	ds_read_b128 v[70:73], v5 offset:23552
	s_waitcnt lgkmcnt(8)
	v_pk_fma_f32 v[28:29], v[8:9], v[28:29], 0 op_sel_hi:[1,1,0]
	v_pk_fma_f32 v[26:27], v[6:7], v[26:27], 0 op_sel_hi:[1,1,0]
	v_pk_fma_f32 v[28:29], v[12:13], v[32:33], v[28:29]
	v_pk_fma_f32 v[26:27], v[10:11], v[30:31], v[26:27]
	v_pk_fma_f32 v[28:29], v[16:17], v[36:37], v[28:29]
	v_pk_fma_f32 v[26:27], v[14:15], v[34:35], v[26:27]
	v_pk_fma_f32 v[28:29], v[20:21], v[40:41], v[28:29]
	v_pk_fma_f32 v[26:27], v[18:19], v[38:39], v[26:27]
	s_waitcnt lgkmcnt(4)
	v_pk_fma_f32 v[44:45], v[8:9], v[44:45], 0 op_sel_hi:[1,1,0]
	v_pk_fma_f32 v[42:43], v[6:7], v[42:43], 0 op_sel_hi:[1,1,0]
	v_pk_fma_f32 v[44:45], v[12:13], v[48:49], v[44:45]
	v_pk_fma_f32 v[42:43], v[10:11], v[46:47], v[42:43]
	v_pk_fma_f32 v[44:45], v[16:17], v[52:53], v[44:45]
	v_pk_fma_f32 v[42:43], v[14:15], v[50:51], v[42:43]
	v_pk_fma_f32 v[44:45], v[20:21], v[56:57], v[44:45]
	v_pk_fma_f32 v[42:43], v[18:19], v[54:55], v[42:43]
	s_waitcnt lgkmcnt(0)
	v_pk_fma_f32 v[60:61], v[8:9], v[60:61], 0 op_sel_hi:[1,1,0]
	v_pk_fma_f32 v[58:59], v[6:7], v[58:59], 0 op_sel_hi:[1,1,0]
	v_pk_fma_f32 v[60:61], v[12:13], v[64:65], v[60:61]
	v_pk_fma_f32 v[58:59], v[10:11], v[62:63], v[58:59]
	v_pk_fma_f32 v[60:61], v[16:17], v[68:69], v[60:61]
	v_pk_fma_f32 v[58:59], v[14:15], v[66:67], v[58:59]
	v_pk_fma_f32 v[60:61], v[20:21], v[72:73], v[60:61]
	v_pk_fma_f32 v[58:59], v[18:19], v[70:71], v[58:59]
	v_add_f32_e32 v30, v28, v29
	v_add_f32_e32 v46, v44, v45
	v_add_f32_e32 v62, v60, v61
	v_add_f32_e32 v26, v26, v27
	v_add_f32_e32 v42, v42, v43
	v_add_f32_e32 v58, v58, v59
	v_mov_b32_e32 v31, 0
	v_mov_b32_e32 v47, 0
	v_mov_b32_e32 v63, 0
	v_add_f32_e32 v26, v26, v30
	v_add_f32_e32 v42, v42, v46
	v_add_f32_e32 v58, v58, v62
	v_mov_b32_e32 v32, 0
	v_mov_b32_e32 v48, 0
	v_mov_b32_e32 v64, 0
	v_add_f32_dpp v26, v26, v26 quad_perm:[1,0,3,2] row_mask:0xf bank_mask:0xf bound_ctrl:1
	v_add_f32_dpp v42, v42, v42 quad_perm:[1,0,3,2] row_mask:0xf bank_mask:0xf bound_ctrl:1
	v_add_f32_dpp v58, v58, v58 quad_perm:[1,0,3,2] row_mask:0xf bank_mask:0xf bound_ctrl:1
	v_add_f32_dpp v26, v26, v26 quad_perm:[2,3,0,1] row_mask:0xf bank_mask:0xf bound_ctrl:1
	v_add_f32_dpp v42, v42, v42 quad_perm:[2,3,0,1] row_mask:0xf bank_mask:0xf bound_ctrl:1
	v_add_f32_dpp v58, v58, v58 quad_perm:[2,3,0,1] row_mask:0xf bank_mask:0xf bound_ctrl:1
	v_add_f32_dpp v26, v26, v26 row_half_mirror row_mask:0xf bank_mask:0xf bound_ctrl:1
	v_add_f32_dpp v42, v42, v42 row_half_mirror row_mask:0xf bank_mask:0xf bound_ctrl:1
	v_add_f32_dpp v58, v58, v58 row_half_mirror row_mask:0xf bank_mask:0xf bound_ctrl:1
	v_add_f32_dpp v26, v26, v26 row_mirror row_mask:0xf bank_mask:0xf bound_ctrl:1
	v_add_f32_dpp v42, v42, v42 row_mirror row_mask:0xf bank_mask:0xf bound_ctrl:1
	v_add_f32_dpp v58, v58, v58 row_mirror row_mask:0xf bank_mask:0xf bound_ctrl:1
	v_mov_b32_dpp v31, v26 row_bcast:15 row_mask:0xa bank_mask:0xf
	v_mov_b32_dpp v47, v42 row_bcast:15 row_mask:0xa bank_mask:0xf
	v_mov_b32_dpp v63, v58 row_bcast:15 row_mask:0xa bank_mask:0xf
	v_add_f32_e32 v26, v26, v31
	v_add_f32_e32 v42, v42, v47
	v_add_f32_e32 v58, v58, v63
	v_mov_b32_dpp v32, v26 row_bcast:31 row_mask:0xc bank_mask:0xf
	v_mov_b32_dpp v48, v42 row_bcast:31 row_mask:0xc bank_mask:0xf
	v_mov_b32_dpp v64, v58 row_bcast:31 row_mask:0xc bank_mask:0xf
	v_add_f32_e32 v26, v26, v32
	v_add_f32_e32 v42, v42, v48
	v_add_f32_e32 v58, v58, v64
	s_nop 0
	v_readlane_b32 s16, v26, 63
	v_readlane_b32 s17, v42, 63
	v_readlane_b32 s18, v58, 63
	v_writelane_b32 v1, s16, 3
	v_writelane_b32 v1, s17, 4
	v_writelane_b32 v1, s18, 5
	ds_read_b128 v[26:29], v5 offset:24576
	ds_read_b128 v[30:33], v5 offset:25600
	ds_read_b128 v[34:37], v5 offset:26624
	ds_read_b128 v[38:41], v5 offset:27648
	ds_read_b128 v[42:45], v5 offset:28672
	ds_read_b128 v[46:49], v5 offset:29696
	ds_read_b128 v[50:53], v5 offset:30720
	ds_read_b128 v[54:57], v5 offset:31744
	ds_read_b128 v[58:61], v5 offset:32768
	ds_read_b128 v[62:65], v5 offset:33792
	ds_read_b128 v[66:69], v5 offset:34816
	ds_read_b128 v[70:73], v5 offset:35840
	s_waitcnt lgkmcnt(8)
	v_pk_fma_f32 v[28:29], v[8:9], v[28:29], 0 op_sel_hi:[1,1,0]
	v_pk_fma_f32 v[26:27], v[6:7], v[26:27], 0 op_sel_hi:[1,1,0]
	v_pk_fma_f32 v[28:29], v[12:13], v[32:33], v[28:29]
	v_pk_fma_f32 v[26:27], v[10:11], v[30:31], v[26:27]
	v_pk_fma_f32 v[28:29], v[16:17], v[36:37], v[28:29]
	v_pk_fma_f32 v[26:27], v[14:15], v[34:35], v[26:27]
	v_pk_fma_f32 v[28:29], v[20:21], v[40:41], v[28:29]
	v_pk_fma_f32 v[26:27], v[18:19], v[38:39], v[26:27]
	s_waitcnt lgkmcnt(4)
	v_pk_fma_f32 v[44:45], v[8:9], v[44:45], 0 op_sel_hi:[1,1,0]
	v_pk_fma_f32 v[42:43], v[6:7], v[42:43], 0 op_sel_hi:[1,1,0]
	v_pk_fma_f32 v[44:45], v[12:13], v[48:49], v[44:45]
	v_pk_fma_f32 v[42:43], v[10:11], v[46:47], v[42:43]
	v_pk_fma_f32 v[44:45], v[16:17], v[52:53], v[44:45]
	v_pk_fma_f32 v[42:43], v[14:15], v[50:51], v[42:43]
	v_pk_fma_f32 v[44:45], v[20:21], v[56:57], v[44:45]
	v_pk_fma_f32 v[42:43], v[18:19], v[54:55], v[42:43]
	s_waitcnt lgkmcnt(0)
	v_pk_fma_f32 v[60:61], v[8:9], v[60:61], 0 op_sel_hi:[1,1,0]
	v_pk_fma_f32 v[58:59], v[6:7], v[58:59], 0 op_sel_hi:[1,1,0]
	v_pk_fma_f32 v[60:61], v[12:13], v[64:65], v[60:61]
	v_pk_fma_f32 v[58:59], v[10:11], v[62:63], v[58:59]
	v_pk_fma_f32 v[60:61], v[16:17], v[68:69], v[60:61]
	v_pk_fma_f32 v[58:59], v[14:15], v[66:67], v[58:59]
	v_pk_fma_f32 v[60:61], v[20:21], v[72:73], v[60:61]
	v_pk_fma_f32 v[58:59], v[18:19], v[70:71], v[58:59]
	v_add_f32_e32 v30, v28, v29
	v_add_f32_e32 v46, v44, v45
	v_add_f32_e32 v62, v60, v61
	v_add_f32_e32 v26, v26, v27
	v_add_f32_e32 v42, v42, v43
	v_add_f32_e32 v58, v58, v59
	v_mov_b32_e32 v31, 0
	v_mov_b32_e32 v47, 0
	v_mov_b32_e32 v63, 0
	v_add_f32_e32 v26, v26, v30
	v_add_f32_e32 v42, v42, v46
	v_add_f32_e32 v58, v58, v62
	v_mov_b32_e32 v32, 0
	v_mov_b32_e32 v48, 0
	v_mov_b32_e32 v64, 0
	v_add_f32_dpp v26, v26, v26 quad_perm:[1,0,3,2] row_mask:0xf bank_mask:0xf bound_ctrl:1
	v_add_f32_dpp v42, v42, v42 quad_perm:[1,0,3,2] row_mask:0xf bank_mask:0xf bound_ctrl:1
	v_add_f32_dpp v58, v58, v58 quad_perm:[1,0,3,2] row_mask:0xf bank_mask:0xf bound_ctrl:1
	v_add_f32_dpp v26, v26, v26 quad_perm:[2,3,0,1] row_mask:0xf bank_mask:0xf bound_ctrl:1
	v_add_f32_dpp v42, v42, v42 quad_perm:[2,3,0,1] row_mask:0xf bank_mask:0xf bound_ctrl:1
	v_add_f32_dpp v58, v58, v58 quad_perm:[2,3,0,1] row_mask:0xf bank_mask:0xf bound_ctrl:1
	v_add_f32_dpp v26, v26, v26 row_half_mirror row_mask:0xf bank_mask:0xf bound_ctrl:1
	v_add_f32_dpp v42, v42, v42 row_half_mirror row_mask:0xf bank_mask:0xf bound_ctrl:1
	v_add_f32_dpp v58, v58, v58 row_half_mirror row_mask:0xf bank_mask:0xf bound_ctrl:1
	v_add_f32_dpp v26, v26, v26 row_mirror row_mask:0xf bank_mask:0xf bound_ctrl:1
	v_add_f32_dpp v42, v42, v42 row_mirror row_mask:0xf bank_mask:0xf bound_ctrl:1
	v_add_f32_dpp v58, v58, v58 row_mirror row_mask:0xf bank_mask:0xf bound_ctrl:1
	v_mov_b32_dpp v31, v26 row_bcast:15 row_mask:0xa bank_mask:0xf
	v_mov_b32_dpp v47, v42 row_bcast:15 row_mask:0xa bank_mask:0xf
	v_mov_b32_dpp v63, v58 row_bcast:15 row_mask:0xa bank_mask:0xf
	v_add_f32_e32 v26, v26, v31
	v_add_f32_e32 v42, v42, v47
	v_add_f32_e32 v58, v58, v63
	v_mov_b32_dpp v32, v26 row_bcast:31 row_mask:0xc bank_mask:0xf
	v_mov_b32_dpp v48, v42 row_bcast:31 row_mask:0xc bank_mask:0xf
	v_mov_b32_dpp v64, v58 row_bcast:31 row_mask:0xc bank_mask:0xf
	v_add_f32_e32 v26, v26, v32
	v_add_f32_e32 v42, v42, v48
	v_add_f32_e32 v58, v58, v64
	s_nop 0
	v_readlane_b32 s16, v26, 63
	v_readlane_b32 s17, v42, 63
	v_readlane_b32 s18, v58, 63
	v_writelane_b32 v1, s16, 6
	v_writelane_b32 v1, s17, 7
	v_writelane_b32 v1, s18, 8
	ds_read_b128 v[26:29], v5 offset:36864
	ds_read_b128 v[30:33], v5 offset:37888
	ds_read_b128 v[34:37], v5 offset:38912
	ds_read_b128 v[38:41], v5 offset:39936
	ds_read_b128 v[42:45], v5 offset:40960
	ds_read_b128 v[46:49], v5 offset:41984
	ds_read_b128 v[50:53], v5 offset:43008
	ds_read_b128 v[54:57], v5 offset:44032
	ds_read_b128 v[58:61], v5 offset:45056
	ds_read_b128 v[62:65], v5 offset:46080
	ds_read_b128 v[66:69], v5 offset:47104
	ds_read_b128 v[70:73], v5 offset:48128
	s_waitcnt lgkmcnt(8)
	v_pk_fma_f32 v[28:29], v[8:9], v[28:29], 0 op_sel_hi:[1,1,0]
	v_pk_fma_f32 v[26:27], v[6:7], v[26:27], 0 op_sel_hi:[1,1,0]
	v_pk_fma_f32 v[28:29], v[12:13], v[32:33], v[28:29]
	v_pk_fma_f32 v[26:27], v[10:11], v[30:31], v[26:27]
	v_pk_fma_f32 v[28:29], v[16:17], v[36:37], v[28:29]
	v_pk_fma_f32 v[26:27], v[14:15], v[34:35], v[26:27]
	v_pk_fma_f32 v[28:29], v[20:21], v[40:41], v[28:29]
	v_pk_fma_f32 v[26:27], v[18:19], v[38:39], v[26:27]
	s_waitcnt lgkmcnt(4)
	v_pk_fma_f32 v[44:45], v[8:9], v[44:45], 0 op_sel_hi:[1,1,0]
	v_pk_fma_f32 v[42:43], v[6:7], v[42:43], 0 op_sel_hi:[1,1,0]
	v_pk_fma_f32 v[44:45], v[12:13], v[48:49], v[44:45]
	v_pk_fma_f32 v[42:43], v[10:11], v[46:47], v[42:43]
	v_pk_fma_f32 v[44:45], v[16:17], v[52:53], v[44:45]
	v_pk_fma_f32 v[42:43], v[14:15], v[50:51], v[42:43]
	v_pk_fma_f32 v[44:45], v[20:21], v[56:57], v[44:45]
	v_pk_fma_f32 v[42:43], v[18:19], v[54:55], v[42:43]
	s_waitcnt lgkmcnt(0)
	v_pk_fma_f32 v[60:61], v[8:9], v[60:61], 0 op_sel_hi:[1,1,0]
	v_pk_fma_f32 v[58:59], v[6:7], v[58:59], 0 op_sel_hi:[1,1,0]
	v_pk_fma_f32 v[60:61], v[12:13], v[64:65], v[60:61]
	v_pk_fma_f32 v[58:59], v[10:11], v[62:63], v[58:59]
	v_pk_fma_f32 v[60:61], v[16:17], v[68:69], v[60:61]
	v_pk_fma_f32 v[58:59], v[14:15], v[66:67], v[58:59]
	v_pk_fma_f32 v[60:61], v[20:21], v[72:73], v[60:61]
	v_pk_fma_f32 v[58:59], v[18:19], v[70:71], v[58:59]
	v_add_f32_e32 v30, v28, v29
	v_add_f32_e32 v46, v44, v45
	v_add_f32_e32 v62, v60, v61
	v_add_f32_e32 v26, v26, v27
	v_add_f32_e32 v42, v42, v43
	v_add_f32_e32 v58, v58, v59
	v_mov_b32_e32 v31, 0
	v_mov_b32_e32 v47, 0
	v_mov_b32_e32 v63, 0
	v_add_f32_e32 v26, v26, v30
	v_add_f32_e32 v42, v42, v46
	v_add_f32_e32 v58, v58, v62
	v_mov_b32_e32 v32, 0
	v_mov_b32_e32 v48, 0
	v_mov_b32_e32 v64, 0
	v_add_f32_dpp v26, v26, v26 quad_perm:[1,0,3,2] row_mask:0xf bank_mask:0xf bound_ctrl:1
	v_add_f32_dpp v42, v42, v42 quad_perm:[1,0,3,2] row_mask:0xf bank_mask:0xf bound_ctrl:1
	v_add_f32_dpp v58, v58, v58 quad_perm:[1,0,3,2] row_mask:0xf bank_mask:0xf bound_ctrl:1
	v_add_f32_dpp v26, v26, v26 quad_perm:[2,3,0,1] row_mask:0xf bank_mask:0xf bound_ctrl:1
	v_add_f32_dpp v42, v42, v42 quad_perm:[2,3,0,1] row_mask:0xf bank_mask:0xf bound_ctrl:1
	v_add_f32_dpp v58, v58, v58 quad_perm:[2,3,0,1] row_mask:0xf bank_mask:0xf bound_ctrl:1
	v_add_f32_dpp v26, v26, v26 row_half_mirror row_mask:0xf bank_mask:0xf bound_ctrl:1
	v_add_f32_dpp v42, v42, v42 row_half_mirror row_mask:0xf bank_mask:0xf bound_ctrl:1
	v_add_f32_dpp v58, v58, v58 row_half_mirror row_mask:0xf bank_mask:0xf bound_ctrl:1
	v_add_f32_dpp v26, v26, v26 row_mirror row_mask:0xf bank_mask:0xf bound_ctrl:1
	v_add_f32_dpp v42, v42, v42 row_mirror row_mask:0xf bank_mask:0xf bound_ctrl:1
	v_add_f32_dpp v58, v58, v58 row_mirror row_mask:0xf bank_mask:0xf bound_ctrl:1
	v_mov_b32_dpp v31, v26 row_bcast:15 row_mask:0xa bank_mask:0xf
	v_mov_b32_dpp v47, v42 row_bcast:15 row_mask:0xa bank_mask:0xf
	v_mov_b32_dpp v63, v58 row_bcast:15 row_mask:0xa bank_mask:0xf
	v_add_f32_e32 v26, v26, v31
	v_add_f32_e32 v42, v42, v47
	v_add_f32_e32 v58, v58, v63
	v_mov_b32_dpp v32, v26 row_bcast:31 row_mask:0xc bank_mask:0xf
	v_mov_b32_dpp v48, v42 row_bcast:31 row_mask:0xc bank_mask:0xf
	v_mov_b32_dpp v64, v58 row_bcast:31 row_mask:0xc bank_mask:0xf
	v_add_f32_e32 v26, v26, v32
	v_add_f32_e32 v42, v42, v48
	v_add_f32_e32 v58, v58, v64
	s_nop 0
	v_readlane_b32 s16, v26, 63
	v_readlane_b32 s17, v42, 63
	v_readlane_b32 s18, v58, 63
	v_writelane_b32 v1, s16, 9
	v_writelane_b32 v1, s17, 10
	v_writelane_b32 v1, s18, 11
	s_mov_b64 s[26:27], exec
	s_mov_b32 exec_lo, 0xfff
	s_mov_b32 exec_hi, 0
	global_store_dword v25, v1, s[42:43]
	s_mov_b64 exec, s[26:27]
	s_add_u32 s40, s40, 0x400000
	s_addc_u32 s41, s41, 0
	s_add_u32 s42, s42, 0x20000
	s_addc_u32 s43, s43, 0
	s_waitcnt vmcnt(33)
	v_pk_mul_f32 v[50:51], v[114:115], v[114:115]
	v_pk_mul_f32 v[52:53], v[112:113], v[112:113]
	v_pk_mul_f32 v[54:55], v[118:119], v[118:119]
	v_pk_mul_f32 v[56:57], v[116:117], v[116:117]
	v_mul_f32_e32 v58, v121, v121
	v_mul_f32_e32 v60, v123, v123
	v_pk_mul_f32 v[64:65], v[124:125], v[124:125]
	v_pk_mul_f32 v[66:67], v[126:127], v[126:127]
	v_add_f32_e32 v52, v53, v52
	v_add_f32_e32 v50, v50, v51
	v_add_f32_e32 v56, v57, v56
	v_add_f32_e32 v54, v54, v55
	v_fma_f32 v58, v120, v120, v58
	v_fma_f32 v60, v122, v122, v60
	v_add_f32_e32 v64, v64, v65
	v_add_f32_e32 v66, v66, v67
	v_add_f32_e32 v52, v52, v50
	v_add_f32_e32 v56, v56, v54
	v_add_f32_e32 v58, v58, v60
	v_add_f32_e32 v64, v64, v66
	v_add_f32_e32 v50, v52, v56
	v_mov_b32_e32 v61, 0
	v_mov_b32_e32 v62, 0
	v_add_f32_e32 v50, v50, v58
	s_nop 0
	v_add_f32_e32 v50, v50, v64
	s_nop 1
	v_add_f32_dpp v50, v50, v50 quad_perm:[1,0,3,2] row_mask:0xf bank_mask:0xf bound_ctrl:1
	s_nop 1
	v_add_f32_dpp v50, v50, v50 quad_perm:[2,3,0,1] row_mask:0xf bank_mask:0xf bound_ctrl:1
	s_nop 1
	v_add_f32_dpp v50, v50, v50 row_half_mirror row_mask:0xf bank_mask:0xf bound_ctrl:1
	s_nop 1
	v_add_f32_dpp v50, v50, v50 row_mirror row_mask:0xf bank_mask:0xf bound_ctrl:1
	s_nop 1
	v_mov_b32_dpp v61, v50 row_bcast:15 row_mask:0xa bank_mask:0xf
	s_nop 1
	v_add_f32_e32 v50, v50, v61
	s_nop 1
	v_mov_b32_dpp v62, v50 row_bcast:31 row_mask:0xc bank_mask:0xf
	s_nop 1
	v_add_f32_e32 v50, v50, v62
	s_nop 0
	v_readlane_b32 s15, v50, 63
	s_nop 1
	v_fma_f32 v50, s15, v24, v23
	v_mul_f32_e32 v51, 0x4b800000, v50
	v_cmp_gt_f32_e32 vcc, s5, v50
	s_nop 1
	v_cndmask_b32_e32 v50, v50, v51, vcc
	v_rsq_f32_e32 v52, v50
	s_nop 0
	v_mul_f32_e32 v53, 0x45800000, v52
	v_cndmask_b32_e32 v52, v52, v53, vcc
	v_pk_mul_f32 v[6:7], v[112:113], v[52:53] op_sel_hi:[1,0]
	v_pk_mul_f32 v[8:9], v[114:115], v[52:53] op_sel_hi:[1,0]
	v_pk_mul_f32 v[10:11], v[116:117], v[52:53] op_sel_hi:[1,0]
	v_pk_mul_f32 v[12:13], v[118:119], v[52:53] op_sel_hi:[1,0]
	v_pk_mul_f32 v[14:15], v[120:121], v[52:53] op_sel_hi:[1,0]
	v_pk_mul_f32 v[16:17], v[122:123], v[52:53] op_sel_hi:[1,0]
	v_pk_mul_f32 v[18:19], v[124:125], v[52:53] op_sel_hi:[1,0]
	v_pk_mul_f32 v[20:21], v[126:127], v[52:53] op_sel_hi:[1,0]
	v_pk_mul_f32 v[6:7], v[80:81], v[6:7]
	v_pk_mul_f32 v[8:9], v[82:83], v[8:9]
	v_pk_mul_f32 v[10:11], v[84:85], v[10:11]
	v_pk_mul_f32 v[12:13], v[86:87], v[12:13]
	v_pk_mul_f32 v[14:15], v[88:89], v[14:15]
	v_pk_mul_f32 v[16:17], v[90:91], v[16:17]
	v_pk_mul_f32 v[18:19], v[92:93], v[18:19]
	v_pk_mul_f32 v[20:21], v[94:95], v[20:21]
	v_cvt_pk_bf16_f32 v240, v6, v7
	v_cvt_pk_bf16_f32 v241, v8, v9
	v_cvt_pk_bf16_f32 v242, v10, v11
	v_cvt_pk_bf16_f32 v243, v12, v13
	v_cvt_pk_bf16_f32 v244, v14, v15
	v_cvt_pk_bf16_f32 v245, v16, v17
	v_cvt_pk_bf16_f32 v246, v18, v19
	v_cvt_pk_bf16_f32 v247, v20, v21
	global_store_dwordx2 v2, v[240:241], s[40:41] offset:0
	global_store_dwordx2 v2, v[242:243], s[40:41] offset:512
	global_store_dwordx2 v2, v[244:245], s[40:41] offset:1024
	global_store_dwordx2 v2, v[246:247], s[40:41] offset:1536
	ds_read_b128 v[26:29], v5 offset:0
	ds_read_b128 v[30:33], v5 offset:1024
	ds_read_b128 v[34:37], v5 offset:2048
	ds_read_b128 v[38:41], v5 offset:3072
	ds_read_b128 v[42:45], v5 offset:4096
	ds_read_b128 v[46:49], v5 offset:5120
	ds_read_b128 v[50:53], v5 offset:6144
	ds_read_b128 v[54:57], v5 offset:7168
	ds_read_b128 v[58:61], v5 offset:8192
	ds_read_b128 v[62:65], v5 offset:9216
	ds_read_b128 v[66:69], v5 offset:10240
	ds_read_b128 v[70:73], v5 offset:11264
	s_waitcnt lgkmcnt(8)
	v_pk_fma_f32 v[28:29], v[8:9], v[28:29], 0 op_sel_hi:[1,1,0]
	v_pk_fma_f32 v[26:27], v[6:7], v[26:27], 0 op_sel_hi:[1,1,0]
	v_pk_fma_f32 v[28:29], v[12:13], v[32:33], v[28:29]
	v_pk_fma_f32 v[26:27], v[10:11], v[30:31], v[26:27]
	v_pk_fma_f32 v[28:29], v[16:17], v[36:37], v[28:29]
	v_pk_fma_f32 v[26:27], v[14:15], v[34:35], v[26:27]
	v_pk_fma_f32 v[28:29], v[20:21], v[40:41], v[28:29]
	v_pk_fma_f32 v[26:27], v[18:19], v[38:39], v[26:27]
	s_waitcnt lgkmcnt(4)
	v_pk_fma_f32 v[44:45], v[8:9], v[44:45], 0 op_sel_hi:[1,1,0]
	v_pk_fma_f32 v[42:43], v[6:7], v[42:43], 0 op_sel_hi:[1,1,0]
	v_pk_fma_f32 v[44:45], v[12:13], v[48:49], v[44:45]
	v_pk_fma_f32 v[42:43], v[10:11], v[46:47], v[42:43]
	v_pk_fma_f32 v[44:45], v[16:17], v[52:53], v[44:45]
	v_pk_fma_f32 v[42:43], v[14:15], v[50:51], v[42:43]
	v_pk_fma_f32 v[44:45], v[20:21], v[56:57], v[44:45]
	v_pk_fma_f32 v[42:43], v[18:19], v[54:55], v[42:43]
	s_waitcnt lgkmcnt(0)
	v_pk_fma_f32 v[60:61], v[8:9], v[60:61], 0 op_sel_hi:[1,1,0]
	v_pk_fma_f32 v[58:59], v[6:7], v[58:59], 0 op_sel_hi:[1,1,0]
	v_pk_fma_f32 v[60:61], v[12:13], v[64:65], v[60:61]
	v_pk_fma_f32 v[58:59], v[10:11], v[62:63], v[58:59]
	v_pk_fma_f32 v[60:61], v[16:17], v[68:69], v[60:61]
	v_pk_fma_f32 v[58:59], v[14:15], v[66:67], v[58:59]
	v_pk_fma_f32 v[60:61], v[20:21], v[72:73], v[60:61]
	v_pk_fma_f32 v[58:59], v[18:19], v[70:71], v[58:59]
	v_add_f32_e32 v30, v28, v29
	v_add_f32_e32 v46, v44, v45
	v_add_f32_e32 v62, v60, v61
	v_add_f32_e32 v26, v26, v27
	v_add_f32_e32 v42, v42, v43
	v_add_f32_e32 v58, v58, v59
	v_mov_b32_e32 v31, 0
	v_mov_b32_e32 v47, 0
	v_mov_b32_e32 v63, 0
	v_add_f32_e32 v26, v26, v30
	v_add_f32_e32 v42, v42, v46
	v_add_f32_e32 v58, v58, v62
	v_mov_b32_e32 v32, 0
	v_mov_b32_e32 v48, 0
	v_mov_b32_e32 v64, 0
	v_add_f32_dpp v26, v26, v26 quad_perm:[1,0,3,2] row_mask:0xf bank_mask:0xf bound_ctrl:1
	v_add_f32_dpp v42, v42, v42 quad_perm:[1,0,3,2] row_mask:0xf bank_mask:0xf bound_ctrl:1
	v_add_f32_dpp v58, v58, v58 quad_perm:[1,0,3,2] row_mask:0xf bank_mask:0xf bound_ctrl:1
	v_add_f32_dpp v26, v26, v26 quad_perm:[2,3,0,1] row_mask:0xf bank_mask:0xf bound_ctrl:1
	v_add_f32_dpp v42, v42, v42 quad_perm:[2,3,0,1] row_mask:0xf bank_mask:0xf bound_ctrl:1
	v_add_f32_dpp v58, v58, v58 quad_perm:[2,3,0,1] row_mask:0xf bank_mask:0xf bound_ctrl:1
	v_add_f32_dpp v26, v26, v26 row_half_mirror row_mask:0xf bank_mask:0xf bound_ctrl:1
	v_add_f32_dpp v42, v42, v42 row_half_mirror row_mask:0xf bank_mask:0xf bound_ctrl:1
	v_add_f32_dpp v58, v58, v58 row_half_mirror row_mask:0xf bank_mask:0xf bound_ctrl:1
	v_add_f32_dpp v26, v26, v26 row_mirror row_mask:0xf bank_mask:0xf bound_ctrl:1
	v_add_f32_dpp v42, v42, v42 row_mirror row_mask:0xf bank_mask:0xf bound_ctrl:1
	v_add_f32_dpp v58, v58, v58 row_mirror row_mask:0xf bank_mask:0xf bound_ctrl:1
	v_mov_b32_dpp v31, v26 row_bcast:15 row_mask:0xa bank_mask:0xf
	v_mov_b32_dpp v47, v42 row_bcast:15 row_mask:0xa bank_mask:0xf
	v_mov_b32_dpp v63, v58 row_bcast:15 row_mask:0xa bank_mask:0xf
	v_add_f32_e32 v26, v26, v31
	v_add_f32_e32 v42, v42, v47
	v_add_f32_e32 v58, v58, v63
	v_mov_b32_dpp v32, v26 row_bcast:31 row_mask:0xc bank_mask:0xf
	v_mov_b32_dpp v48, v42 row_bcast:31 row_mask:0xc bank_mask:0xf
	v_mov_b32_dpp v64, v58 row_bcast:31 row_mask:0xc bank_mask:0xf
	v_add_f32_e32 v26, v26, v32
	v_add_f32_e32 v42, v42, v48
	v_add_f32_e32 v58, v58, v64
	s_nop 0
	v_readlane_b32 s16, v26, 63
	v_readlane_b32 s17, v42, 63
	v_readlane_b32 s18, v58, 63
	v_writelane_b32 v1, s16, 0
	v_writelane_b32 v1, s17, 1
	v_writelane_b32 v1, s18, 2
	ds_read_b128 v[26:29], v5 offset:12288
	ds_read_b128 v[30:33], v5 offset:13312
	ds_read_b128 v[34:37], v5 offset:14336
	ds_read_b128 v[38:41], v5 offset:15360
	ds_read_b128 v[42:45], v5 offset:16384
	ds_read_b128 v[46:49], v5 offset:17408
	ds_read_b128 v[50:53], v5 offset:18432
	ds_read_b128 v[54:57], v5 offset:19456
	ds_read_b128 v[58:61], v5 offset:20480
	ds_read_b128 v[62:65], v5 offset:21504
	ds_read_b128 v[66:69], v5 offset:22528
	ds_read_b128 v[70:73], v5 offset:23552
	s_waitcnt lgkmcnt(8)
	v_pk_fma_f32 v[28:29], v[8:9], v[28:29], 0 op_sel_hi:[1,1,0]
	v_pk_fma_f32 v[26:27], v[6:7], v[26:27], 0 op_sel_hi:[1,1,0]
	v_pk_fma_f32 v[28:29], v[12:13], v[32:33], v[28:29]
	v_pk_fma_f32 v[26:27], v[10:11], v[30:31], v[26:27]
	v_pk_fma_f32 v[28:29], v[16:17], v[36:37], v[28:29]
	v_pk_fma_f32 v[26:27], v[14:15], v[34:35], v[26:27]
	v_pk_fma_f32 v[28:29], v[20:21], v[40:41], v[28:29]
	v_pk_fma_f32 v[26:27], v[18:19], v[38:39], v[26:27]
	s_waitcnt lgkmcnt(4)
	v_pk_fma_f32 v[44:45], v[8:9], v[44:45], 0 op_sel_hi:[1,1,0]
	v_pk_fma_f32 v[42:43], v[6:7], v[42:43], 0 op_sel_hi:[1,1,0]
	v_pk_fma_f32 v[44:45], v[12:13], v[48:49], v[44:45]
	v_pk_fma_f32 v[42:43], v[10:11], v[46:47], v[42:43]
	v_pk_fma_f32 v[44:45], v[16:17], v[52:53], v[44:45]
	v_pk_fma_f32 v[42:43], v[14:15], v[50:51], v[42:43]
	v_pk_fma_f32 v[44:45], v[20:21], v[56:57], v[44:45]
	v_pk_fma_f32 v[42:43], v[18:19], v[54:55], v[42:43]
	s_waitcnt lgkmcnt(0)
	v_pk_fma_f32 v[60:61], v[8:9], v[60:61], 0 op_sel_hi:[1,1,0]
	v_pk_fma_f32 v[58:59], v[6:7], v[58:59], 0 op_sel_hi:[1,1,0]
	v_pk_fma_f32 v[60:61], v[12:13], v[64:65], v[60:61]
	v_pk_fma_f32 v[58:59], v[10:11], v[62:63], v[58:59]
	v_pk_fma_f32 v[60:61], v[16:17], v[68:69], v[60:61]
	v_pk_fma_f32 v[58:59], v[14:15], v[66:67], v[58:59]
	v_pk_fma_f32 v[60:61], v[20:21], v[72:73], v[60:61]
	v_pk_fma_f32 v[58:59], v[18:19], v[70:71], v[58:59]
	v_add_f32_e32 v30, v28, v29
	v_add_f32_e32 v46, v44, v45
	v_add_f32_e32 v62, v60, v61
	v_add_f32_e32 v26, v26, v27
	v_add_f32_e32 v42, v42, v43
	v_add_f32_e32 v58, v58, v59
	v_mov_b32_e32 v31, 0
	v_mov_b32_e32 v47, 0
	v_mov_b32_e32 v63, 0
	v_add_f32_e32 v26, v26, v30
	v_add_f32_e32 v42, v42, v46
	v_add_f32_e32 v58, v58, v62
	v_mov_b32_e32 v32, 0
	v_mov_b32_e32 v48, 0
	v_mov_b32_e32 v64, 0
	v_add_f32_dpp v26, v26, v26 quad_perm:[1,0,3,2] row_mask:0xf bank_mask:0xf bound_ctrl:1
	v_add_f32_dpp v42, v42, v42 quad_perm:[1,0,3,2] row_mask:0xf bank_mask:0xf bound_ctrl:1
	v_add_f32_dpp v58, v58, v58 quad_perm:[1,0,3,2] row_mask:0xf bank_mask:0xf bound_ctrl:1
	v_add_f32_dpp v26, v26, v26 quad_perm:[2,3,0,1] row_mask:0xf bank_mask:0xf bound_ctrl:1
	v_add_f32_dpp v42, v42, v42 quad_perm:[2,3,0,1] row_mask:0xf bank_mask:0xf bound_ctrl:1
	v_add_f32_dpp v58, v58, v58 quad_perm:[2,3,0,1] row_mask:0xf bank_mask:0xf bound_ctrl:1
	v_add_f32_dpp v26, v26, v26 row_half_mirror row_mask:0xf bank_mask:0xf bound_ctrl:1
	v_add_f32_dpp v42, v42, v42 row_half_mirror row_mask:0xf bank_mask:0xf bound_ctrl:1
	v_add_f32_dpp v58, v58, v58 row_half_mirror row_mask:0xf bank_mask:0xf bound_ctrl:1
	v_add_f32_dpp v26, v26, v26 row_mirror row_mask:0xf bank_mask:0xf bound_ctrl:1
	v_add_f32_dpp v42, v42, v42 row_mirror row_mask:0xf bank_mask:0xf bound_ctrl:1
	v_add_f32_dpp v58, v58, v58 row_mirror row_mask:0xf bank_mask:0xf bound_ctrl:1
	v_mov_b32_dpp v31, v26 row_bcast:15 row_mask:0xa bank_mask:0xf
	v_mov_b32_dpp v47, v42 row_bcast:15 row_mask:0xa bank_mask:0xf
	v_mov_b32_dpp v63, v58 row_bcast:15 row_mask:0xa bank_mask:0xf
	v_add_f32_e32 v26, v26, v31
	v_add_f32_e32 v42, v42, v47
	v_add_f32_e32 v58, v58, v63
	v_mov_b32_dpp v32, v26 row_bcast:31 row_mask:0xc bank_mask:0xf
	v_mov_b32_dpp v48, v42 row_bcast:31 row_mask:0xc bank_mask:0xf
	v_mov_b32_dpp v64, v58 row_bcast:31 row_mask:0xc bank_mask:0xf
	v_add_f32_e32 v26, v26, v32
	v_add_f32_e32 v42, v42, v48
	v_add_f32_e32 v58, v58, v64
	s_nop 0
	v_readlane_b32 s16, v26, 63
	v_readlane_b32 s17, v42, 63
	v_readlane_b32 s18, v58, 63
	v_writelane_b32 v1, s16, 3
	v_writelane_b32 v1, s17, 4
	v_writelane_b32 v1, s18, 5
	ds_read_b128 v[26:29], v5 offset:24576
	ds_read_b128 v[30:33], v5 offset:25600
	ds_read_b128 v[34:37], v5 offset:26624
	ds_read_b128 v[38:41], v5 offset:27648
	ds_read_b128 v[42:45], v5 offset:28672
	ds_read_b128 v[46:49], v5 offset:29696
	ds_read_b128 v[50:53], v5 offset:30720
	ds_read_b128 v[54:57], v5 offset:31744
	ds_read_b128 v[58:61], v5 offset:32768
	ds_read_b128 v[62:65], v5 offset:33792
	ds_read_b128 v[66:69], v5 offset:34816
	ds_read_b128 v[70:73], v5 offset:35840
	s_waitcnt lgkmcnt(8)
	v_pk_fma_f32 v[28:29], v[8:9], v[28:29], 0 op_sel_hi:[1,1,0]
	v_pk_fma_f32 v[26:27], v[6:7], v[26:27], 0 op_sel_hi:[1,1,0]
	v_pk_fma_f32 v[28:29], v[12:13], v[32:33], v[28:29]
	v_pk_fma_f32 v[26:27], v[10:11], v[30:31], v[26:27]
	v_pk_fma_f32 v[28:29], v[16:17], v[36:37], v[28:29]
	v_pk_fma_f32 v[26:27], v[14:15], v[34:35], v[26:27]
	v_pk_fma_f32 v[28:29], v[20:21], v[40:41], v[28:29]
	v_pk_fma_f32 v[26:27], v[18:19], v[38:39], v[26:27]
	s_waitcnt lgkmcnt(4)
	v_pk_fma_f32 v[44:45], v[8:9], v[44:45], 0 op_sel_hi:[1,1,0]
	v_pk_fma_f32 v[42:43], v[6:7], v[42:43], 0 op_sel_hi:[1,1,0]
	v_pk_fma_f32 v[44:45], v[12:13], v[48:49], v[44:45]
	v_pk_fma_f32 v[42:43], v[10:11], v[46:47], v[42:43]
	v_pk_fma_f32 v[44:45], v[16:17], v[52:53], v[44:45]
	v_pk_fma_f32 v[42:43], v[14:15], v[50:51], v[42:43]
	v_pk_fma_f32 v[44:45], v[20:21], v[56:57], v[44:45]
	v_pk_fma_f32 v[42:43], v[18:19], v[54:55], v[42:43]
	s_waitcnt lgkmcnt(0)
	v_pk_fma_f32 v[60:61], v[8:9], v[60:61], 0 op_sel_hi:[1,1,0]
	v_pk_fma_f32 v[58:59], v[6:7], v[58:59], 0 op_sel_hi:[1,1,0]
	v_pk_fma_f32 v[60:61], v[12:13], v[64:65], v[60:61]
	v_pk_fma_f32 v[58:59], v[10:11], v[62:63], v[58:59]
	v_pk_fma_f32 v[60:61], v[16:17], v[68:69], v[60:61]
	v_pk_fma_f32 v[58:59], v[14:15], v[66:67], v[58:59]
	v_pk_fma_f32 v[60:61], v[20:21], v[72:73], v[60:61]
	v_pk_fma_f32 v[58:59], v[18:19], v[70:71], v[58:59]
	v_add_f32_e32 v30, v28, v29
	v_add_f32_e32 v46, v44, v45
	v_add_f32_e32 v62, v60, v61
	v_add_f32_e32 v26, v26, v27
	v_add_f32_e32 v42, v42, v43
	v_add_f32_e32 v58, v58, v59
	v_mov_b32_e32 v31, 0
	v_mov_b32_e32 v47, 0
	v_mov_b32_e32 v63, 0
	v_add_f32_e32 v26, v26, v30
	v_add_f32_e32 v42, v42, v46
	v_add_f32_e32 v58, v58, v62
	v_mov_b32_e32 v32, 0
	v_mov_b32_e32 v48, 0
	v_mov_b32_e32 v64, 0
	v_add_f32_dpp v26, v26, v26 quad_perm:[1,0,3,2] row_mask:0xf bank_mask:0xf bound_ctrl:1
	v_add_f32_dpp v42, v42, v42 quad_perm:[1,0,3,2] row_mask:0xf bank_mask:0xf bound_ctrl:1
	v_add_f32_dpp v58, v58, v58 quad_perm:[1,0,3,2] row_mask:0xf bank_mask:0xf bound_ctrl:1
	v_add_f32_dpp v26, v26, v26 quad_perm:[2,3,0,1] row_mask:0xf bank_mask:0xf bound_ctrl:1
	v_add_f32_dpp v42, v42, v42 quad_perm:[2,3,0,1] row_mask:0xf bank_mask:0xf bound_ctrl:1
	v_add_f32_dpp v58, v58, v58 quad_perm:[2,3,0,1] row_mask:0xf bank_mask:0xf bound_ctrl:1
	v_add_f32_dpp v26, v26, v26 row_half_mirror row_mask:0xf bank_mask:0xf bound_ctrl:1
	v_add_f32_dpp v42, v42, v42 row_half_mirror row_mask:0xf bank_mask:0xf bound_ctrl:1
	v_add_f32_dpp v58, v58, v58 row_half_mirror row_mask:0xf bank_mask:0xf bound_ctrl:1
	v_add_f32_dpp v26, v26, v26 row_mirror row_mask:0xf bank_mask:0xf bound_ctrl:1
	v_add_f32_dpp v42, v42, v42 row_mirror row_mask:0xf bank_mask:0xf bound_ctrl:1
	v_add_f32_dpp v58, v58, v58 row_mirror row_mask:0xf bank_mask:0xf bound_ctrl:1
	v_mov_b32_dpp v31, v26 row_bcast:15 row_mask:0xa bank_mask:0xf
	v_mov_b32_dpp v47, v42 row_bcast:15 row_mask:0xa bank_mask:0xf
	v_mov_b32_dpp v63, v58 row_bcast:15 row_mask:0xa bank_mask:0xf
	v_add_f32_e32 v26, v26, v31
	v_add_f32_e32 v42, v42, v47
	v_add_f32_e32 v58, v58, v63
	v_mov_b32_dpp v32, v26 row_bcast:31 row_mask:0xc bank_mask:0xf
	v_mov_b32_dpp v48, v42 row_bcast:31 row_mask:0xc bank_mask:0xf
	v_mov_b32_dpp v64, v58 row_bcast:31 row_mask:0xc bank_mask:0xf
	v_add_f32_e32 v26, v26, v32
	v_add_f32_e32 v42, v42, v48
	v_add_f32_e32 v58, v58, v64
	s_nop 0
	v_readlane_b32 s16, v26, 63
	v_readlane_b32 s17, v42, 63
	v_readlane_b32 s18, v58, 63
	v_writelane_b32 v1, s16, 6
	v_writelane_b32 v1, s17, 7
	v_writelane_b32 v1, s18, 8
	ds_read_b128 v[26:29], v5 offset:36864
	ds_read_b128 v[30:33], v5 offset:37888
	ds_read_b128 v[34:37], v5 offset:38912
	ds_read_b128 v[38:41], v5 offset:39936
	ds_read_b128 v[42:45], v5 offset:40960
	ds_read_b128 v[46:49], v5 offset:41984
	ds_read_b128 v[50:53], v5 offset:43008
	ds_read_b128 v[54:57], v5 offset:44032
	ds_read_b128 v[58:61], v5 offset:45056
	ds_read_b128 v[62:65], v5 offset:46080
	ds_read_b128 v[66:69], v5 offset:47104
	ds_read_b128 v[70:73], v5 offset:48128
	s_waitcnt lgkmcnt(8)
	v_pk_fma_f32 v[28:29], v[8:9], v[28:29], 0 op_sel_hi:[1,1,0]
	v_pk_fma_f32 v[26:27], v[6:7], v[26:27], 0 op_sel_hi:[1,1,0]
	v_pk_fma_f32 v[28:29], v[12:13], v[32:33], v[28:29]
	v_pk_fma_f32 v[26:27], v[10:11], v[30:31], v[26:27]
	v_pk_fma_f32 v[28:29], v[16:17], v[36:37], v[28:29]
	v_pk_fma_f32 v[26:27], v[14:15], v[34:35], v[26:27]
	v_pk_fma_f32 v[28:29], v[20:21], v[40:41], v[28:29]
	v_pk_fma_f32 v[26:27], v[18:19], v[38:39], v[26:27]
	s_waitcnt lgkmcnt(4)
	v_pk_fma_f32 v[44:45], v[8:9], v[44:45], 0 op_sel_hi:[1,1,0]
	v_pk_fma_f32 v[42:43], v[6:7], v[42:43], 0 op_sel_hi:[1,1,0]
	v_pk_fma_f32 v[44:45], v[12:13], v[48:49], v[44:45]
	v_pk_fma_f32 v[42:43], v[10:11], v[46:47], v[42:43]
	v_pk_fma_f32 v[44:45], v[16:17], v[52:53], v[44:45]
	v_pk_fma_f32 v[42:43], v[14:15], v[50:51], v[42:43]
	v_pk_fma_f32 v[44:45], v[20:21], v[56:57], v[44:45]
	v_pk_fma_f32 v[42:43], v[18:19], v[54:55], v[42:43]
	s_waitcnt lgkmcnt(0)
	v_pk_fma_f32 v[60:61], v[8:9], v[60:61], 0 op_sel_hi:[1,1,0]
	v_pk_fma_f32 v[58:59], v[6:7], v[58:59], 0 op_sel_hi:[1,1,0]
	v_pk_fma_f32 v[60:61], v[12:13], v[64:65], v[60:61]
	v_pk_fma_f32 v[58:59], v[10:11], v[62:63], v[58:59]
	v_pk_fma_f32 v[60:61], v[16:17], v[68:69], v[60:61]
	v_pk_fma_f32 v[58:59], v[14:15], v[66:67], v[58:59]
	v_pk_fma_f32 v[60:61], v[20:21], v[72:73], v[60:61]
	v_pk_fma_f32 v[58:59], v[18:19], v[70:71], v[58:59]
	v_add_f32_e32 v30, v28, v29
	v_add_f32_e32 v46, v44, v45
	v_add_f32_e32 v62, v60, v61
	v_add_f32_e32 v26, v26, v27
	v_add_f32_e32 v42, v42, v43
	v_add_f32_e32 v58, v58, v59
	v_mov_b32_e32 v31, 0
	v_mov_b32_e32 v47, 0
	v_mov_b32_e32 v63, 0
	v_add_f32_e32 v26, v26, v30
	v_add_f32_e32 v42, v42, v46
	v_add_f32_e32 v58, v58, v62
	v_mov_b32_e32 v32, 0
	v_mov_b32_e32 v48, 0
	v_mov_b32_e32 v64, 0
	v_add_f32_dpp v26, v26, v26 quad_perm:[1,0,3,2] row_mask:0xf bank_mask:0xf bound_ctrl:1
	v_add_f32_dpp v42, v42, v42 quad_perm:[1,0,3,2] row_mask:0xf bank_mask:0xf bound_ctrl:1
	v_add_f32_dpp v58, v58, v58 quad_perm:[1,0,3,2] row_mask:0xf bank_mask:0xf bound_ctrl:1
	v_add_f32_dpp v26, v26, v26 quad_perm:[2,3,0,1] row_mask:0xf bank_mask:0xf bound_ctrl:1
	v_add_f32_dpp v42, v42, v42 quad_perm:[2,3,0,1] row_mask:0xf bank_mask:0xf bound_ctrl:1
	v_add_f32_dpp v58, v58, v58 quad_perm:[2,3,0,1] row_mask:0xf bank_mask:0xf bound_ctrl:1
	v_add_f32_dpp v26, v26, v26 row_half_mirror row_mask:0xf bank_mask:0xf bound_ctrl:1
	v_add_f32_dpp v42, v42, v42 row_half_mirror row_mask:0xf bank_mask:0xf bound_ctrl:1
	v_add_f32_dpp v58, v58, v58 row_half_mirror row_mask:0xf bank_mask:0xf bound_ctrl:1
	v_add_f32_dpp v26, v26, v26 row_mirror row_mask:0xf bank_mask:0xf bound_ctrl:1
	v_add_f32_dpp v42, v42, v42 row_mirror row_mask:0xf bank_mask:0xf bound_ctrl:1
	v_add_f32_dpp v58, v58, v58 row_mirror row_mask:0xf bank_mask:0xf bound_ctrl:1
	v_mov_b32_dpp v31, v26 row_bcast:15 row_mask:0xa bank_mask:0xf
	v_mov_b32_dpp v47, v42 row_bcast:15 row_mask:0xa bank_mask:0xf
	v_mov_b32_dpp v63, v58 row_bcast:15 row_mask:0xa bank_mask:0xf
	v_add_f32_e32 v26, v26, v31
	v_add_f32_e32 v42, v42, v47
	v_add_f32_e32 v58, v58, v63
	v_mov_b32_dpp v32, v26 row_bcast:31 row_mask:0xc bank_mask:0xf
	v_mov_b32_dpp v48, v42 row_bcast:31 row_mask:0xc bank_mask:0xf
	v_mov_b32_dpp v64, v58 row_bcast:31 row_mask:0xc bank_mask:0xf
	v_add_f32_e32 v26, v26, v32
	v_add_f32_e32 v42, v42, v48
	v_add_f32_e32 v58, v58, v64
	s_nop 0
	v_readlane_b32 s16, v26, 63
	v_readlane_b32 s17, v42, 63
	v_readlane_b32 s18, v58, 63
	v_writelane_b32 v1, s16, 9
	v_writelane_b32 v1, s17, 10
	v_writelane_b32 v1, s18, 11
	s_mov_b64 s[26:27], exec
	s_mov_b32 exec_lo, 0xfff
	s_mov_b32 exec_hi, 0
	global_store_dword v25, v1, s[42:43]
	s_mov_b64 exec, s[26:27]
	s_add_u32 s40, s40, 0x400000
	s_addc_u32 s41, s41, 0
	s_add_u32 s42, s42, 0x20000
	s_addc_u32 s43, s43, 0
	s_waitcnt vmcnt(34)
	v_pk_mul_f32 v[50:51], v[130:131], v[130:131]
	v_pk_mul_f32 v[52:53], v[128:129], v[128:129]
	v_pk_mul_f32 v[54:55], v[134:135], v[134:135]
	v_pk_mul_f32 v[56:57], v[132:133], v[132:133]
	v_mul_f32_e32 v58, v137, v137
	v_mul_f32_e32 v60, v139, v139
	v_pk_mul_f32 v[64:65], v[140:141], v[140:141]
	v_pk_mul_f32 v[66:67], v[142:143], v[142:143]
	v_add_f32_e32 v52, v53, v52
	v_add_f32_e32 v50, v50, v51
	v_add_f32_e32 v56, v57, v56
	v_add_f32_e32 v54, v54, v55
	v_fma_f32 v58, v136, v136, v58
	v_fma_f32 v60, v138, v138, v60
	v_add_f32_e32 v64, v64, v65
	v_add_f32_e32 v66, v66, v67
	v_add_f32_e32 v52, v52, v50
	v_add_f32_e32 v56, v56, v54
	v_add_f32_e32 v58, v58, v60
	v_add_f32_e32 v64, v64, v66
	v_add_f32_e32 v50, v52, v56
	v_mov_b32_e32 v61, 0
	v_mov_b32_e32 v62, 0
	v_add_f32_e32 v50, v50, v58
	s_nop 0
	v_add_f32_e32 v50, v50, v64
	s_nop 1
	v_add_f32_dpp v50, v50, v50 quad_perm:[1,0,3,2] row_mask:0xf bank_mask:0xf bound_ctrl:1
	s_nop 1
	v_add_f32_dpp v50, v50, v50 quad_perm:[2,3,0,1] row_mask:0xf bank_mask:0xf bound_ctrl:1
	s_nop 1
	v_add_f32_dpp v50, v50, v50 row_half_mirror row_mask:0xf bank_mask:0xf bound_ctrl:1
	s_nop 1
	v_add_f32_dpp v50, v50, v50 row_mirror row_mask:0xf bank_mask:0xf bound_ctrl:1
	s_nop 1
	v_mov_b32_dpp v61, v50 row_bcast:15 row_mask:0xa bank_mask:0xf
	s_nop 1
	v_add_f32_e32 v50, v50, v61
	s_nop 1
	v_mov_b32_dpp v62, v50 row_bcast:31 row_mask:0xc bank_mask:0xf
	s_nop 1
	v_add_f32_e32 v50, v50, v62
	s_nop 0
	v_readlane_b32 s15, v50, 63
	s_nop 1
	v_fma_f32 v50, s15, v24, v23
	v_mul_f32_e32 v51, 0x4b800000, v50
	v_cmp_gt_f32_e32 vcc, s5, v50
	s_nop 1
	v_cndmask_b32_e32 v50, v50, v51, vcc
	v_rsq_f32_e32 v52, v50
	s_nop 0
	v_mul_f32_e32 v53, 0x45800000, v52
	v_cndmask_b32_e32 v52, v52, v53, vcc
	v_pk_mul_f32 v[6:7], v[128:129], v[52:53] op_sel_hi:[1,0]
	v_pk_mul_f32 v[8:9], v[130:131], v[52:53] op_sel_hi:[1,0]
	v_pk_mul_f32 v[10:11], v[132:133], v[52:53] op_sel_hi:[1,0]
	v_pk_mul_f32 v[12:13], v[134:135], v[52:53] op_sel_hi:[1,0]
	v_pk_mul_f32 v[14:15], v[136:137], v[52:53] op_sel_hi:[1,0]
	v_pk_mul_f32 v[16:17], v[138:139], v[52:53] op_sel_hi:[1,0]
	v_pk_mul_f32 v[18:19], v[140:141], v[52:53] op_sel_hi:[1,0]
	v_pk_mul_f32 v[20:21], v[142:143], v[52:53] op_sel_hi:[1,0]
	v_pk_mul_f32 v[6:7], v[80:81], v[6:7]
	v_pk_mul_f32 v[8:9], v[82:83], v[8:9]
	v_pk_mul_f32 v[10:11], v[84:85], v[10:11]
	v_pk_mul_f32 v[12:13], v[86:87], v[12:13]
	v_pk_mul_f32 v[14:15], v[88:89], v[14:15]
	v_pk_mul_f32 v[16:17], v[90:91], v[16:17]
	v_pk_mul_f32 v[18:19], v[92:93], v[18:19]
	v_pk_mul_f32 v[20:21], v[94:95], v[20:21]
	v_cvt_pk_bf16_f32 v240, v6, v7
	v_cvt_pk_bf16_f32 v241, v8, v9
	v_cvt_pk_bf16_f32 v242, v10, v11
	v_cvt_pk_bf16_f32 v243, v12, v13
	v_cvt_pk_bf16_f32 v244, v14, v15
	v_cvt_pk_bf16_f32 v245, v16, v17
	v_cvt_pk_bf16_f32 v246, v18, v19
	v_cvt_pk_bf16_f32 v247, v20, v21
	global_store_dwordx2 v2, v[240:241], s[40:41] offset:0
	global_store_dwordx2 v2, v[242:243], s[40:41] offset:512
	global_store_dwordx2 v2, v[244:245], s[40:41] offset:1024
	global_store_dwordx2 v2, v[246:247], s[40:41] offset:1536
	ds_read_b128 v[26:29], v5 offset:0
	ds_read_b128 v[30:33], v5 offset:1024
	ds_read_b128 v[34:37], v5 offset:2048
	ds_read_b128 v[38:41], v5 offset:3072
	ds_read_b128 v[42:45], v5 offset:4096
	ds_read_b128 v[46:49], v5 offset:5120
	ds_read_b128 v[50:53], v5 offset:6144
	ds_read_b128 v[54:57], v5 offset:7168
	ds_read_b128 v[58:61], v5 offset:8192
	ds_read_b128 v[62:65], v5 offset:9216
	ds_read_b128 v[66:69], v5 offset:10240
	ds_read_b128 v[70:73], v5 offset:11264
	s_waitcnt lgkmcnt(8)
	v_pk_fma_f32 v[28:29], v[8:9], v[28:29], 0 op_sel_hi:[1,1,0]
	v_pk_fma_f32 v[26:27], v[6:7], v[26:27], 0 op_sel_hi:[1,1,0]
	v_pk_fma_f32 v[28:29], v[12:13], v[32:33], v[28:29]
	v_pk_fma_f32 v[26:27], v[10:11], v[30:31], v[26:27]
	v_pk_fma_f32 v[28:29], v[16:17], v[36:37], v[28:29]
	v_pk_fma_f32 v[26:27], v[14:15], v[34:35], v[26:27]
	v_pk_fma_f32 v[28:29], v[20:21], v[40:41], v[28:29]
	v_pk_fma_f32 v[26:27], v[18:19], v[38:39], v[26:27]
	s_waitcnt lgkmcnt(4)
	v_pk_fma_f32 v[44:45], v[8:9], v[44:45], 0 op_sel_hi:[1,1,0]
	v_pk_fma_f32 v[42:43], v[6:7], v[42:43], 0 op_sel_hi:[1,1,0]
	v_pk_fma_f32 v[44:45], v[12:13], v[48:49], v[44:45]
	v_pk_fma_f32 v[42:43], v[10:11], v[46:47], v[42:43]
	v_pk_fma_f32 v[44:45], v[16:17], v[52:53], v[44:45]
	v_pk_fma_f32 v[42:43], v[14:15], v[50:51], v[42:43]
	v_pk_fma_f32 v[44:45], v[20:21], v[56:57], v[44:45]
	v_pk_fma_f32 v[42:43], v[18:19], v[54:55], v[42:43]
	s_waitcnt lgkmcnt(0)
	v_pk_fma_f32 v[60:61], v[8:9], v[60:61], 0 op_sel_hi:[1,1,0]
	v_pk_fma_f32 v[58:59], v[6:7], v[58:59], 0 op_sel_hi:[1,1,0]
	v_pk_fma_f32 v[60:61], v[12:13], v[64:65], v[60:61]
	v_pk_fma_f32 v[58:59], v[10:11], v[62:63], v[58:59]
	v_pk_fma_f32 v[60:61], v[16:17], v[68:69], v[60:61]
	v_pk_fma_f32 v[58:59], v[14:15], v[66:67], v[58:59]
	v_pk_fma_f32 v[60:61], v[20:21], v[72:73], v[60:61]
	v_pk_fma_f32 v[58:59], v[18:19], v[70:71], v[58:59]
	v_add_f32_e32 v30, v28, v29
	v_add_f32_e32 v46, v44, v45
	v_add_f32_e32 v62, v60, v61
	v_add_f32_e32 v26, v26, v27
	v_add_f32_e32 v42, v42, v43
	v_add_f32_e32 v58, v58, v59
	v_mov_b32_e32 v31, 0
	v_mov_b32_e32 v47, 0
	v_mov_b32_e32 v63, 0
	v_add_f32_e32 v26, v26, v30
	v_add_f32_e32 v42, v42, v46
	v_add_f32_e32 v58, v58, v62
	v_mov_b32_e32 v32, 0
	v_mov_b32_e32 v48, 0
	v_mov_b32_e32 v64, 0
	v_add_f32_dpp v26, v26, v26 quad_perm:[1,0,3,2] row_mask:0xf bank_mask:0xf bound_ctrl:1
	v_add_f32_dpp v42, v42, v42 quad_perm:[1,0,3,2] row_mask:0xf bank_mask:0xf bound_ctrl:1
	v_add_f32_dpp v58, v58, v58 quad_perm:[1,0,3,2] row_mask:0xf bank_mask:0xf bound_ctrl:1
	v_add_f32_dpp v26, v26, v26 quad_perm:[2,3,0,1] row_mask:0xf bank_mask:0xf bound_ctrl:1
	v_add_f32_dpp v42, v42, v42 quad_perm:[2,3,0,1] row_mask:0xf bank_mask:0xf bound_ctrl:1
	v_add_f32_dpp v58, v58, v58 quad_perm:[2,3,0,1] row_mask:0xf bank_mask:0xf bound_ctrl:1
	v_add_f32_dpp v26, v26, v26 row_half_mirror row_mask:0xf bank_mask:0xf bound_ctrl:1
	v_add_f32_dpp v42, v42, v42 row_half_mirror row_mask:0xf bank_mask:0xf bound_ctrl:1
	v_add_f32_dpp v58, v58, v58 row_half_mirror row_mask:0xf bank_mask:0xf bound_ctrl:1
	v_add_f32_dpp v26, v26, v26 row_mirror row_mask:0xf bank_mask:0xf bound_ctrl:1
	v_add_f32_dpp v42, v42, v42 row_mirror row_mask:0xf bank_mask:0xf bound_ctrl:1
	v_add_f32_dpp v58, v58, v58 row_mirror row_mask:0xf bank_mask:0xf bound_ctrl:1
	v_mov_b32_dpp v31, v26 row_bcast:15 row_mask:0xa bank_mask:0xf
	v_mov_b32_dpp v47, v42 row_bcast:15 row_mask:0xa bank_mask:0xf
	v_mov_b32_dpp v63, v58 row_bcast:15 row_mask:0xa bank_mask:0xf
	v_add_f32_e32 v26, v26, v31
	v_add_f32_e32 v42, v42, v47
	v_add_f32_e32 v58, v58, v63
	v_mov_b32_dpp v32, v26 row_bcast:31 row_mask:0xc bank_mask:0xf
	v_mov_b32_dpp v48, v42 row_bcast:31 row_mask:0xc bank_mask:0xf
	v_mov_b32_dpp v64, v58 row_bcast:31 row_mask:0xc bank_mask:0xf
	v_add_f32_e32 v26, v26, v32
	v_add_f32_e32 v42, v42, v48
	v_add_f32_e32 v58, v58, v64
	s_nop 0
	v_readlane_b32 s16, v26, 63
	v_readlane_b32 s17, v42, 63
	v_readlane_b32 s18, v58, 63
	v_writelane_b32 v1, s16, 0
	v_writelane_b32 v1, s17, 1
	v_writelane_b32 v1, s18, 2
	ds_read_b128 v[26:29], v5 offset:12288
	ds_read_b128 v[30:33], v5 offset:13312
	ds_read_b128 v[34:37], v5 offset:14336
	ds_read_b128 v[38:41], v5 offset:15360
	ds_read_b128 v[42:45], v5 offset:16384
	ds_read_b128 v[46:49], v5 offset:17408
	ds_read_b128 v[50:53], v5 offset:18432
	ds_read_b128 v[54:57], v5 offset:19456
	ds_read_b128 v[58:61], v5 offset:20480
	ds_read_b128 v[62:65], v5 offset:21504
	ds_read_b128 v[66:69], v5 offset:22528
	ds_read_b128 v[70:73], v5 offset:23552
	s_waitcnt lgkmcnt(8)
	v_pk_fma_f32 v[28:29], v[8:9], v[28:29], 0 op_sel_hi:[1,1,0]
	v_pk_fma_f32 v[26:27], v[6:7], v[26:27], 0 op_sel_hi:[1,1,0]
	v_pk_fma_f32 v[28:29], v[12:13], v[32:33], v[28:29]
	v_pk_fma_f32 v[26:27], v[10:11], v[30:31], v[26:27]
	v_pk_fma_f32 v[28:29], v[16:17], v[36:37], v[28:29]
	v_pk_fma_f32 v[26:27], v[14:15], v[34:35], v[26:27]
	v_pk_fma_f32 v[28:29], v[20:21], v[40:41], v[28:29]
	v_pk_fma_f32 v[26:27], v[18:19], v[38:39], v[26:27]
	s_waitcnt lgkmcnt(4)
	v_pk_fma_f32 v[44:45], v[8:9], v[44:45], 0 op_sel_hi:[1,1,0]
	v_pk_fma_f32 v[42:43], v[6:7], v[42:43], 0 op_sel_hi:[1,1,0]
	v_pk_fma_f32 v[44:45], v[12:13], v[48:49], v[44:45]
	v_pk_fma_f32 v[42:43], v[10:11], v[46:47], v[42:43]
	v_pk_fma_f32 v[44:45], v[16:17], v[52:53], v[44:45]
	v_pk_fma_f32 v[42:43], v[14:15], v[50:51], v[42:43]
	v_pk_fma_f32 v[44:45], v[20:21], v[56:57], v[44:45]
	v_pk_fma_f32 v[42:43], v[18:19], v[54:55], v[42:43]
	s_waitcnt lgkmcnt(0)
	v_pk_fma_f32 v[60:61], v[8:9], v[60:61], 0 op_sel_hi:[1,1,0]
	v_pk_fma_f32 v[58:59], v[6:7], v[58:59], 0 op_sel_hi:[1,1,0]
	v_pk_fma_f32 v[60:61], v[12:13], v[64:65], v[60:61]
	v_pk_fma_f32 v[58:59], v[10:11], v[62:63], v[58:59]
	v_pk_fma_f32 v[60:61], v[16:17], v[68:69], v[60:61]
	v_pk_fma_f32 v[58:59], v[14:15], v[66:67], v[58:59]
	v_pk_fma_f32 v[60:61], v[20:21], v[72:73], v[60:61]
	v_pk_fma_f32 v[58:59], v[18:19], v[70:71], v[58:59]
	v_add_f32_e32 v30, v28, v29
	v_add_f32_e32 v46, v44, v45
	v_add_f32_e32 v62, v60, v61
	v_add_f32_e32 v26, v26, v27
	v_add_f32_e32 v42, v42, v43
	v_add_f32_e32 v58, v58, v59
	v_mov_b32_e32 v31, 0
	v_mov_b32_e32 v47, 0
	v_mov_b32_e32 v63, 0
	v_add_f32_e32 v26, v26, v30
	v_add_f32_e32 v42, v42, v46
	v_add_f32_e32 v58, v58, v62
	v_mov_b32_e32 v32, 0
	v_mov_b32_e32 v48, 0
	v_mov_b32_e32 v64, 0
	v_add_f32_dpp v26, v26, v26 quad_perm:[1,0,3,2] row_mask:0xf bank_mask:0xf bound_ctrl:1
	v_add_f32_dpp v42, v42, v42 quad_perm:[1,0,3,2] row_mask:0xf bank_mask:0xf bound_ctrl:1
	v_add_f32_dpp v58, v58, v58 quad_perm:[1,0,3,2] row_mask:0xf bank_mask:0xf bound_ctrl:1
	v_add_f32_dpp v26, v26, v26 quad_perm:[2,3,0,1] row_mask:0xf bank_mask:0xf bound_ctrl:1
	v_add_f32_dpp v42, v42, v42 quad_perm:[2,3,0,1] row_mask:0xf bank_mask:0xf bound_ctrl:1
	v_add_f32_dpp v58, v58, v58 quad_perm:[2,3,0,1] row_mask:0xf bank_mask:0xf bound_ctrl:1
	v_add_f32_dpp v26, v26, v26 row_half_mirror row_mask:0xf bank_mask:0xf bound_ctrl:1
	v_add_f32_dpp v42, v42, v42 row_half_mirror row_mask:0xf bank_mask:0xf bound_ctrl:1
	v_add_f32_dpp v58, v58, v58 row_half_mirror row_mask:0xf bank_mask:0xf bound_ctrl:1
	v_add_f32_dpp v26, v26, v26 row_mirror row_mask:0xf bank_mask:0xf bound_ctrl:1
	v_add_f32_dpp v42, v42, v42 row_mirror row_mask:0xf bank_mask:0xf bound_ctrl:1
	v_add_f32_dpp v58, v58, v58 row_mirror row_mask:0xf bank_mask:0xf bound_ctrl:1
	v_mov_b32_dpp v31, v26 row_bcast:15 row_mask:0xa bank_mask:0xf
	v_mov_b32_dpp v47, v42 row_bcast:15 row_mask:0xa bank_mask:0xf
	v_mov_b32_dpp v63, v58 row_bcast:15 row_mask:0xa bank_mask:0xf
	v_add_f32_e32 v26, v26, v31
	v_add_f32_e32 v42, v42, v47
	v_add_f32_e32 v58, v58, v63
	v_mov_b32_dpp v32, v26 row_bcast:31 row_mask:0xc bank_mask:0xf
	v_mov_b32_dpp v48, v42 row_bcast:31 row_mask:0xc bank_mask:0xf
	v_mov_b32_dpp v64, v58 row_bcast:31 row_mask:0xc bank_mask:0xf
	v_add_f32_e32 v26, v26, v32
	v_add_f32_e32 v42, v42, v48
	v_add_f32_e32 v58, v58, v64
	s_nop 0
	v_readlane_b32 s16, v26, 63
	v_readlane_b32 s17, v42, 63
	v_readlane_b32 s18, v58, 63
	v_writelane_b32 v1, s16, 3
	v_writelane_b32 v1, s17, 4
	v_writelane_b32 v1, s18, 5
	ds_read_b128 v[26:29], v5 offset:24576
	ds_read_b128 v[30:33], v5 offset:25600
	ds_read_b128 v[34:37], v5 offset:26624
	ds_read_b128 v[38:41], v5 offset:27648
	ds_read_b128 v[42:45], v5 offset:28672
	ds_read_b128 v[46:49], v5 offset:29696
	ds_read_b128 v[50:53], v5 offset:30720
	ds_read_b128 v[54:57], v5 offset:31744
	ds_read_b128 v[58:61], v5 offset:32768
	ds_read_b128 v[62:65], v5 offset:33792
	ds_read_b128 v[66:69], v5 offset:34816
	ds_read_b128 v[70:73], v5 offset:35840
	s_waitcnt lgkmcnt(8)
	v_pk_fma_f32 v[28:29], v[8:9], v[28:29], 0 op_sel_hi:[1,1,0]
	v_pk_fma_f32 v[26:27], v[6:7], v[26:27], 0 op_sel_hi:[1,1,0]
	v_pk_fma_f32 v[28:29], v[12:13], v[32:33], v[28:29]
	v_pk_fma_f32 v[26:27], v[10:11], v[30:31], v[26:27]
	v_pk_fma_f32 v[28:29], v[16:17], v[36:37], v[28:29]
	v_pk_fma_f32 v[26:27], v[14:15], v[34:35], v[26:27]
	v_pk_fma_f32 v[28:29], v[20:21], v[40:41], v[28:29]
	v_pk_fma_f32 v[26:27], v[18:19], v[38:39], v[26:27]
	s_waitcnt lgkmcnt(4)
	v_pk_fma_f32 v[44:45], v[8:9], v[44:45], 0 op_sel_hi:[1,1,0]
	v_pk_fma_f32 v[42:43], v[6:7], v[42:43], 0 op_sel_hi:[1,1,0]
	v_pk_fma_f32 v[44:45], v[12:13], v[48:49], v[44:45]
	v_pk_fma_f32 v[42:43], v[10:11], v[46:47], v[42:43]
	v_pk_fma_f32 v[44:45], v[16:17], v[52:53], v[44:45]
	v_pk_fma_f32 v[42:43], v[14:15], v[50:51], v[42:43]
	v_pk_fma_f32 v[44:45], v[20:21], v[56:57], v[44:45]
	v_pk_fma_f32 v[42:43], v[18:19], v[54:55], v[42:43]
	s_waitcnt lgkmcnt(0)
	v_pk_fma_f32 v[60:61], v[8:9], v[60:61], 0 op_sel_hi:[1,1,0]
	v_pk_fma_f32 v[58:59], v[6:7], v[58:59], 0 op_sel_hi:[1,1,0]
	v_pk_fma_f32 v[60:61], v[12:13], v[64:65], v[60:61]
	v_pk_fma_f32 v[58:59], v[10:11], v[62:63], v[58:59]
	v_pk_fma_f32 v[60:61], v[16:17], v[68:69], v[60:61]
	v_pk_fma_f32 v[58:59], v[14:15], v[66:67], v[58:59]
	v_pk_fma_f32 v[60:61], v[20:21], v[72:73], v[60:61]
	v_pk_fma_f32 v[58:59], v[18:19], v[70:71], v[58:59]
	v_add_f32_e32 v30, v28, v29
	v_add_f32_e32 v46, v44, v45
	v_add_f32_e32 v62, v60, v61
	v_add_f32_e32 v26, v26, v27
	v_add_f32_e32 v42, v42, v43
	v_add_f32_e32 v58, v58, v59
	v_mov_b32_e32 v31, 0
	v_mov_b32_e32 v47, 0
	v_mov_b32_e32 v63, 0
	v_add_f32_e32 v26, v26, v30
	v_add_f32_e32 v42, v42, v46
	v_add_f32_e32 v58, v58, v62
	v_mov_b32_e32 v32, 0
	v_mov_b32_e32 v48, 0
	v_mov_b32_e32 v64, 0
	v_add_f32_dpp v26, v26, v26 quad_perm:[1,0,3,2] row_mask:0xf bank_mask:0xf bound_ctrl:1
	v_add_f32_dpp v42, v42, v42 quad_perm:[1,0,3,2] row_mask:0xf bank_mask:0xf bound_ctrl:1
	v_add_f32_dpp v58, v58, v58 quad_perm:[1,0,3,2] row_mask:0xf bank_mask:0xf bound_ctrl:1
	v_add_f32_dpp v26, v26, v26 quad_perm:[2,3,0,1] row_mask:0xf bank_mask:0xf bound_ctrl:1
	v_add_f32_dpp v42, v42, v42 quad_perm:[2,3,0,1] row_mask:0xf bank_mask:0xf bound_ctrl:1
	v_add_f32_dpp v58, v58, v58 quad_perm:[2,3,0,1] row_mask:0xf bank_mask:0xf bound_ctrl:1
	v_add_f32_dpp v26, v26, v26 row_half_mirror row_mask:0xf bank_mask:0xf bound_ctrl:1
	v_add_f32_dpp v42, v42, v42 row_half_mirror row_mask:0xf bank_mask:0xf bound_ctrl:1
	v_add_f32_dpp v58, v58, v58 row_half_mirror row_mask:0xf bank_mask:0xf bound_ctrl:1
	v_add_f32_dpp v26, v26, v26 row_mirror row_mask:0xf bank_mask:0xf bound_ctrl:1
	v_add_f32_dpp v42, v42, v42 row_mirror row_mask:0xf bank_mask:0xf bound_ctrl:1
	v_add_f32_dpp v58, v58, v58 row_mirror row_mask:0xf bank_mask:0xf bound_ctrl:1
	v_mov_b32_dpp v31, v26 row_bcast:15 row_mask:0xa bank_mask:0xf
	v_mov_b32_dpp v47, v42 row_bcast:15 row_mask:0xa bank_mask:0xf
	v_mov_b32_dpp v63, v58 row_bcast:15 row_mask:0xa bank_mask:0xf
	v_add_f32_e32 v26, v26, v31
	v_add_f32_e32 v42, v42, v47
	v_add_f32_e32 v58, v58, v63
	v_mov_b32_dpp v32, v26 row_bcast:31 row_mask:0xc bank_mask:0xf
	v_mov_b32_dpp v48, v42 row_bcast:31 row_mask:0xc bank_mask:0xf
	v_mov_b32_dpp v64, v58 row_bcast:31 row_mask:0xc bank_mask:0xf
	v_add_f32_e32 v26, v26, v32
	v_add_f32_e32 v42, v42, v48
	v_add_f32_e32 v58, v58, v64
	s_nop 0
	v_readlane_b32 s16, v26, 63
	v_readlane_b32 s17, v42, 63
	v_readlane_b32 s18, v58, 63
	v_writelane_b32 v1, s16, 6
	v_writelane_b32 v1, s17, 7
	v_writelane_b32 v1, s18, 8
	ds_read_b128 v[26:29], v5 offset:36864
	ds_read_b128 v[30:33], v5 offset:37888
	ds_read_b128 v[34:37], v5 offset:38912
	ds_read_b128 v[38:41], v5 offset:39936
	ds_read_b128 v[42:45], v5 offset:40960
	ds_read_b128 v[46:49], v5 offset:41984
	ds_read_b128 v[50:53], v5 offset:43008
	ds_read_b128 v[54:57], v5 offset:44032
	ds_read_b128 v[58:61], v5 offset:45056
	ds_read_b128 v[62:65], v5 offset:46080
	ds_read_b128 v[66:69], v5 offset:47104
	ds_read_b128 v[70:73], v5 offset:48128
	s_waitcnt lgkmcnt(8)
	v_pk_fma_f32 v[28:29], v[8:9], v[28:29], 0 op_sel_hi:[1,1,0]
	v_pk_fma_f32 v[26:27], v[6:7], v[26:27], 0 op_sel_hi:[1,1,0]
	v_pk_fma_f32 v[28:29], v[12:13], v[32:33], v[28:29]
	v_pk_fma_f32 v[26:27], v[10:11], v[30:31], v[26:27]
	v_pk_fma_f32 v[28:29], v[16:17], v[36:37], v[28:29]
	v_pk_fma_f32 v[26:27], v[14:15], v[34:35], v[26:27]
	v_pk_fma_f32 v[28:29], v[20:21], v[40:41], v[28:29]
	v_pk_fma_f32 v[26:27], v[18:19], v[38:39], v[26:27]
	s_waitcnt lgkmcnt(4)
	v_pk_fma_f32 v[44:45], v[8:9], v[44:45], 0 op_sel_hi:[1,1,0]
	v_pk_fma_f32 v[42:43], v[6:7], v[42:43], 0 op_sel_hi:[1,1,0]
	v_pk_fma_f32 v[44:45], v[12:13], v[48:49], v[44:45]
	v_pk_fma_f32 v[42:43], v[10:11], v[46:47], v[42:43]
	v_pk_fma_f32 v[44:45], v[16:17], v[52:53], v[44:45]
	v_pk_fma_f32 v[42:43], v[14:15], v[50:51], v[42:43]
	v_pk_fma_f32 v[44:45], v[20:21], v[56:57], v[44:45]
	v_pk_fma_f32 v[42:43], v[18:19], v[54:55], v[42:43]
	s_waitcnt lgkmcnt(0)
	v_pk_fma_f32 v[60:61], v[8:9], v[60:61], 0 op_sel_hi:[1,1,0]
	v_pk_fma_f32 v[58:59], v[6:7], v[58:59], 0 op_sel_hi:[1,1,0]
	v_pk_fma_f32 v[60:61], v[12:13], v[64:65], v[60:61]
	v_pk_fma_f32 v[58:59], v[10:11], v[62:63], v[58:59]
	v_pk_fma_f32 v[60:61], v[16:17], v[68:69], v[60:61]
	v_pk_fma_f32 v[58:59], v[14:15], v[66:67], v[58:59]
	v_pk_fma_f32 v[60:61], v[20:21], v[72:73], v[60:61]
	v_pk_fma_f32 v[58:59], v[18:19], v[70:71], v[58:59]
	v_add_f32_e32 v30, v28, v29
	v_add_f32_e32 v46, v44, v45
	v_add_f32_e32 v62, v60, v61
	v_add_f32_e32 v26, v26, v27
	v_add_f32_e32 v42, v42, v43
	v_add_f32_e32 v58, v58, v59
	v_mov_b32_e32 v31, 0
	v_mov_b32_e32 v47, 0
	v_mov_b32_e32 v63, 0
	v_add_f32_e32 v26, v26, v30
	v_add_f32_e32 v42, v42, v46
	v_add_f32_e32 v58, v58, v62
	v_mov_b32_e32 v32, 0
	v_mov_b32_e32 v48, 0
	v_mov_b32_e32 v64, 0
	v_add_f32_dpp v26, v26, v26 quad_perm:[1,0,3,2] row_mask:0xf bank_mask:0xf bound_ctrl:1
	v_add_f32_dpp v42, v42, v42 quad_perm:[1,0,3,2] row_mask:0xf bank_mask:0xf bound_ctrl:1
	v_add_f32_dpp v58, v58, v58 quad_perm:[1,0,3,2] row_mask:0xf bank_mask:0xf bound_ctrl:1
	v_add_f32_dpp v26, v26, v26 quad_perm:[2,3,0,1] row_mask:0xf bank_mask:0xf bound_ctrl:1
	v_add_f32_dpp v42, v42, v42 quad_perm:[2,3,0,1] row_mask:0xf bank_mask:0xf bound_ctrl:1
	v_add_f32_dpp v58, v58, v58 quad_perm:[2,3,0,1] row_mask:0xf bank_mask:0xf bound_ctrl:1
	v_add_f32_dpp v26, v26, v26 row_half_mirror row_mask:0xf bank_mask:0xf bound_ctrl:1
	v_add_f32_dpp v42, v42, v42 row_half_mirror row_mask:0xf bank_mask:0xf bound_ctrl:1
	v_add_f32_dpp v58, v58, v58 row_half_mirror row_mask:0xf bank_mask:0xf bound_ctrl:1
	v_add_f32_dpp v26, v26, v26 row_mirror row_mask:0xf bank_mask:0xf bound_ctrl:1
	v_add_f32_dpp v42, v42, v42 row_mirror row_mask:0xf bank_mask:0xf bound_ctrl:1
	v_add_f32_dpp v58, v58, v58 row_mirror row_mask:0xf bank_mask:0xf bound_ctrl:1
	v_mov_b32_dpp v31, v26 row_bcast:15 row_mask:0xa bank_mask:0xf
	v_mov_b32_dpp v47, v42 row_bcast:15 row_mask:0xa bank_mask:0xf
	v_mov_b32_dpp v63, v58 row_bcast:15 row_mask:0xa bank_mask:0xf
	v_add_f32_e32 v26, v26, v31
	v_add_f32_e32 v42, v42, v47
	v_add_f32_e32 v58, v58, v63
	v_mov_b32_dpp v32, v26 row_bcast:31 row_mask:0xc bank_mask:0xf
	v_mov_b32_dpp v48, v42 row_bcast:31 row_mask:0xc bank_mask:0xf
	v_mov_b32_dpp v64, v58 row_bcast:31 row_mask:0xc bank_mask:0xf
	v_add_f32_e32 v26, v26, v32
	v_add_f32_e32 v42, v42, v48
	v_add_f32_e32 v58, v58, v64
	s_nop 0
	v_readlane_b32 s16, v26, 63
	v_readlane_b32 s17, v42, 63
	v_readlane_b32 s18, v58, 63
	v_writelane_b32 v1, s16, 9
	v_writelane_b32 v1, s17, 10
	v_writelane_b32 v1, s18, 11
	s_mov_b64 s[26:27], exec
	s_mov_b32 exec_lo, 0xfff
	s_mov_b32 exec_hi, 0
	global_store_dword v25, v1, s[42:43]
	s_mov_b64 exec, s[26:27]
	s_add_u32 s40, s40, 0x400000
	s_addc_u32 s41, s41, 0
	s_add_u32 s42, s42, 0x20000
	s_addc_u32 s43, s43, 0
	s_waitcnt vmcnt(35)
	v_pk_mul_f32 v[50:51], v[146:147], v[146:147]
	v_pk_mul_f32 v[52:53], v[144:145], v[144:145]
	v_pk_mul_f32 v[54:55], v[150:151], v[150:151]
	v_pk_mul_f32 v[56:57], v[148:149], v[148:149]
	v_mul_f32_e32 v58, v153, v153
	v_mul_f32_e32 v60, v155, v155
	v_pk_mul_f32 v[64:65], v[156:157], v[156:157]
	v_pk_mul_f32 v[66:67], v[158:159], v[158:159]
	v_add_f32_e32 v52, v53, v52
	v_add_f32_e32 v50, v50, v51
	v_add_f32_e32 v56, v57, v56
	v_add_f32_e32 v54, v54, v55
	v_fma_f32 v58, v152, v152, v58
	v_fma_f32 v60, v154, v154, v60
	v_add_f32_e32 v64, v64, v65
	v_add_f32_e32 v66, v66, v67
	v_add_f32_e32 v52, v52, v50
	v_add_f32_e32 v56, v56, v54
	v_add_f32_e32 v58, v58, v60
	v_add_f32_e32 v64, v64, v66
	v_add_f32_e32 v50, v52, v56
	v_mov_b32_e32 v61, 0
	v_mov_b32_e32 v62, 0
	v_add_f32_e32 v50, v50, v58
	s_nop 0
	v_add_f32_e32 v50, v50, v64
	s_nop 1
	v_add_f32_dpp v50, v50, v50 quad_perm:[1,0,3,2] row_mask:0xf bank_mask:0xf bound_ctrl:1
	s_nop 1
	v_add_f32_dpp v50, v50, v50 quad_perm:[2,3,0,1] row_mask:0xf bank_mask:0xf bound_ctrl:1
	s_nop 1
	v_add_f32_dpp v50, v50, v50 row_half_mirror row_mask:0xf bank_mask:0xf bound_ctrl:1
	s_nop 1
	v_add_f32_dpp v50, v50, v50 row_mirror row_mask:0xf bank_mask:0xf bound_ctrl:1
	s_nop 1
	v_mov_b32_dpp v61, v50 row_bcast:15 row_mask:0xa bank_mask:0xf
	s_nop 1
	v_add_f32_e32 v50, v50, v61
	s_nop 1
	v_mov_b32_dpp v62, v50 row_bcast:31 row_mask:0xc bank_mask:0xf
	s_nop 1
	v_add_f32_e32 v50, v50, v62
	s_nop 0
	v_readlane_b32 s15, v50, 63
	s_nop 1
	v_fma_f32 v50, s15, v24, v23
	v_mul_f32_e32 v51, 0x4b800000, v50
	v_cmp_gt_f32_e32 vcc, s5, v50
	s_nop 1
	v_cndmask_b32_e32 v50, v50, v51, vcc
	v_rsq_f32_e32 v52, v50
	s_nop 0
	v_mul_f32_e32 v53, 0x45800000, v52
	v_cndmask_b32_e32 v52, v52, v53, vcc
	v_pk_mul_f32 v[6:7], v[144:145], v[52:53] op_sel_hi:[1,0]
	v_pk_mul_f32 v[8:9], v[146:147], v[52:53] op_sel_hi:[1,0]
	v_pk_mul_f32 v[10:11], v[148:149], v[52:53] op_sel_hi:[1,0]
	v_pk_mul_f32 v[12:13], v[150:151], v[52:53] op_sel_hi:[1,0]
	v_pk_mul_f32 v[14:15], v[152:153], v[52:53] op_sel_hi:[1,0]
	v_pk_mul_f32 v[16:17], v[154:155], v[52:53] op_sel_hi:[1,0]
	v_pk_mul_f32 v[18:19], v[156:157], v[52:53] op_sel_hi:[1,0]
	v_pk_mul_f32 v[20:21], v[158:159], v[52:53] op_sel_hi:[1,0]
	v_pk_mul_f32 v[6:7], v[80:81], v[6:7]
	v_pk_mul_f32 v[8:9], v[82:83], v[8:9]
	v_pk_mul_f32 v[10:11], v[84:85], v[10:11]
	v_pk_mul_f32 v[12:13], v[86:87], v[12:13]
	v_pk_mul_f32 v[14:15], v[88:89], v[14:15]
	v_pk_mul_f32 v[16:17], v[90:91], v[16:17]
	v_pk_mul_f32 v[18:19], v[92:93], v[18:19]
	v_pk_mul_f32 v[20:21], v[94:95], v[20:21]
	v_cvt_pk_bf16_f32 v240, v6, v7
	v_cvt_pk_bf16_f32 v241, v8, v9
	v_cvt_pk_bf16_f32 v242, v10, v11
	v_cvt_pk_bf16_f32 v243, v12, v13
	v_cvt_pk_bf16_f32 v244, v14, v15
	v_cvt_pk_bf16_f32 v245, v16, v17
	v_cvt_pk_bf16_f32 v246, v18, v19
	v_cvt_pk_bf16_f32 v247, v20, v21
	global_store_dwordx2 v2, v[240:241], s[40:41] offset:0
	global_store_dwordx2 v2, v[242:243], s[40:41] offset:512
	global_store_dwordx2 v2, v[244:245], s[40:41] offset:1024
	global_store_dwordx2 v2, v[246:247], s[40:41] offset:1536
	ds_read_b128 v[26:29], v5 offset:0
	ds_read_b128 v[30:33], v5 offset:1024
	ds_read_b128 v[34:37], v5 offset:2048
	ds_read_b128 v[38:41], v5 offset:3072
	ds_read_b128 v[42:45], v5 offset:4096
	ds_read_b128 v[46:49], v5 offset:5120
	ds_read_b128 v[50:53], v5 offset:6144
	ds_read_b128 v[54:57], v5 offset:7168
	ds_read_b128 v[58:61], v5 offset:8192
	ds_read_b128 v[62:65], v5 offset:9216
	ds_read_b128 v[66:69], v5 offset:10240
	ds_read_b128 v[70:73], v5 offset:11264
	s_waitcnt lgkmcnt(8)
	v_pk_fma_f32 v[28:29], v[8:9], v[28:29], 0 op_sel_hi:[1,1,0]
	v_pk_fma_f32 v[26:27], v[6:7], v[26:27], 0 op_sel_hi:[1,1,0]
	v_pk_fma_f32 v[28:29], v[12:13], v[32:33], v[28:29]
	v_pk_fma_f32 v[26:27], v[10:11], v[30:31], v[26:27]
	v_pk_fma_f32 v[28:29], v[16:17], v[36:37], v[28:29]
	v_pk_fma_f32 v[26:27], v[14:15], v[34:35], v[26:27]
	v_pk_fma_f32 v[28:29], v[20:21], v[40:41], v[28:29]
	v_pk_fma_f32 v[26:27], v[18:19], v[38:39], v[26:27]
	s_waitcnt lgkmcnt(4)
	v_pk_fma_f32 v[44:45], v[8:9], v[44:45], 0 op_sel_hi:[1,1,0]
	v_pk_fma_f32 v[42:43], v[6:7], v[42:43], 0 op_sel_hi:[1,1,0]
	v_pk_fma_f32 v[44:45], v[12:13], v[48:49], v[44:45]
	v_pk_fma_f32 v[42:43], v[10:11], v[46:47], v[42:43]
	v_pk_fma_f32 v[44:45], v[16:17], v[52:53], v[44:45]
	v_pk_fma_f32 v[42:43], v[14:15], v[50:51], v[42:43]
	v_pk_fma_f32 v[44:45], v[20:21], v[56:57], v[44:45]
	v_pk_fma_f32 v[42:43], v[18:19], v[54:55], v[42:43]
	s_waitcnt lgkmcnt(0)
	v_pk_fma_f32 v[60:61], v[8:9], v[60:61], 0 op_sel_hi:[1,1,0]
	v_pk_fma_f32 v[58:59], v[6:7], v[58:59], 0 op_sel_hi:[1,1,0]
	v_pk_fma_f32 v[60:61], v[12:13], v[64:65], v[60:61]
	v_pk_fma_f32 v[58:59], v[10:11], v[62:63], v[58:59]
	v_pk_fma_f32 v[60:61], v[16:17], v[68:69], v[60:61]
	v_pk_fma_f32 v[58:59], v[14:15], v[66:67], v[58:59]
	v_pk_fma_f32 v[60:61], v[20:21], v[72:73], v[60:61]
	v_pk_fma_f32 v[58:59], v[18:19], v[70:71], v[58:59]
	v_add_f32_e32 v30, v28, v29
	v_add_f32_e32 v46, v44, v45
	v_add_f32_e32 v62, v60, v61
	v_add_f32_e32 v26, v26, v27
	v_add_f32_e32 v42, v42, v43
	v_add_f32_e32 v58, v58, v59
	v_mov_b32_e32 v31, 0
	v_mov_b32_e32 v47, 0
	v_mov_b32_e32 v63, 0
	v_add_f32_e32 v26, v26, v30
	v_add_f32_e32 v42, v42, v46
	v_add_f32_e32 v58, v58, v62
	v_mov_b32_e32 v32, 0
	v_mov_b32_e32 v48, 0
	v_mov_b32_e32 v64, 0
	v_add_f32_dpp v26, v26, v26 quad_perm:[1,0,3,2] row_mask:0xf bank_mask:0xf bound_ctrl:1
	v_add_f32_dpp v42, v42, v42 quad_perm:[1,0,3,2] row_mask:0xf bank_mask:0xf bound_ctrl:1
	v_add_f32_dpp v58, v58, v58 quad_perm:[1,0,3,2] row_mask:0xf bank_mask:0xf bound_ctrl:1
	v_add_f32_dpp v26, v26, v26 quad_perm:[2,3,0,1] row_mask:0xf bank_mask:0xf bound_ctrl:1
	v_add_f32_dpp v42, v42, v42 quad_perm:[2,3,0,1] row_mask:0xf bank_mask:0xf bound_ctrl:1
	v_add_f32_dpp v58, v58, v58 quad_perm:[2,3,0,1] row_mask:0xf bank_mask:0xf bound_ctrl:1
	v_add_f32_dpp v26, v26, v26 row_half_mirror row_mask:0xf bank_mask:0xf bound_ctrl:1
	v_add_f32_dpp v42, v42, v42 row_half_mirror row_mask:0xf bank_mask:0xf bound_ctrl:1
	v_add_f32_dpp v58, v58, v58 row_half_mirror row_mask:0xf bank_mask:0xf bound_ctrl:1
	v_add_f32_dpp v26, v26, v26 row_mirror row_mask:0xf bank_mask:0xf bound_ctrl:1
	v_add_f32_dpp v42, v42, v42 row_mirror row_mask:0xf bank_mask:0xf bound_ctrl:1
	v_add_f32_dpp v58, v58, v58 row_mirror row_mask:0xf bank_mask:0xf bound_ctrl:1
	v_mov_b32_dpp v31, v26 row_bcast:15 row_mask:0xa bank_mask:0xf
	v_mov_b32_dpp v47, v42 row_bcast:15 row_mask:0xa bank_mask:0xf
	v_mov_b32_dpp v63, v58 row_bcast:15 row_mask:0xa bank_mask:0xf
	v_add_f32_e32 v26, v26, v31
	v_add_f32_e32 v42, v42, v47
	v_add_f32_e32 v58, v58, v63
	v_mov_b32_dpp v32, v26 row_bcast:31 row_mask:0xc bank_mask:0xf
	v_mov_b32_dpp v48, v42 row_bcast:31 row_mask:0xc bank_mask:0xf
	v_mov_b32_dpp v64, v58 row_bcast:31 row_mask:0xc bank_mask:0xf
	v_add_f32_e32 v26, v26, v32
	v_add_f32_e32 v42, v42, v48
	v_add_f32_e32 v58, v58, v64
	s_nop 0
	v_readlane_b32 s16, v26, 63
	v_readlane_b32 s17, v42, 63
	v_readlane_b32 s18, v58, 63
	v_writelane_b32 v1, s16, 0
	v_writelane_b32 v1, s17, 1
	v_writelane_b32 v1, s18, 2
	ds_read_b128 v[26:29], v5 offset:12288
	ds_read_b128 v[30:33], v5 offset:13312
	ds_read_b128 v[34:37], v5 offset:14336
	ds_read_b128 v[38:41], v5 offset:15360
	ds_read_b128 v[42:45], v5 offset:16384
	ds_read_b128 v[46:49], v5 offset:17408
	ds_read_b128 v[50:53], v5 offset:18432
	ds_read_b128 v[54:57], v5 offset:19456
	ds_read_b128 v[58:61], v5 offset:20480
	ds_read_b128 v[62:65], v5 offset:21504
	ds_read_b128 v[66:69], v5 offset:22528
	ds_read_b128 v[70:73], v5 offset:23552
	s_waitcnt lgkmcnt(8)
	v_pk_fma_f32 v[28:29], v[8:9], v[28:29], 0 op_sel_hi:[1,1,0]
	v_pk_fma_f32 v[26:27], v[6:7], v[26:27], 0 op_sel_hi:[1,1,0]
	v_pk_fma_f32 v[28:29], v[12:13], v[32:33], v[28:29]
	v_pk_fma_f32 v[26:27], v[10:11], v[30:31], v[26:27]
	v_pk_fma_f32 v[28:29], v[16:17], v[36:37], v[28:29]
	v_pk_fma_f32 v[26:27], v[14:15], v[34:35], v[26:27]
	v_pk_fma_f32 v[28:29], v[20:21], v[40:41], v[28:29]
	v_pk_fma_f32 v[26:27], v[18:19], v[38:39], v[26:27]
	s_waitcnt lgkmcnt(4)
	v_pk_fma_f32 v[44:45], v[8:9], v[44:45], 0 op_sel_hi:[1,1,0]
	v_pk_fma_f32 v[42:43], v[6:7], v[42:43], 0 op_sel_hi:[1,1,0]
	v_pk_fma_f32 v[44:45], v[12:13], v[48:49], v[44:45]
	v_pk_fma_f32 v[42:43], v[10:11], v[46:47], v[42:43]
	v_pk_fma_f32 v[44:45], v[16:17], v[52:53], v[44:45]
	v_pk_fma_f32 v[42:43], v[14:15], v[50:51], v[42:43]
	v_pk_fma_f32 v[44:45], v[20:21], v[56:57], v[44:45]
	v_pk_fma_f32 v[42:43], v[18:19], v[54:55], v[42:43]
	s_waitcnt lgkmcnt(0)
	v_pk_fma_f32 v[60:61], v[8:9], v[60:61], 0 op_sel_hi:[1,1,0]
	v_pk_fma_f32 v[58:59], v[6:7], v[58:59], 0 op_sel_hi:[1,1,0]
	v_pk_fma_f32 v[60:61], v[12:13], v[64:65], v[60:61]
	v_pk_fma_f32 v[58:59], v[10:11], v[62:63], v[58:59]
	v_pk_fma_f32 v[60:61], v[16:17], v[68:69], v[60:61]
	v_pk_fma_f32 v[58:59], v[14:15], v[66:67], v[58:59]
	v_pk_fma_f32 v[60:61], v[20:21], v[72:73], v[60:61]
	v_pk_fma_f32 v[58:59], v[18:19], v[70:71], v[58:59]
	v_add_f32_e32 v30, v28, v29
	v_add_f32_e32 v46, v44, v45
	v_add_f32_e32 v62, v60, v61
	v_add_f32_e32 v26, v26, v27
	v_add_f32_e32 v42, v42, v43
	v_add_f32_e32 v58, v58, v59
	v_mov_b32_e32 v31, 0
	v_mov_b32_e32 v47, 0
	v_mov_b32_e32 v63, 0
	v_add_f32_e32 v26, v26, v30
	v_add_f32_e32 v42, v42, v46
	v_add_f32_e32 v58, v58, v62
	v_mov_b32_e32 v32, 0
	v_mov_b32_e32 v48, 0
	v_mov_b32_e32 v64, 0
	v_add_f32_dpp v26, v26, v26 quad_perm:[1,0,3,2] row_mask:0xf bank_mask:0xf bound_ctrl:1
	v_add_f32_dpp v42, v42, v42 quad_perm:[1,0,3,2] row_mask:0xf bank_mask:0xf bound_ctrl:1
	v_add_f32_dpp v58, v58, v58 quad_perm:[1,0,3,2] row_mask:0xf bank_mask:0xf bound_ctrl:1
	v_add_f32_dpp v26, v26, v26 quad_perm:[2,3,0,1] row_mask:0xf bank_mask:0xf bound_ctrl:1
	v_add_f32_dpp v42, v42, v42 quad_perm:[2,3,0,1] row_mask:0xf bank_mask:0xf bound_ctrl:1
	v_add_f32_dpp v58, v58, v58 quad_perm:[2,3,0,1] row_mask:0xf bank_mask:0xf bound_ctrl:1
	v_add_f32_dpp v26, v26, v26 row_half_mirror row_mask:0xf bank_mask:0xf bound_ctrl:1
	v_add_f32_dpp v42, v42, v42 row_half_mirror row_mask:0xf bank_mask:0xf bound_ctrl:1
	v_add_f32_dpp v58, v58, v58 row_half_mirror row_mask:0xf bank_mask:0xf bound_ctrl:1
	v_add_f32_dpp v26, v26, v26 row_mirror row_mask:0xf bank_mask:0xf bound_ctrl:1
	v_add_f32_dpp v42, v42, v42 row_mirror row_mask:0xf bank_mask:0xf bound_ctrl:1
	v_add_f32_dpp v58, v58, v58 row_mirror row_mask:0xf bank_mask:0xf bound_ctrl:1
	v_mov_b32_dpp v31, v26 row_bcast:15 row_mask:0xa bank_mask:0xf
	v_mov_b32_dpp v47, v42 row_bcast:15 row_mask:0xa bank_mask:0xf
	v_mov_b32_dpp v63, v58 row_bcast:15 row_mask:0xa bank_mask:0xf
	v_add_f32_e32 v26, v26, v31
	v_add_f32_e32 v42, v42, v47
	v_add_f32_e32 v58, v58, v63
	v_mov_b32_dpp v32, v26 row_bcast:31 row_mask:0xc bank_mask:0xf
	v_mov_b32_dpp v48, v42 row_bcast:31 row_mask:0xc bank_mask:0xf
	v_mov_b32_dpp v64, v58 row_bcast:31 row_mask:0xc bank_mask:0xf
	v_add_f32_e32 v26, v26, v32
	v_add_f32_e32 v42, v42, v48
	v_add_f32_e32 v58, v58, v64
	s_nop 0
	v_readlane_b32 s16, v26, 63
	v_readlane_b32 s17, v42, 63
	v_readlane_b32 s18, v58, 63
	v_writelane_b32 v1, s16, 3
	v_writelane_b32 v1, s17, 4
	v_writelane_b32 v1, s18, 5
	ds_read_b128 v[26:29], v5 offset:24576
	ds_read_b128 v[30:33], v5 offset:25600
	ds_read_b128 v[34:37], v5 offset:26624
	ds_read_b128 v[38:41], v5 offset:27648
	ds_read_b128 v[42:45], v5 offset:28672
	ds_read_b128 v[46:49], v5 offset:29696
	ds_read_b128 v[50:53], v5 offset:30720
	ds_read_b128 v[54:57], v5 offset:31744
	ds_read_b128 v[58:61], v5 offset:32768
	ds_read_b128 v[62:65], v5 offset:33792
	ds_read_b128 v[66:69], v5 offset:34816
	ds_read_b128 v[70:73], v5 offset:35840
	s_waitcnt lgkmcnt(8)
	v_pk_fma_f32 v[28:29], v[8:9], v[28:29], 0 op_sel_hi:[1,1,0]
	v_pk_fma_f32 v[26:27], v[6:7], v[26:27], 0 op_sel_hi:[1,1,0]
	v_pk_fma_f32 v[28:29], v[12:13], v[32:33], v[28:29]
	v_pk_fma_f32 v[26:27], v[10:11], v[30:31], v[26:27]
	v_pk_fma_f32 v[28:29], v[16:17], v[36:37], v[28:29]
	v_pk_fma_f32 v[26:27], v[14:15], v[34:35], v[26:27]
	v_pk_fma_f32 v[28:29], v[20:21], v[40:41], v[28:29]
	v_pk_fma_f32 v[26:27], v[18:19], v[38:39], v[26:27]
	s_waitcnt lgkmcnt(4)
	v_pk_fma_f32 v[44:45], v[8:9], v[44:45], 0 op_sel_hi:[1,1,0]
	v_pk_fma_f32 v[42:43], v[6:7], v[42:43], 0 op_sel_hi:[1,1,0]
	v_pk_fma_f32 v[44:45], v[12:13], v[48:49], v[44:45]
	v_pk_fma_f32 v[42:43], v[10:11], v[46:47], v[42:43]
	v_pk_fma_f32 v[44:45], v[16:17], v[52:53], v[44:45]
	v_pk_fma_f32 v[42:43], v[14:15], v[50:51], v[42:43]
	v_pk_fma_f32 v[44:45], v[20:21], v[56:57], v[44:45]
	v_pk_fma_f32 v[42:43], v[18:19], v[54:55], v[42:43]
	s_waitcnt lgkmcnt(0)
	v_pk_fma_f32 v[60:61], v[8:9], v[60:61], 0 op_sel_hi:[1,1,0]
	v_pk_fma_f32 v[58:59], v[6:7], v[58:59], 0 op_sel_hi:[1,1,0]
	v_pk_fma_f32 v[60:61], v[12:13], v[64:65], v[60:61]
	v_pk_fma_f32 v[58:59], v[10:11], v[62:63], v[58:59]
	v_pk_fma_f32 v[60:61], v[16:17], v[68:69], v[60:61]
	v_pk_fma_f32 v[58:59], v[14:15], v[66:67], v[58:59]
	v_pk_fma_f32 v[60:61], v[20:21], v[72:73], v[60:61]
	v_pk_fma_f32 v[58:59], v[18:19], v[70:71], v[58:59]
	v_add_f32_e32 v30, v28, v29
	v_add_f32_e32 v46, v44, v45
	v_add_f32_e32 v62, v60, v61
	v_add_f32_e32 v26, v26, v27
	v_add_f32_e32 v42, v42, v43
	v_add_f32_e32 v58, v58, v59
	v_mov_b32_e32 v31, 0
	v_mov_b32_e32 v47, 0
	v_mov_b32_e32 v63, 0
	v_add_f32_e32 v26, v26, v30
	v_add_f32_e32 v42, v42, v46
	v_add_f32_e32 v58, v58, v62
	v_mov_b32_e32 v32, 0
	v_mov_b32_e32 v48, 0
	v_mov_b32_e32 v64, 0
	v_add_f32_dpp v26, v26, v26 quad_perm:[1,0,3,2] row_mask:0xf bank_mask:0xf bound_ctrl:1
	v_add_f32_dpp v42, v42, v42 quad_perm:[1,0,3,2] row_mask:0xf bank_mask:0xf bound_ctrl:1
	v_add_f32_dpp v58, v58, v58 quad_perm:[1,0,3,2] row_mask:0xf bank_mask:0xf bound_ctrl:1
	v_add_f32_dpp v26, v26, v26 quad_perm:[2,3,0,1] row_mask:0xf bank_mask:0xf bound_ctrl:1
	v_add_f32_dpp v42, v42, v42 quad_perm:[2,3,0,1] row_mask:0xf bank_mask:0xf bound_ctrl:1
	v_add_f32_dpp v58, v58, v58 quad_perm:[2,3,0,1] row_mask:0xf bank_mask:0xf bound_ctrl:1
	v_add_f32_dpp v26, v26, v26 row_half_mirror row_mask:0xf bank_mask:0xf bound_ctrl:1
	v_add_f32_dpp v42, v42, v42 row_half_mirror row_mask:0xf bank_mask:0xf bound_ctrl:1
	v_add_f32_dpp v58, v58, v58 row_half_mirror row_mask:0xf bank_mask:0xf bound_ctrl:1
	v_add_f32_dpp v26, v26, v26 row_mirror row_mask:0xf bank_mask:0xf bound_ctrl:1
	v_add_f32_dpp v42, v42, v42 row_mirror row_mask:0xf bank_mask:0xf bound_ctrl:1
	v_add_f32_dpp v58, v58, v58 row_mirror row_mask:0xf bank_mask:0xf bound_ctrl:1
	v_mov_b32_dpp v31, v26 row_bcast:15 row_mask:0xa bank_mask:0xf
	v_mov_b32_dpp v47, v42 row_bcast:15 row_mask:0xa bank_mask:0xf
	v_mov_b32_dpp v63, v58 row_bcast:15 row_mask:0xa bank_mask:0xf
	v_add_f32_e32 v26, v26, v31
	v_add_f32_e32 v42, v42, v47
	v_add_f32_e32 v58, v58, v63
	v_mov_b32_dpp v32, v26 row_bcast:31 row_mask:0xc bank_mask:0xf
	v_mov_b32_dpp v48, v42 row_bcast:31 row_mask:0xc bank_mask:0xf
	v_mov_b32_dpp v64, v58 row_bcast:31 row_mask:0xc bank_mask:0xf
	v_add_f32_e32 v26, v26, v32
	v_add_f32_e32 v42, v42, v48
	v_add_f32_e32 v58, v58, v64
	s_nop 0
	v_readlane_b32 s16, v26, 63
	v_readlane_b32 s17, v42, 63
	v_readlane_b32 s18, v58, 63
	v_writelane_b32 v1, s16, 6
	v_writelane_b32 v1, s17, 7
	v_writelane_b32 v1, s18, 8
	ds_read_b128 v[26:29], v5 offset:36864
	ds_read_b128 v[30:33], v5 offset:37888
	ds_read_b128 v[34:37], v5 offset:38912
	ds_read_b128 v[38:41], v5 offset:39936
	ds_read_b128 v[42:45], v5 offset:40960
	ds_read_b128 v[46:49], v5 offset:41984
	ds_read_b128 v[50:53], v5 offset:43008
	ds_read_b128 v[54:57], v5 offset:44032
	ds_read_b128 v[58:61], v5 offset:45056
	ds_read_b128 v[62:65], v5 offset:46080
	ds_read_b128 v[66:69], v5 offset:47104
	ds_read_b128 v[70:73], v5 offset:48128
	s_waitcnt lgkmcnt(8)
	v_pk_fma_f32 v[28:29], v[8:9], v[28:29], 0 op_sel_hi:[1,1,0]
	v_pk_fma_f32 v[26:27], v[6:7], v[26:27], 0 op_sel_hi:[1,1,0]
	v_pk_fma_f32 v[28:29], v[12:13], v[32:33], v[28:29]
	v_pk_fma_f32 v[26:27], v[10:11], v[30:31], v[26:27]
	v_pk_fma_f32 v[28:29], v[16:17], v[36:37], v[28:29]
	v_pk_fma_f32 v[26:27], v[14:15], v[34:35], v[26:27]
	v_pk_fma_f32 v[28:29], v[20:21], v[40:41], v[28:29]
	v_pk_fma_f32 v[26:27], v[18:19], v[38:39], v[26:27]
	s_waitcnt lgkmcnt(4)
	v_pk_fma_f32 v[44:45], v[8:9], v[44:45], 0 op_sel_hi:[1,1,0]
	v_pk_fma_f32 v[42:43], v[6:7], v[42:43], 0 op_sel_hi:[1,1,0]
	v_pk_fma_f32 v[44:45], v[12:13], v[48:49], v[44:45]
	v_pk_fma_f32 v[42:43], v[10:11], v[46:47], v[42:43]
	v_pk_fma_f32 v[44:45], v[16:17], v[52:53], v[44:45]
	v_pk_fma_f32 v[42:43], v[14:15], v[50:51], v[42:43]
	v_pk_fma_f32 v[44:45], v[20:21], v[56:57], v[44:45]
	v_pk_fma_f32 v[42:43], v[18:19], v[54:55], v[42:43]
	s_waitcnt lgkmcnt(0)
	v_pk_fma_f32 v[60:61], v[8:9], v[60:61], 0 op_sel_hi:[1,1,0]
	v_pk_fma_f32 v[58:59], v[6:7], v[58:59], 0 op_sel_hi:[1,1,0]
	v_pk_fma_f32 v[60:61], v[12:13], v[64:65], v[60:61]
	v_pk_fma_f32 v[58:59], v[10:11], v[62:63], v[58:59]
	v_pk_fma_f32 v[60:61], v[16:17], v[68:69], v[60:61]
	v_pk_fma_f32 v[58:59], v[14:15], v[66:67], v[58:59]
	v_pk_fma_f32 v[60:61], v[20:21], v[72:73], v[60:61]
	v_pk_fma_f32 v[58:59], v[18:19], v[70:71], v[58:59]
	v_add_f32_e32 v30, v28, v29
	v_add_f32_e32 v46, v44, v45
	v_add_f32_e32 v62, v60, v61
	v_add_f32_e32 v26, v26, v27
	v_add_f32_e32 v42, v42, v43
	v_add_f32_e32 v58, v58, v59
	v_mov_b32_e32 v31, 0
	v_mov_b32_e32 v47, 0
	v_mov_b32_e32 v63, 0
	v_add_f32_e32 v26, v26, v30
	v_add_f32_e32 v42, v42, v46
	v_add_f32_e32 v58, v58, v62
	v_mov_b32_e32 v32, 0
	v_mov_b32_e32 v48, 0
	v_mov_b32_e32 v64, 0
	v_add_f32_dpp v26, v26, v26 quad_perm:[1,0,3,2] row_mask:0xf bank_mask:0xf bound_ctrl:1
	v_add_f32_dpp v42, v42, v42 quad_perm:[1,0,3,2] row_mask:0xf bank_mask:0xf bound_ctrl:1
	v_add_f32_dpp v58, v58, v58 quad_perm:[1,0,3,2] row_mask:0xf bank_mask:0xf bound_ctrl:1
	v_add_f32_dpp v26, v26, v26 quad_perm:[2,3,0,1] row_mask:0xf bank_mask:0xf bound_ctrl:1
	v_add_f32_dpp v42, v42, v42 quad_perm:[2,3,0,1] row_mask:0xf bank_mask:0xf bound_ctrl:1
	v_add_f32_dpp v58, v58, v58 quad_perm:[2,3,0,1] row_mask:0xf bank_mask:0xf bound_ctrl:1
	v_add_f32_dpp v26, v26, v26 row_half_mirror row_mask:0xf bank_mask:0xf bound_ctrl:1
	v_add_f32_dpp v42, v42, v42 row_half_mirror row_mask:0xf bank_mask:0xf bound_ctrl:1
	v_add_f32_dpp v58, v58, v58 row_half_mirror row_mask:0xf bank_mask:0xf bound_ctrl:1
	v_add_f32_dpp v26, v26, v26 row_mirror row_mask:0xf bank_mask:0xf bound_ctrl:1
	v_add_f32_dpp v42, v42, v42 row_mirror row_mask:0xf bank_mask:0xf bound_ctrl:1
	v_add_f32_dpp v58, v58, v58 row_mirror row_mask:0xf bank_mask:0xf bound_ctrl:1
	v_mov_b32_dpp v31, v26 row_bcast:15 row_mask:0xa bank_mask:0xf
	v_mov_b32_dpp v47, v42 row_bcast:15 row_mask:0xa bank_mask:0xf
	v_mov_b32_dpp v63, v58 row_bcast:15 row_mask:0xa bank_mask:0xf
	v_add_f32_e32 v26, v26, v31
	v_add_f32_e32 v42, v42, v47
	v_add_f32_e32 v58, v58, v63
	v_mov_b32_dpp v32, v26 row_bcast:31 row_mask:0xc bank_mask:0xf
	v_mov_b32_dpp v48, v42 row_bcast:31 row_mask:0xc bank_mask:0xf
	v_mov_b32_dpp v64, v58 row_bcast:31 row_mask:0xc bank_mask:0xf
	v_add_f32_e32 v26, v26, v32
	v_add_f32_e32 v42, v42, v48
	v_add_f32_e32 v58, v58, v64
	s_nop 0
	v_readlane_b32 s16, v26, 63
	v_readlane_b32 s17, v42, 63
	v_readlane_b32 s18, v58, 63
	v_writelane_b32 v1, s16, 9
	v_writelane_b32 v1, s17, 10
	v_writelane_b32 v1, s18, 11
	s_mov_b64 s[26:27], exec
	s_mov_b32 exec_lo, 0xfff
	s_mov_b32 exec_hi, 0
	global_store_dword v25, v1, s[42:43]
	s_mov_b64 exec, s[26:27]
	s_add_u32 s40, s40, 0x400000
	s_addc_u32 s41, s41, 0
	s_add_u32 s42, s42, 0x20000
	s_addc_u32 s43, s43, 0
	s_waitcnt vmcnt(36)
	v_pk_mul_f32 v[50:51], v[162:163], v[162:163]
	v_pk_mul_f32 v[52:53], v[160:161], v[160:161]
	v_pk_mul_f32 v[54:55], v[166:167], v[166:167]
	v_pk_mul_f32 v[56:57], v[164:165], v[164:165]
	v_mul_f32_e32 v58, v169, v169
	v_mul_f32_e32 v60, v171, v171
	v_pk_mul_f32 v[64:65], v[172:173], v[172:173]
	v_pk_mul_f32 v[66:67], v[174:175], v[174:175]
	v_add_f32_e32 v52, v53, v52
	v_add_f32_e32 v50, v50, v51
	v_add_f32_e32 v56, v57, v56
	v_add_f32_e32 v54, v54, v55
	v_fma_f32 v58, v168, v168, v58
	v_fma_f32 v60, v170, v170, v60
	v_add_f32_e32 v64, v64, v65
	v_add_f32_e32 v66, v66, v67
	v_add_f32_e32 v52, v52, v50
	v_add_f32_e32 v56, v56, v54
	v_add_f32_e32 v58, v58, v60
	v_add_f32_e32 v64, v64, v66
	v_add_f32_e32 v50, v52, v56
	v_mov_b32_e32 v61, 0
	v_mov_b32_e32 v62, 0
	v_add_f32_e32 v50, v50, v58
	s_nop 0
	v_add_f32_e32 v50, v50, v64
	s_nop 1
	v_add_f32_dpp v50, v50, v50 quad_perm:[1,0,3,2] row_mask:0xf bank_mask:0xf bound_ctrl:1
	s_nop 1
	v_add_f32_dpp v50, v50, v50 quad_perm:[2,3,0,1] row_mask:0xf bank_mask:0xf bound_ctrl:1
	s_nop 1
	v_add_f32_dpp v50, v50, v50 row_half_mirror row_mask:0xf bank_mask:0xf bound_ctrl:1
	s_nop 1
	v_add_f32_dpp v50, v50, v50 row_mirror row_mask:0xf bank_mask:0xf bound_ctrl:1
	s_nop 1
	v_mov_b32_dpp v61, v50 row_bcast:15 row_mask:0xa bank_mask:0xf
	s_nop 1
	v_add_f32_e32 v50, v50, v61
	s_nop 1
	v_mov_b32_dpp v62, v50 row_bcast:31 row_mask:0xc bank_mask:0xf
	s_nop 1
	v_add_f32_e32 v50, v50, v62
	s_nop 0
	v_readlane_b32 s15, v50, 63
	s_nop 1
	v_fma_f32 v50, s15, v24, v23
	v_mul_f32_e32 v51, 0x4b800000, v50
	v_cmp_gt_f32_e32 vcc, s5, v50
	s_nop 1
	v_cndmask_b32_e32 v50, v50, v51, vcc
	v_rsq_f32_e32 v52, v50
	s_nop 0
	v_mul_f32_e32 v53, 0x45800000, v52
	v_cndmask_b32_e32 v52, v52, v53, vcc
	v_pk_mul_f32 v[6:7], v[160:161], v[52:53] op_sel_hi:[1,0]
	v_pk_mul_f32 v[8:9], v[162:163], v[52:53] op_sel_hi:[1,0]
	v_pk_mul_f32 v[10:11], v[164:165], v[52:53] op_sel_hi:[1,0]
	v_pk_mul_f32 v[12:13], v[166:167], v[52:53] op_sel_hi:[1,0]
	v_pk_mul_f32 v[14:15], v[168:169], v[52:53] op_sel_hi:[1,0]
	v_pk_mul_f32 v[16:17], v[170:171], v[52:53] op_sel_hi:[1,0]
	v_pk_mul_f32 v[18:19], v[172:173], v[52:53] op_sel_hi:[1,0]
	v_pk_mul_f32 v[20:21], v[174:175], v[52:53] op_sel_hi:[1,0]
	v_pk_mul_f32 v[6:7], v[80:81], v[6:7]
	v_pk_mul_f32 v[8:9], v[82:83], v[8:9]
	v_pk_mul_f32 v[10:11], v[84:85], v[10:11]
	v_pk_mul_f32 v[12:13], v[86:87], v[12:13]
	v_pk_mul_f32 v[14:15], v[88:89], v[14:15]
	v_pk_mul_f32 v[16:17], v[90:91], v[16:17]
	v_pk_mul_f32 v[18:19], v[92:93], v[18:19]
	v_pk_mul_f32 v[20:21], v[94:95], v[20:21]
	v_cvt_pk_bf16_f32 v240, v6, v7
	v_cvt_pk_bf16_f32 v241, v8, v9
	v_cvt_pk_bf16_f32 v242, v10, v11
	v_cvt_pk_bf16_f32 v243, v12, v13
	v_cvt_pk_bf16_f32 v244, v14, v15
	v_cvt_pk_bf16_f32 v245, v16, v17
	v_cvt_pk_bf16_f32 v246, v18, v19
	v_cvt_pk_bf16_f32 v247, v20, v21
	global_store_dwordx2 v2, v[240:241], s[40:41] offset:0
	global_store_dwordx2 v2, v[242:243], s[40:41] offset:512
	global_store_dwordx2 v2, v[244:245], s[40:41] offset:1024
	global_store_dwordx2 v2, v[246:247], s[40:41] offset:1536
	ds_read_b128 v[26:29], v5 offset:0
	ds_read_b128 v[30:33], v5 offset:1024
	ds_read_b128 v[34:37], v5 offset:2048
	ds_read_b128 v[38:41], v5 offset:3072
	ds_read_b128 v[42:45], v5 offset:4096
	ds_read_b128 v[46:49], v5 offset:5120
	ds_read_b128 v[50:53], v5 offset:6144
	ds_read_b128 v[54:57], v5 offset:7168
	ds_read_b128 v[58:61], v5 offset:8192
	ds_read_b128 v[62:65], v5 offset:9216
	ds_read_b128 v[66:69], v5 offset:10240
	ds_read_b128 v[70:73], v5 offset:11264
	s_waitcnt lgkmcnt(8)
	v_pk_fma_f32 v[28:29], v[8:9], v[28:29], 0 op_sel_hi:[1,1,0]
	v_pk_fma_f32 v[26:27], v[6:7], v[26:27], 0 op_sel_hi:[1,1,0]
	v_pk_fma_f32 v[28:29], v[12:13], v[32:33], v[28:29]
	v_pk_fma_f32 v[26:27], v[10:11], v[30:31], v[26:27]
	v_pk_fma_f32 v[28:29], v[16:17], v[36:37], v[28:29]
	v_pk_fma_f32 v[26:27], v[14:15], v[34:35], v[26:27]
	v_pk_fma_f32 v[28:29], v[20:21], v[40:41], v[28:29]
	v_pk_fma_f32 v[26:27], v[18:19], v[38:39], v[26:27]
	s_waitcnt lgkmcnt(4)
	v_pk_fma_f32 v[44:45], v[8:9], v[44:45], 0 op_sel_hi:[1,1,0]
	v_pk_fma_f32 v[42:43], v[6:7], v[42:43], 0 op_sel_hi:[1,1,0]
	v_pk_fma_f32 v[44:45], v[12:13], v[48:49], v[44:45]
	v_pk_fma_f32 v[42:43], v[10:11], v[46:47], v[42:43]
	v_pk_fma_f32 v[44:45], v[16:17], v[52:53], v[44:45]
	v_pk_fma_f32 v[42:43], v[14:15], v[50:51], v[42:43]
	v_pk_fma_f32 v[44:45], v[20:21], v[56:57], v[44:45]
	v_pk_fma_f32 v[42:43], v[18:19], v[54:55], v[42:43]
	s_waitcnt lgkmcnt(0)
	v_pk_fma_f32 v[60:61], v[8:9], v[60:61], 0 op_sel_hi:[1,1,0]
	v_pk_fma_f32 v[58:59], v[6:7], v[58:59], 0 op_sel_hi:[1,1,0]
	v_pk_fma_f32 v[60:61], v[12:13], v[64:65], v[60:61]
	v_pk_fma_f32 v[58:59], v[10:11], v[62:63], v[58:59]
	v_pk_fma_f32 v[60:61], v[16:17], v[68:69], v[60:61]
	v_pk_fma_f32 v[58:59], v[14:15], v[66:67], v[58:59]
	v_pk_fma_f32 v[60:61], v[20:21], v[72:73], v[60:61]
	v_pk_fma_f32 v[58:59], v[18:19], v[70:71], v[58:59]
	v_add_f32_e32 v30, v28, v29
	v_add_f32_e32 v46, v44, v45
	v_add_f32_e32 v62, v60, v61
	v_add_f32_e32 v26, v26, v27
	v_add_f32_e32 v42, v42, v43
	v_add_f32_e32 v58, v58, v59
	v_mov_b32_e32 v31, 0
	v_mov_b32_e32 v47, 0
	v_mov_b32_e32 v63, 0
	v_add_f32_e32 v26, v26, v30
	v_add_f32_e32 v42, v42, v46
	v_add_f32_e32 v58, v58, v62
	v_mov_b32_e32 v32, 0
	v_mov_b32_e32 v48, 0
	v_mov_b32_e32 v64, 0
	v_add_f32_dpp v26, v26, v26 quad_perm:[1,0,3,2] row_mask:0xf bank_mask:0xf bound_ctrl:1
	v_add_f32_dpp v42, v42, v42 quad_perm:[1,0,3,2] row_mask:0xf bank_mask:0xf bound_ctrl:1
	v_add_f32_dpp v58, v58, v58 quad_perm:[1,0,3,2] row_mask:0xf bank_mask:0xf bound_ctrl:1
	v_add_f32_dpp v26, v26, v26 quad_perm:[2,3,0,1] row_mask:0xf bank_mask:0xf bound_ctrl:1
	v_add_f32_dpp v42, v42, v42 quad_perm:[2,3,0,1] row_mask:0xf bank_mask:0xf bound_ctrl:1
	v_add_f32_dpp v58, v58, v58 quad_perm:[2,3,0,1] row_mask:0xf bank_mask:0xf bound_ctrl:1
	v_add_f32_dpp v26, v26, v26 row_half_mirror row_mask:0xf bank_mask:0xf bound_ctrl:1
	v_add_f32_dpp v42, v42, v42 row_half_mirror row_mask:0xf bank_mask:0xf bound_ctrl:1
	v_add_f32_dpp v58, v58, v58 row_half_mirror row_mask:0xf bank_mask:0xf bound_ctrl:1
	v_add_f32_dpp v26, v26, v26 row_mirror row_mask:0xf bank_mask:0xf bound_ctrl:1
	v_add_f32_dpp v42, v42, v42 row_mirror row_mask:0xf bank_mask:0xf bound_ctrl:1
	v_add_f32_dpp v58, v58, v58 row_mirror row_mask:0xf bank_mask:0xf bound_ctrl:1
	v_mov_b32_dpp v31, v26 row_bcast:15 row_mask:0xa bank_mask:0xf
	v_mov_b32_dpp v47, v42 row_bcast:15 row_mask:0xa bank_mask:0xf
	v_mov_b32_dpp v63, v58 row_bcast:15 row_mask:0xa bank_mask:0xf
	v_add_f32_e32 v26, v26, v31
	v_add_f32_e32 v42, v42, v47
	v_add_f32_e32 v58, v58, v63
	v_mov_b32_dpp v32, v26 row_bcast:31 row_mask:0xc bank_mask:0xf
	v_mov_b32_dpp v48, v42 row_bcast:31 row_mask:0xc bank_mask:0xf
	v_mov_b32_dpp v64, v58 row_bcast:31 row_mask:0xc bank_mask:0xf
	v_add_f32_e32 v26, v26, v32
	v_add_f32_e32 v42, v42, v48
	v_add_f32_e32 v58, v58, v64
	s_nop 0
	v_readlane_b32 s16, v26, 63
	v_readlane_b32 s17, v42, 63
	v_readlane_b32 s18, v58, 63
	v_writelane_b32 v1, s16, 0
	v_writelane_b32 v1, s17, 1
	v_writelane_b32 v1, s18, 2
	ds_read_b128 v[26:29], v5 offset:12288
	ds_read_b128 v[30:33], v5 offset:13312
	ds_read_b128 v[34:37], v5 offset:14336
	ds_read_b128 v[38:41], v5 offset:15360
	ds_read_b128 v[42:45], v5 offset:16384
	ds_read_b128 v[46:49], v5 offset:17408
	ds_read_b128 v[50:53], v5 offset:18432
	ds_read_b128 v[54:57], v5 offset:19456
	ds_read_b128 v[58:61], v5 offset:20480
	ds_read_b128 v[62:65], v5 offset:21504
	ds_read_b128 v[66:69], v5 offset:22528
	ds_read_b128 v[70:73], v5 offset:23552
	s_waitcnt lgkmcnt(8)
	v_pk_fma_f32 v[28:29], v[8:9], v[28:29], 0 op_sel_hi:[1,1,0]
	v_pk_fma_f32 v[26:27], v[6:7], v[26:27], 0 op_sel_hi:[1,1,0]
	v_pk_fma_f32 v[28:29], v[12:13], v[32:33], v[28:29]
	v_pk_fma_f32 v[26:27], v[10:11], v[30:31], v[26:27]
	v_pk_fma_f32 v[28:29], v[16:17], v[36:37], v[28:29]
	v_pk_fma_f32 v[26:27], v[14:15], v[34:35], v[26:27]
	v_pk_fma_f32 v[28:29], v[20:21], v[40:41], v[28:29]
	v_pk_fma_f32 v[26:27], v[18:19], v[38:39], v[26:27]
	s_waitcnt lgkmcnt(4)
	v_pk_fma_f32 v[44:45], v[8:9], v[44:45], 0 op_sel_hi:[1,1,0]
	v_pk_fma_f32 v[42:43], v[6:7], v[42:43], 0 op_sel_hi:[1,1,0]
	v_pk_fma_f32 v[44:45], v[12:13], v[48:49], v[44:45]
	v_pk_fma_f32 v[42:43], v[10:11], v[46:47], v[42:43]
	v_pk_fma_f32 v[44:45], v[16:17], v[52:53], v[44:45]
	v_pk_fma_f32 v[42:43], v[14:15], v[50:51], v[42:43]
	v_pk_fma_f32 v[44:45], v[20:21], v[56:57], v[44:45]
	v_pk_fma_f32 v[42:43], v[18:19], v[54:55], v[42:43]
	s_waitcnt lgkmcnt(0)
	v_pk_fma_f32 v[60:61], v[8:9], v[60:61], 0 op_sel_hi:[1,1,0]
	v_pk_fma_f32 v[58:59], v[6:7], v[58:59], 0 op_sel_hi:[1,1,0]
	v_pk_fma_f32 v[60:61], v[12:13], v[64:65], v[60:61]
	v_pk_fma_f32 v[58:59], v[10:11], v[62:63], v[58:59]
	v_pk_fma_f32 v[60:61], v[16:17], v[68:69], v[60:61]
	v_pk_fma_f32 v[58:59], v[14:15], v[66:67], v[58:59]
	v_pk_fma_f32 v[60:61], v[20:21], v[72:73], v[60:61]
	v_pk_fma_f32 v[58:59], v[18:19], v[70:71], v[58:59]
	v_add_f32_e32 v30, v28, v29
	v_add_f32_e32 v46, v44, v45
	v_add_f32_e32 v62, v60, v61
	v_add_f32_e32 v26, v26, v27
	v_add_f32_e32 v42, v42, v43
	v_add_f32_e32 v58, v58, v59
	v_mov_b32_e32 v31, 0
	v_mov_b32_e32 v47, 0
	v_mov_b32_e32 v63, 0
	v_add_f32_e32 v26, v26, v30
	v_add_f32_e32 v42, v42, v46
	v_add_f32_e32 v58, v58, v62
	v_mov_b32_e32 v32, 0
	v_mov_b32_e32 v48, 0
	v_mov_b32_e32 v64, 0
	v_add_f32_dpp v26, v26, v26 quad_perm:[1,0,3,2] row_mask:0xf bank_mask:0xf bound_ctrl:1
	v_add_f32_dpp v42, v42, v42 quad_perm:[1,0,3,2] row_mask:0xf bank_mask:0xf bound_ctrl:1
	v_add_f32_dpp v58, v58, v58 quad_perm:[1,0,3,2] row_mask:0xf bank_mask:0xf bound_ctrl:1
	v_add_f32_dpp v26, v26, v26 quad_perm:[2,3,0,1] row_mask:0xf bank_mask:0xf bound_ctrl:1
	v_add_f32_dpp v42, v42, v42 quad_perm:[2,3,0,1] row_mask:0xf bank_mask:0xf bound_ctrl:1
	v_add_f32_dpp v58, v58, v58 quad_perm:[2,3,0,1] row_mask:0xf bank_mask:0xf bound_ctrl:1
	v_add_f32_dpp v26, v26, v26 row_half_mirror row_mask:0xf bank_mask:0xf bound_ctrl:1
	v_add_f32_dpp v42, v42, v42 row_half_mirror row_mask:0xf bank_mask:0xf bound_ctrl:1
	v_add_f32_dpp v58, v58, v58 row_half_mirror row_mask:0xf bank_mask:0xf bound_ctrl:1
	v_add_f32_dpp v26, v26, v26 row_mirror row_mask:0xf bank_mask:0xf bound_ctrl:1
	v_add_f32_dpp v42, v42, v42 row_mirror row_mask:0xf bank_mask:0xf bound_ctrl:1
	v_add_f32_dpp v58, v58, v58 row_mirror row_mask:0xf bank_mask:0xf bound_ctrl:1
	v_mov_b32_dpp v31, v26 row_bcast:15 row_mask:0xa bank_mask:0xf
	v_mov_b32_dpp v47, v42 row_bcast:15 row_mask:0xa bank_mask:0xf
	v_mov_b32_dpp v63, v58 row_bcast:15 row_mask:0xa bank_mask:0xf
	v_add_f32_e32 v26, v26, v31
	v_add_f32_e32 v42, v42, v47
	v_add_f32_e32 v58, v58, v63
	v_mov_b32_dpp v32, v26 row_bcast:31 row_mask:0xc bank_mask:0xf
	v_mov_b32_dpp v48, v42 row_bcast:31 row_mask:0xc bank_mask:0xf
	v_mov_b32_dpp v64, v58 row_bcast:31 row_mask:0xc bank_mask:0xf
	v_add_f32_e32 v26, v26, v32
	v_add_f32_e32 v42, v42, v48
	v_add_f32_e32 v58, v58, v64
	s_nop 0
	v_readlane_b32 s16, v26, 63
	v_readlane_b32 s17, v42, 63
	v_readlane_b32 s18, v58, 63
	v_writelane_b32 v1, s16, 3
	v_writelane_b32 v1, s17, 4
	v_writelane_b32 v1, s18, 5
	ds_read_b128 v[26:29], v5 offset:24576
	ds_read_b128 v[30:33], v5 offset:25600
	ds_read_b128 v[34:37], v5 offset:26624
	ds_read_b128 v[38:41], v5 offset:27648
	ds_read_b128 v[42:45], v5 offset:28672
	ds_read_b128 v[46:49], v5 offset:29696
	ds_read_b128 v[50:53], v5 offset:30720
	ds_read_b128 v[54:57], v5 offset:31744
	ds_read_b128 v[58:61], v5 offset:32768
	ds_read_b128 v[62:65], v5 offset:33792
	ds_read_b128 v[66:69], v5 offset:34816
	ds_read_b128 v[70:73], v5 offset:35840
	s_waitcnt lgkmcnt(8)
	v_pk_fma_f32 v[28:29], v[8:9], v[28:29], 0 op_sel_hi:[1,1,0]
	v_pk_fma_f32 v[26:27], v[6:7], v[26:27], 0 op_sel_hi:[1,1,0]
	v_pk_fma_f32 v[28:29], v[12:13], v[32:33], v[28:29]
	v_pk_fma_f32 v[26:27], v[10:11], v[30:31], v[26:27]
	v_pk_fma_f32 v[28:29], v[16:17], v[36:37], v[28:29]
	v_pk_fma_f32 v[26:27], v[14:15], v[34:35], v[26:27]
	v_pk_fma_f32 v[28:29], v[20:21], v[40:41], v[28:29]
	v_pk_fma_f32 v[26:27], v[18:19], v[38:39], v[26:27]
	s_waitcnt lgkmcnt(4)
	v_pk_fma_f32 v[44:45], v[8:9], v[44:45], 0 op_sel_hi:[1,1,0]
	v_pk_fma_f32 v[42:43], v[6:7], v[42:43], 0 op_sel_hi:[1,1,0]
	v_pk_fma_f32 v[44:45], v[12:13], v[48:49], v[44:45]
	v_pk_fma_f32 v[42:43], v[10:11], v[46:47], v[42:43]
	v_pk_fma_f32 v[44:45], v[16:17], v[52:53], v[44:45]
	v_pk_fma_f32 v[42:43], v[14:15], v[50:51], v[42:43]
	v_pk_fma_f32 v[44:45], v[20:21], v[56:57], v[44:45]
	v_pk_fma_f32 v[42:43], v[18:19], v[54:55], v[42:43]
	s_waitcnt lgkmcnt(0)
	v_pk_fma_f32 v[60:61], v[8:9], v[60:61], 0 op_sel_hi:[1,1,0]
	v_pk_fma_f32 v[58:59], v[6:7], v[58:59], 0 op_sel_hi:[1,1,0]
	v_pk_fma_f32 v[60:61], v[12:13], v[64:65], v[60:61]
	v_pk_fma_f32 v[58:59], v[10:11], v[62:63], v[58:59]
	v_pk_fma_f32 v[60:61], v[16:17], v[68:69], v[60:61]
	v_pk_fma_f32 v[58:59], v[14:15], v[66:67], v[58:59]
	v_pk_fma_f32 v[60:61], v[20:21], v[72:73], v[60:61]
	v_pk_fma_f32 v[58:59], v[18:19], v[70:71], v[58:59]
	v_add_f32_e32 v30, v28, v29
	v_add_f32_e32 v46, v44, v45
	v_add_f32_e32 v62, v60, v61
	v_add_f32_e32 v26, v26, v27
	v_add_f32_e32 v42, v42, v43
	v_add_f32_e32 v58, v58, v59
	v_mov_b32_e32 v31, 0
	v_mov_b32_e32 v47, 0
	v_mov_b32_e32 v63, 0
	v_add_f32_e32 v26, v26, v30
	v_add_f32_e32 v42, v42, v46
	v_add_f32_e32 v58, v58, v62
	v_mov_b32_e32 v32, 0
	v_mov_b32_e32 v48, 0
	v_mov_b32_e32 v64, 0
	v_add_f32_dpp v26, v26, v26 quad_perm:[1,0,3,2] row_mask:0xf bank_mask:0xf bound_ctrl:1
	v_add_f32_dpp v42, v42, v42 quad_perm:[1,0,3,2] row_mask:0xf bank_mask:0xf bound_ctrl:1
	v_add_f32_dpp v58, v58, v58 quad_perm:[1,0,3,2] row_mask:0xf bank_mask:0xf bound_ctrl:1
	v_add_f32_dpp v26, v26, v26 quad_perm:[2,3,0,1] row_mask:0xf bank_mask:0xf bound_ctrl:1
	v_add_f32_dpp v42, v42, v42 quad_perm:[2,3,0,1] row_mask:0xf bank_mask:0xf bound_ctrl:1
	v_add_f32_dpp v58, v58, v58 quad_perm:[2,3,0,1] row_mask:0xf bank_mask:0xf bound_ctrl:1
	v_add_f32_dpp v26, v26, v26 row_half_mirror row_mask:0xf bank_mask:0xf bound_ctrl:1
	v_add_f32_dpp v42, v42, v42 row_half_mirror row_mask:0xf bank_mask:0xf bound_ctrl:1
	v_add_f32_dpp v58, v58, v58 row_half_mirror row_mask:0xf bank_mask:0xf bound_ctrl:1
	v_add_f32_dpp v26, v26, v26 row_mirror row_mask:0xf bank_mask:0xf bound_ctrl:1
	v_add_f32_dpp v42, v42, v42 row_mirror row_mask:0xf bank_mask:0xf bound_ctrl:1
	v_add_f32_dpp v58, v58, v58 row_mirror row_mask:0xf bank_mask:0xf bound_ctrl:1
	v_mov_b32_dpp v31, v26 row_bcast:15 row_mask:0xa bank_mask:0xf
	v_mov_b32_dpp v47, v42 row_bcast:15 row_mask:0xa bank_mask:0xf
	v_mov_b32_dpp v63, v58 row_bcast:15 row_mask:0xa bank_mask:0xf
	v_add_f32_e32 v26, v26, v31
	v_add_f32_e32 v42, v42, v47
	v_add_f32_e32 v58, v58, v63
	v_mov_b32_dpp v32, v26 row_bcast:31 row_mask:0xc bank_mask:0xf
	v_mov_b32_dpp v48, v42 row_bcast:31 row_mask:0xc bank_mask:0xf
	v_mov_b32_dpp v64, v58 row_bcast:31 row_mask:0xc bank_mask:0xf
	v_add_f32_e32 v26, v26, v32
	v_add_f32_e32 v42, v42, v48
	v_add_f32_e32 v58, v58, v64
	s_nop 0
	v_readlane_b32 s16, v26, 63
	v_readlane_b32 s17, v42, 63
	v_readlane_b32 s18, v58, 63
	v_writelane_b32 v1, s16, 6
	v_writelane_b32 v1, s17, 7
	v_writelane_b32 v1, s18, 8
	ds_read_b128 v[26:29], v5 offset:36864
	ds_read_b128 v[30:33], v5 offset:37888
	ds_read_b128 v[34:37], v5 offset:38912
	ds_read_b128 v[38:41], v5 offset:39936
	ds_read_b128 v[42:45], v5 offset:40960
	ds_read_b128 v[46:49], v5 offset:41984
	ds_read_b128 v[50:53], v5 offset:43008
	ds_read_b128 v[54:57], v5 offset:44032
	ds_read_b128 v[58:61], v5 offset:45056
	ds_read_b128 v[62:65], v5 offset:46080
	ds_read_b128 v[66:69], v5 offset:47104
	ds_read_b128 v[70:73], v5 offset:48128
	s_waitcnt lgkmcnt(8)
	v_pk_fma_f32 v[28:29], v[8:9], v[28:29], 0 op_sel_hi:[1,1,0]
	v_pk_fma_f32 v[26:27], v[6:7], v[26:27], 0 op_sel_hi:[1,1,0]
	v_pk_fma_f32 v[28:29], v[12:13], v[32:33], v[28:29]
	v_pk_fma_f32 v[26:27], v[10:11], v[30:31], v[26:27]
	v_pk_fma_f32 v[28:29], v[16:17], v[36:37], v[28:29]
	v_pk_fma_f32 v[26:27], v[14:15], v[34:35], v[26:27]
	v_pk_fma_f32 v[28:29], v[20:21], v[40:41], v[28:29]
	v_pk_fma_f32 v[26:27], v[18:19], v[38:39], v[26:27]
	s_waitcnt lgkmcnt(4)
	v_pk_fma_f32 v[44:45], v[8:9], v[44:45], 0 op_sel_hi:[1,1,0]
	v_pk_fma_f32 v[42:43], v[6:7], v[42:43], 0 op_sel_hi:[1,1,0]
	v_pk_fma_f32 v[44:45], v[12:13], v[48:49], v[44:45]
	v_pk_fma_f32 v[42:43], v[10:11], v[46:47], v[42:43]
	v_pk_fma_f32 v[44:45], v[16:17], v[52:53], v[44:45]
	v_pk_fma_f32 v[42:43], v[14:15], v[50:51], v[42:43]
	v_pk_fma_f32 v[44:45], v[20:21], v[56:57], v[44:45]
	v_pk_fma_f32 v[42:43], v[18:19], v[54:55], v[42:43]
	s_waitcnt lgkmcnt(0)
	v_pk_fma_f32 v[60:61], v[8:9], v[60:61], 0 op_sel_hi:[1,1,0]
	v_pk_fma_f32 v[58:59], v[6:7], v[58:59], 0 op_sel_hi:[1,1,0]
	v_pk_fma_f32 v[60:61], v[12:13], v[64:65], v[60:61]
	v_pk_fma_f32 v[58:59], v[10:11], v[62:63], v[58:59]
	v_pk_fma_f32 v[60:61], v[16:17], v[68:69], v[60:61]
	v_pk_fma_f32 v[58:59], v[14:15], v[66:67], v[58:59]
	v_pk_fma_f32 v[60:61], v[20:21], v[72:73], v[60:61]
	v_pk_fma_f32 v[58:59], v[18:19], v[70:71], v[58:59]
	v_add_f32_e32 v30, v28, v29
	v_add_f32_e32 v46, v44, v45
	v_add_f32_e32 v62, v60, v61
	v_add_f32_e32 v26, v26, v27
	v_add_f32_e32 v42, v42, v43
	v_add_f32_e32 v58, v58, v59
	v_mov_b32_e32 v31, 0
	v_mov_b32_e32 v47, 0
	v_mov_b32_e32 v63, 0
	v_add_f32_e32 v26, v26, v30
	v_add_f32_e32 v42, v42, v46
	v_add_f32_e32 v58, v58, v62
	v_mov_b32_e32 v32, 0
	v_mov_b32_e32 v48, 0
	v_mov_b32_e32 v64, 0
	v_add_f32_dpp v26, v26, v26 quad_perm:[1,0,3,2] row_mask:0xf bank_mask:0xf bound_ctrl:1
	v_add_f32_dpp v42, v42, v42 quad_perm:[1,0,3,2] row_mask:0xf bank_mask:0xf bound_ctrl:1
	v_add_f32_dpp v58, v58, v58 quad_perm:[1,0,3,2] row_mask:0xf bank_mask:0xf bound_ctrl:1
	v_add_f32_dpp v26, v26, v26 quad_perm:[2,3,0,1] row_mask:0xf bank_mask:0xf bound_ctrl:1
	v_add_f32_dpp v42, v42, v42 quad_perm:[2,3,0,1] row_mask:0xf bank_mask:0xf bound_ctrl:1
	v_add_f32_dpp v58, v58, v58 quad_perm:[2,3,0,1] row_mask:0xf bank_mask:0xf bound_ctrl:1
	v_add_f32_dpp v26, v26, v26 row_half_mirror row_mask:0xf bank_mask:0xf bound_ctrl:1
	v_add_f32_dpp v42, v42, v42 row_half_mirror row_mask:0xf bank_mask:0xf bound_ctrl:1
	v_add_f32_dpp v58, v58, v58 row_half_mirror row_mask:0xf bank_mask:0xf bound_ctrl:1
	v_add_f32_dpp v26, v26, v26 row_mirror row_mask:0xf bank_mask:0xf bound_ctrl:1
	v_add_f32_dpp v42, v42, v42 row_mirror row_mask:0xf bank_mask:0xf bound_ctrl:1
	v_add_f32_dpp v58, v58, v58 row_mirror row_mask:0xf bank_mask:0xf bound_ctrl:1
	v_mov_b32_dpp v31, v26 row_bcast:15 row_mask:0xa bank_mask:0xf
	v_mov_b32_dpp v47, v42 row_bcast:15 row_mask:0xa bank_mask:0xf
	v_mov_b32_dpp v63, v58 row_bcast:15 row_mask:0xa bank_mask:0xf
	v_add_f32_e32 v26, v26, v31
	v_add_f32_e32 v42, v42, v47
	v_add_f32_e32 v58, v58, v63
	v_mov_b32_dpp v32, v26 row_bcast:31 row_mask:0xc bank_mask:0xf
	v_mov_b32_dpp v48, v42 row_bcast:31 row_mask:0xc bank_mask:0xf
	v_mov_b32_dpp v64, v58 row_bcast:31 row_mask:0xc bank_mask:0xf
	v_add_f32_e32 v26, v26, v32
	v_add_f32_e32 v42, v42, v48
	v_add_f32_e32 v58, v58, v64
	s_nop 0
	v_readlane_b32 s16, v26, 63
	v_readlane_b32 s17, v42, 63
	v_readlane_b32 s18, v58, 63
	v_writelane_b32 v1, s16, 9
	v_writelane_b32 v1, s17, 10
	v_writelane_b32 v1, s18, 11
	s_mov_b64 s[26:27], exec
	s_mov_b32 exec_lo, 0xfff
	s_mov_b32 exec_hi, 0
	global_store_dword v25, v1, s[42:43]
	s_mov_b64 exec, s[26:27]
	s_add_u32 s40, s40, 0x400000
	s_addc_u32 s41, s41, 0
	s_add_u32 s42, s42, 0x20000
	s_addc_u32 s43, s43, 0
	s_waitcnt vmcnt(37)
	v_pk_mul_f32 v[50:51], v[178:179], v[178:179]
	v_pk_mul_f32 v[52:53], v[176:177], v[176:177]
	v_pk_mul_f32 v[54:55], v[182:183], v[182:183]
	v_pk_mul_f32 v[56:57], v[180:181], v[180:181]
	v_mul_f32_e32 v58, v185, v185
	v_mul_f32_e32 v60, v187, v187
	v_pk_mul_f32 v[64:65], v[188:189], v[188:189]
	v_pk_mul_f32 v[66:67], v[190:191], v[190:191]
	v_add_f32_e32 v52, v53, v52
	v_add_f32_e32 v50, v50, v51
	v_add_f32_e32 v56, v57, v56
	v_add_f32_e32 v54, v54, v55
	v_fma_f32 v58, v184, v184, v58
	v_fma_f32 v60, v186, v186, v60
	v_add_f32_e32 v64, v64, v65
	v_add_f32_e32 v66, v66, v67
	v_add_f32_e32 v52, v52, v50
	v_add_f32_e32 v56, v56, v54
	v_add_f32_e32 v58, v58, v60
	v_add_f32_e32 v64, v64, v66
	v_add_f32_e32 v50, v52, v56
	v_mov_b32_e32 v61, 0
	v_mov_b32_e32 v62, 0
	v_add_f32_e32 v50, v50, v58
	s_nop 0
	v_add_f32_e32 v50, v50, v64
	s_nop 1
	v_add_f32_dpp v50, v50, v50 quad_perm:[1,0,3,2] row_mask:0xf bank_mask:0xf bound_ctrl:1
	s_nop 1
	v_add_f32_dpp v50, v50, v50 quad_perm:[2,3,0,1] row_mask:0xf bank_mask:0xf bound_ctrl:1
	s_nop 1
	v_add_f32_dpp v50, v50, v50 row_half_mirror row_mask:0xf bank_mask:0xf bound_ctrl:1
	s_nop 1
	v_add_f32_dpp v50, v50, v50 row_mirror row_mask:0xf bank_mask:0xf bound_ctrl:1
	s_nop 1
	v_mov_b32_dpp v61, v50 row_bcast:15 row_mask:0xa bank_mask:0xf
	s_nop 1
	v_add_f32_e32 v50, v50, v61
	s_nop 1
	v_mov_b32_dpp v62, v50 row_bcast:31 row_mask:0xc bank_mask:0xf
	s_nop 1
	v_add_f32_e32 v50, v50, v62
	s_nop 0
	v_readlane_b32 s15, v50, 63
	s_nop 1
	v_fma_f32 v50, s15, v24, v23
	v_mul_f32_e32 v51, 0x4b800000, v50
	v_cmp_gt_f32_e32 vcc, s5, v50
	s_nop 1
	v_cndmask_b32_e32 v50, v50, v51, vcc
	v_rsq_f32_e32 v52, v50
	s_nop 0
	v_mul_f32_e32 v53, 0x45800000, v52
	v_cndmask_b32_e32 v52, v52, v53, vcc
	v_pk_mul_f32 v[6:7], v[176:177], v[52:53] op_sel_hi:[1,0]
	v_pk_mul_f32 v[8:9], v[178:179], v[52:53] op_sel_hi:[1,0]
	v_pk_mul_f32 v[10:11], v[180:181], v[52:53] op_sel_hi:[1,0]
	v_pk_mul_f32 v[12:13], v[182:183], v[52:53] op_sel_hi:[1,0]
	v_pk_mul_f32 v[14:15], v[184:185], v[52:53] op_sel_hi:[1,0]
	v_pk_mul_f32 v[16:17], v[186:187], v[52:53] op_sel_hi:[1,0]
	v_pk_mul_f32 v[18:19], v[188:189], v[52:53] op_sel_hi:[1,0]
	v_pk_mul_f32 v[20:21], v[190:191], v[52:53] op_sel_hi:[1,0]
	v_pk_mul_f32 v[6:7], v[80:81], v[6:7]
	v_pk_mul_f32 v[8:9], v[82:83], v[8:9]
	v_pk_mul_f32 v[10:11], v[84:85], v[10:11]
	v_pk_mul_f32 v[12:13], v[86:87], v[12:13]
	v_pk_mul_f32 v[14:15], v[88:89], v[14:15]
	v_pk_mul_f32 v[16:17], v[90:91], v[16:17]
	v_pk_mul_f32 v[18:19], v[92:93], v[18:19]
	v_pk_mul_f32 v[20:21], v[94:95], v[20:21]
	v_cvt_pk_bf16_f32 v240, v6, v7
	v_cvt_pk_bf16_f32 v241, v8, v9
	v_cvt_pk_bf16_f32 v242, v10, v11
	v_cvt_pk_bf16_f32 v243, v12, v13
	v_cvt_pk_bf16_f32 v244, v14, v15
	v_cvt_pk_bf16_f32 v245, v16, v17
	v_cvt_pk_bf16_f32 v246, v18, v19
	v_cvt_pk_bf16_f32 v247, v20, v21
	global_store_dwordx2 v2, v[240:241], s[40:41] offset:0
	global_store_dwordx2 v2, v[242:243], s[40:41] offset:512
	global_store_dwordx2 v2, v[244:245], s[40:41] offset:1024
	global_store_dwordx2 v2, v[246:247], s[40:41] offset:1536
	ds_read_b128 v[26:29], v5 offset:0
	ds_read_b128 v[30:33], v5 offset:1024
	ds_read_b128 v[34:37], v5 offset:2048
	ds_read_b128 v[38:41], v5 offset:3072
	ds_read_b128 v[42:45], v5 offset:4096
	ds_read_b128 v[46:49], v5 offset:5120
	ds_read_b128 v[50:53], v5 offset:6144
	ds_read_b128 v[54:57], v5 offset:7168
	ds_read_b128 v[58:61], v5 offset:8192
	ds_read_b128 v[62:65], v5 offset:9216
	ds_read_b128 v[66:69], v5 offset:10240
	ds_read_b128 v[70:73], v5 offset:11264
	s_waitcnt lgkmcnt(8)
	v_pk_fma_f32 v[28:29], v[8:9], v[28:29], 0 op_sel_hi:[1,1,0]
	v_pk_fma_f32 v[26:27], v[6:7], v[26:27], 0 op_sel_hi:[1,1,0]
	v_pk_fma_f32 v[28:29], v[12:13], v[32:33], v[28:29]
	v_pk_fma_f32 v[26:27], v[10:11], v[30:31], v[26:27]
	v_pk_fma_f32 v[28:29], v[16:17], v[36:37], v[28:29]
	v_pk_fma_f32 v[26:27], v[14:15], v[34:35], v[26:27]
	v_pk_fma_f32 v[28:29], v[20:21], v[40:41], v[28:29]
	v_pk_fma_f32 v[26:27], v[18:19], v[38:39], v[26:27]
	s_waitcnt lgkmcnt(4)
	v_pk_fma_f32 v[44:45], v[8:9], v[44:45], 0 op_sel_hi:[1,1,0]
	v_pk_fma_f32 v[42:43], v[6:7], v[42:43], 0 op_sel_hi:[1,1,0]
	v_pk_fma_f32 v[44:45], v[12:13], v[48:49], v[44:45]
	v_pk_fma_f32 v[42:43], v[10:11], v[46:47], v[42:43]
	v_pk_fma_f32 v[44:45], v[16:17], v[52:53], v[44:45]
	v_pk_fma_f32 v[42:43], v[14:15], v[50:51], v[42:43]
	v_pk_fma_f32 v[44:45], v[20:21], v[56:57], v[44:45]
	v_pk_fma_f32 v[42:43], v[18:19], v[54:55], v[42:43]
	s_waitcnt lgkmcnt(0)
	v_pk_fma_f32 v[60:61], v[8:9], v[60:61], 0 op_sel_hi:[1,1,0]
	v_pk_fma_f32 v[58:59], v[6:7], v[58:59], 0 op_sel_hi:[1,1,0]
	v_pk_fma_f32 v[60:61], v[12:13], v[64:65], v[60:61]
	v_pk_fma_f32 v[58:59], v[10:11], v[62:63], v[58:59]
	v_pk_fma_f32 v[60:61], v[16:17], v[68:69], v[60:61]
	v_pk_fma_f32 v[58:59], v[14:15], v[66:67], v[58:59]
	v_pk_fma_f32 v[60:61], v[20:21], v[72:73], v[60:61]
	v_pk_fma_f32 v[58:59], v[18:19], v[70:71], v[58:59]
	v_add_f32_e32 v30, v28, v29
	v_add_f32_e32 v46, v44, v45
	v_add_f32_e32 v62, v60, v61
	v_add_f32_e32 v26, v26, v27
	v_add_f32_e32 v42, v42, v43
	v_add_f32_e32 v58, v58, v59
	v_mov_b32_e32 v31, 0
	v_mov_b32_e32 v47, 0
	v_mov_b32_e32 v63, 0
	v_add_f32_e32 v26, v26, v30
	v_add_f32_e32 v42, v42, v46
	v_add_f32_e32 v58, v58, v62
	v_mov_b32_e32 v32, 0
	v_mov_b32_e32 v48, 0
	v_mov_b32_e32 v64, 0
	v_add_f32_dpp v26, v26, v26 quad_perm:[1,0,3,2] row_mask:0xf bank_mask:0xf bound_ctrl:1
	v_add_f32_dpp v42, v42, v42 quad_perm:[1,0,3,2] row_mask:0xf bank_mask:0xf bound_ctrl:1
	v_add_f32_dpp v58, v58, v58 quad_perm:[1,0,3,2] row_mask:0xf bank_mask:0xf bound_ctrl:1
	v_add_f32_dpp v26, v26, v26 quad_perm:[2,3,0,1] row_mask:0xf bank_mask:0xf bound_ctrl:1
	v_add_f32_dpp v42, v42, v42 quad_perm:[2,3,0,1] row_mask:0xf bank_mask:0xf bound_ctrl:1
	v_add_f32_dpp v58, v58, v58 quad_perm:[2,3,0,1] row_mask:0xf bank_mask:0xf bound_ctrl:1
	v_add_f32_dpp v26, v26, v26 row_half_mirror row_mask:0xf bank_mask:0xf bound_ctrl:1
	v_add_f32_dpp v42, v42, v42 row_half_mirror row_mask:0xf bank_mask:0xf bound_ctrl:1
	v_add_f32_dpp v58, v58, v58 row_half_mirror row_mask:0xf bank_mask:0xf bound_ctrl:1
	v_add_f32_dpp v26, v26, v26 row_mirror row_mask:0xf bank_mask:0xf bound_ctrl:1
	v_add_f32_dpp v42, v42, v42 row_mirror row_mask:0xf bank_mask:0xf bound_ctrl:1
	v_add_f32_dpp v58, v58, v58 row_mirror row_mask:0xf bank_mask:0xf bound_ctrl:1
	v_mov_b32_dpp v31, v26 row_bcast:15 row_mask:0xa bank_mask:0xf
	v_mov_b32_dpp v47, v42 row_bcast:15 row_mask:0xa bank_mask:0xf
	v_mov_b32_dpp v63, v58 row_bcast:15 row_mask:0xa bank_mask:0xf
	v_add_f32_e32 v26, v26, v31
	v_add_f32_e32 v42, v42, v47
	v_add_f32_e32 v58, v58, v63
	v_mov_b32_dpp v32, v26 row_bcast:31 row_mask:0xc bank_mask:0xf
	v_mov_b32_dpp v48, v42 row_bcast:31 row_mask:0xc bank_mask:0xf
	v_mov_b32_dpp v64, v58 row_bcast:31 row_mask:0xc bank_mask:0xf
	v_add_f32_e32 v26, v26, v32
	v_add_f32_e32 v42, v42, v48
	v_add_f32_e32 v58, v58, v64
	s_nop 0
	v_readlane_b32 s16, v26, 63
	v_readlane_b32 s17, v42, 63
	v_readlane_b32 s18, v58, 63
	v_writelane_b32 v1, s16, 0
	v_writelane_b32 v1, s17, 1
	v_writelane_b32 v1, s18, 2
	ds_read_b128 v[26:29], v5 offset:12288
	ds_read_b128 v[30:33], v5 offset:13312
	ds_read_b128 v[34:37], v5 offset:14336
	ds_read_b128 v[38:41], v5 offset:15360
	ds_read_b128 v[42:45], v5 offset:16384
	ds_read_b128 v[46:49], v5 offset:17408
	ds_read_b128 v[50:53], v5 offset:18432
	ds_read_b128 v[54:57], v5 offset:19456
	ds_read_b128 v[58:61], v5 offset:20480
	ds_read_b128 v[62:65], v5 offset:21504
	ds_read_b128 v[66:69], v5 offset:22528
	ds_read_b128 v[70:73], v5 offset:23552
	s_waitcnt lgkmcnt(8)
	v_pk_fma_f32 v[28:29], v[8:9], v[28:29], 0 op_sel_hi:[1,1,0]
	v_pk_fma_f32 v[26:27], v[6:7], v[26:27], 0 op_sel_hi:[1,1,0]
	v_pk_fma_f32 v[28:29], v[12:13], v[32:33], v[28:29]
	v_pk_fma_f32 v[26:27], v[10:11], v[30:31], v[26:27]
	v_pk_fma_f32 v[28:29], v[16:17], v[36:37], v[28:29]
	v_pk_fma_f32 v[26:27], v[14:15], v[34:35], v[26:27]
	v_pk_fma_f32 v[28:29], v[20:21], v[40:41], v[28:29]
	v_pk_fma_f32 v[26:27], v[18:19], v[38:39], v[26:27]
	s_waitcnt lgkmcnt(4)
	v_pk_fma_f32 v[44:45], v[8:9], v[44:45], 0 op_sel_hi:[1,1,0]
	v_pk_fma_f32 v[42:43], v[6:7], v[42:43], 0 op_sel_hi:[1,1,0]
	v_pk_fma_f32 v[44:45], v[12:13], v[48:49], v[44:45]
	v_pk_fma_f32 v[42:43], v[10:11], v[46:47], v[42:43]
	v_pk_fma_f32 v[44:45], v[16:17], v[52:53], v[44:45]
	v_pk_fma_f32 v[42:43], v[14:15], v[50:51], v[42:43]
	v_pk_fma_f32 v[44:45], v[20:21], v[56:57], v[44:45]
	v_pk_fma_f32 v[42:43], v[18:19], v[54:55], v[42:43]
	s_waitcnt lgkmcnt(0)
	v_pk_fma_f32 v[60:61], v[8:9], v[60:61], 0 op_sel_hi:[1,1,0]
	v_pk_fma_f32 v[58:59], v[6:7], v[58:59], 0 op_sel_hi:[1,1,0]
	v_pk_fma_f32 v[60:61], v[12:13], v[64:65], v[60:61]
	v_pk_fma_f32 v[58:59], v[10:11], v[62:63], v[58:59]
	v_pk_fma_f32 v[60:61], v[16:17], v[68:69], v[60:61]
	v_pk_fma_f32 v[58:59], v[14:15], v[66:67], v[58:59]
	v_pk_fma_f32 v[60:61], v[20:21], v[72:73], v[60:61]
	v_pk_fma_f32 v[58:59], v[18:19], v[70:71], v[58:59]
	v_add_f32_e32 v30, v28, v29
	v_add_f32_e32 v46, v44, v45
	v_add_f32_e32 v62, v60, v61
	v_add_f32_e32 v26, v26, v27
	v_add_f32_e32 v42, v42, v43
	v_add_f32_e32 v58, v58, v59
	v_mov_b32_e32 v31, 0
	v_mov_b32_e32 v47, 0
	v_mov_b32_e32 v63, 0
	v_add_f32_e32 v26, v26, v30
	v_add_f32_e32 v42, v42, v46
	v_add_f32_e32 v58, v58, v62
	v_mov_b32_e32 v32, 0
	v_mov_b32_e32 v48, 0
	v_mov_b32_e32 v64, 0
	v_add_f32_dpp v26, v26, v26 quad_perm:[1,0,3,2] row_mask:0xf bank_mask:0xf bound_ctrl:1
	v_add_f32_dpp v42, v42, v42 quad_perm:[1,0,3,2] row_mask:0xf bank_mask:0xf bound_ctrl:1
	v_add_f32_dpp v58, v58, v58 quad_perm:[1,0,3,2] row_mask:0xf bank_mask:0xf bound_ctrl:1
	v_add_f32_dpp v26, v26, v26 quad_perm:[2,3,0,1] row_mask:0xf bank_mask:0xf bound_ctrl:1
	v_add_f32_dpp v42, v42, v42 quad_perm:[2,3,0,1] row_mask:0xf bank_mask:0xf bound_ctrl:1
	v_add_f32_dpp v58, v58, v58 quad_perm:[2,3,0,1] row_mask:0xf bank_mask:0xf bound_ctrl:1
	v_add_f32_dpp v26, v26, v26 row_half_mirror row_mask:0xf bank_mask:0xf bound_ctrl:1
	v_add_f32_dpp v42, v42, v42 row_half_mirror row_mask:0xf bank_mask:0xf bound_ctrl:1
	v_add_f32_dpp v58, v58, v58 row_half_mirror row_mask:0xf bank_mask:0xf bound_ctrl:1
	v_add_f32_dpp v26, v26, v26 row_mirror row_mask:0xf bank_mask:0xf bound_ctrl:1
	v_add_f32_dpp v42, v42, v42 row_mirror row_mask:0xf bank_mask:0xf bound_ctrl:1
	v_add_f32_dpp v58, v58, v58 row_mirror row_mask:0xf bank_mask:0xf bound_ctrl:1
	v_mov_b32_dpp v31, v26 row_bcast:15 row_mask:0xa bank_mask:0xf
	v_mov_b32_dpp v47, v42 row_bcast:15 row_mask:0xa bank_mask:0xf
	v_mov_b32_dpp v63, v58 row_bcast:15 row_mask:0xa bank_mask:0xf
	v_add_f32_e32 v26, v26, v31
	v_add_f32_e32 v42, v42, v47
	v_add_f32_e32 v58, v58, v63
	v_mov_b32_dpp v32, v26 row_bcast:31 row_mask:0xc bank_mask:0xf
	v_mov_b32_dpp v48, v42 row_bcast:31 row_mask:0xc bank_mask:0xf
	v_mov_b32_dpp v64, v58 row_bcast:31 row_mask:0xc bank_mask:0xf
	v_add_f32_e32 v26, v26, v32
	v_add_f32_e32 v42, v42, v48
	v_add_f32_e32 v58, v58, v64
	s_nop 0
	v_readlane_b32 s16, v26, 63
	v_readlane_b32 s17, v42, 63
	v_readlane_b32 s18, v58, 63
	v_writelane_b32 v1, s16, 3
	v_writelane_b32 v1, s17, 4
	v_writelane_b32 v1, s18, 5
	ds_read_b128 v[26:29], v5 offset:24576
	ds_read_b128 v[30:33], v5 offset:25600
	ds_read_b128 v[34:37], v5 offset:26624
	ds_read_b128 v[38:41], v5 offset:27648
	ds_read_b128 v[42:45], v5 offset:28672
	ds_read_b128 v[46:49], v5 offset:29696
	ds_read_b128 v[50:53], v5 offset:30720
	ds_read_b128 v[54:57], v5 offset:31744
	ds_read_b128 v[58:61], v5 offset:32768
	ds_read_b128 v[62:65], v5 offset:33792
	ds_read_b128 v[66:69], v5 offset:34816
	ds_read_b128 v[70:73], v5 offset:35840
	s_waitcnt lgkmcnt(8)
	v_pk_fma_f32 v[28:29], v[8:9], v[28:29], 0 op_sel_hi:[1,1,0]
	v_pk_fma_f32 v[26:27], v[6:7], v[26:27], 0 op_sel_hi:[1,1,0]
	v_pk_fma_f32 v[28:29], v[12:13], v[32:33], v[28:29]
	v_pk_fma_f32 v[26:27], v[10:11], v[30:31], v[26:27]
	v_pk_fma_f32 v[28:29], v[16:17], v[36:37], v[28:29]
	v_pk_fma_f32 v[26:27], v[14:15], v[34:35], v[26:27]
	v_pk_fma_f32 v[28:29], v[20:21], v[40:41], v[28:29]
	v_pk_fma_f32 v[26:27], v[18:19], v[38:39], v[26:27]
	s_waitcnt lgkmcnt(4)
	v_pk_fma_f32 v[44:45], v[8:9], v[44:45], 0 op_sel_hi:[1,1,0]
	v_pk_fma_f32 v[42:43], v[6:7], v[42:43], 0 op_sel_hi:[1,1,0]
	v_pk_fma_f32 v[44:45], v[12:13], v[48:49], v[44:45]
	v_pk_fma_f32 v[42:43], v[10:11], v[46:47], v[42:43]
	v_pk_fma_f32 v[44:45], v[16:17], v[52:53], v[44:45]
	v_pk_fma_f32 v[42:43], v[14:15], v[50:51], v[42:43]
	v_pk_fma_f32 v[44:45], v[20:21], v[56:57], v[44:45]
	v_pk_fma_f32 v[42:43], v[18:19], v[54:55], v[42:43]
	s_waitcnt lgkmcnt(0)
	v_pk_fma_f32 v[60:61], v[8:9], v[60:61], 0 op_sel_hi:[1,1,0]
	v_pk_fma_f32 v[58:59], v[6:7], v[58:59], 0 op_sel_hi:[1,1,0]
	v_pk_fma_f32 v[60:61], v[12:13], v[64:65], v[60:61]
	v_pk_fma_f32 v[58:59], v[10:11], v[62:63], v[58:59]
	v_pk_fma_f32 v[60:61], v[16:17], v[68:69], v[60:61]
	v_pk_fma_f32 v[58:59], v[14:15], v[66:67], v[58:59]
	v_pk_fma_f32 v[60:61], v[20:21], v[72:73], v[60:61]
	v_pk_fma_f32 v[58:59], v[18:19], v[70:71], v[58:59]
	v_add_f32_e32 v30, v28, v29
	v_add_f32_e32 v46, v44, v45
	v_add_f32_e32 v62, v60, v61
	v_add_f32_e32 v26, v26, v27
	v_add_f32_e32 v42, v42, v43
	v_add_f32_e32 v58, v58, v59
	v_mov_b32_e32 v31, 0
	v_mov_b32_e32 v47, 0
	v_mov_b32_e32 v63, 0
	v_add_f32_e32 v26, v26, v30
	v_add_f32_e32 v42, v42, v46
	v_add_f32_e32 v58, v58, v62
	v_mov_b32_e32 v32, 0
	v_mov_b32_e32 v48, 0
	v_mov_b32_e32 v64, 0
	v_add_f32_dpp v26, v26, v26 quad_perm:[1,0,3,2] row_mask:0xf bank_mask:0xf bound_ctrl:1
	v_add_f32_dpp v42, v42, v42 quad_perm:[1,0,3,2] row_mask:0xf bank_mask:0xf bound_ctrl:1
	v_add_f32_dpp v58, v58, v58 quad_perm:[1,0,3,2] row_mask:0xf bank_mask:0xf bound_ctrl:1
	v_add_f32_dpp v26, v26, v26 quad_perm:[2,3,0,1] row_mask:0xf bank_mask:0xf bound_ctrl:1
	v_add_f32_dpp v42, v42, v42 quad_perm:[2,3,0,1] row_mask:0xf bank_mask:0xf bound_ctrl:1
	v_add_f32_dpp v58, v58, v58 quad_perm:[2,3,0,1] row_mask:0xf bank_mask:0xf bound_ctrl:1
	v_add_f32_dpp v26, v26, v26 row_half_mirror row_mask:0xf bank_mask:0xf bound_ctrl:1
	v_add_f32_dpp v42, v42, v42 row_half_mirror row_mask:0xf bank_mask:0xf bound_ctrl:1
	v_add_f32_dpp v58, v58, v58 row_half_mirror row_mask:0xf bank_mask:0xf bound_ctrl:1
	v_add_f32_dpp v26, v26, v26 row_mirror row_mask:0xf bank_mask:0xf bound_ctrl:1
	v_add_f32_dpp v42, v42, v42 row_mirror row_mask:0xf bank_mask:0xf bound_ctrl:1
	v_add_f32_dpp v58, v58, v58 row_mirror row_mask:0xf bank_mask:0xf bound_ctrl:1
	v_mov_b32_dpp v31, v26 row_bcast:15 row_mask:0xa bank_mask:0xf
	v_mov_b32_dpp v47, v42 row_bcast:15 row_mask:0xa bank_mask:0xf
	v_mov_b32_dpp v63, v58 row_bcast:15 row_mask:0xa bank_mask:0xf
	v_add_f32_e32 v26, v26, v31
	v_add_f32_e32 v42, v42, v47
	v_add_f32_e32 v58, v58, v63
	v_mov_b32_dpp v32, v26 row_bcast:31 row_mask:0xc bank_mask:0xf
	v_mov_b32_dpp v48, v42 row_bcast:31 row_mask:0xc bank_mask:0xf
	v_mov_b32_dpp v64, v58 row_bcast:31 row_mask:0xc bank_mask:0xf
	v_add_f32_e32 v26, v26, v32
	v_add_f32_e32 v42, v42, v48
	v_add_f32_e32 v58, v58, v64
	s_nop 0
	v_readlane_b32 s16, v26, 63
	v_readlane_b32 s17, v42, 63
	v_readlane_b32 s18, v58, 63
	v_writelane_b32 v1, s16, 6
	v_writelane_b32 v1, s17, 7
	v_writelane_b32 v1, s18, 8
	ds_read_b128 v[26:29], v5 offset:36864
	ds_read_b128 v[30:33], v5 offset:37888
	ds_read_b128 v[34:37], v5 offset:38912
	ds_read_b128 v[38:41], v5 offset:39936
	ds_read_b128 v[42:45], v5 offset:40960
	ds_read_b128 v[46:49], v5 offset:41984
	ds_read_b128 v[50:53], v5 offset:43008
	ds_read_b128 v[54:57], v5 offset:44032
	ds_read_b128 v[58:61], v5 offset:45056
	ds_read_b128 v[62:65], v5 offset:46080
	ds_read_b128 v[66:69], v5 offset:47104
	ds_read_b128 v[70:73], v5 offset:48128
	s_waitcnt lgkmcnt(8)
	v_pk_fma_f32 v[28:29], v[8:9], v[28:29], 0 op_sel_hi:[1,1,0]
	v_pk_fma_f32 v[26:27], v[6:7], v[26:27], 0 op_sel_hi:[1,1,0]
	v_pk_fma_f32 v[28:29], v[12:13], v[32:33], v[28:29]
	v_pk_fma_f32 v[26:27], v[10:11], v[30:31], v[26:27]
	v_pk_fma_f32 v[28:29], v[16:17], v[36:37], v[28:29]
	v_pk_fma_f32 v[26:27], v[14:15], v[34:35], v[26:27]
	v_pk_fma_f32 v[28:29], v[20:21], v[40:41], v[28:29]
	v_pk_fma_f32 v[26:27], v[18:19], v[38:39], v[26:27]
	s_waitcnt lgkmcnt(4)
	v_pk_fma_f32 v[44:45], v[8:9], v[44:45], 0 op_sel_hi:[1,1,0]
	v_pk_fma_f32 v[42:43], v[6:7], v[42:43], 0 op_sel_hi:[1,1,0]
	v_pk_fma_f32 v[44:45], v[12:13], v[48:49], v[44:45]
	v_pk_fma_f32 v[42:43], v[10:11], v[46:47], v[42:43]
	v_pk_fma_f32 v[44:45], v[16:17], v[52:53], v[44:45]
	v_pk_fma_f32 v[42:43], v[14:15], v[50:51], v[42:43]
	v_pk_fma_f32 v[44:45], v[20:21], v[56:57], v[44:45]
	v_pk_fma_f32 v[42:43], v[18:19], v[54:55], v[42:43]
	s_waitcnt lgkmcnt(0)
	v_pk_fma_f32 v[60:61], v[8:9], v[60:61], 0 op_sel_hi:[1,1,0]
	v_pk_fma_f32 v[58:59], v[6:7], v[58:59], 0 op_sel_hi:[1,1,0]
	v_pk_fma_f32 v[60:61], v[12:13], v[64:65], v[60:61]
	v_pk_fma_f32 v[58:59], v[10:11], v[62:63], v[58:59]
	v_pk_fma_f32 v[60:61], v[16:17], v[68:69], v[60:61]
	v_pk_fma_f32 v[58:59], v[14:15], v[66:67], v[58:59]
	v_pk_fma_f32 v[60:61], v[20:21], v[72:73], v[60:61]
	v_pk_fma_f32 v[58:59], v[18:19], v[70:71], v[58:59]
	v_add_f32_e32 v30, v28, v29
	v_add_f32_e32 v46, v44, v45
	v_add_f32_e32 v62, v60, v61
	v_add_f32_e32 v26, v26, v27
	v_add_f32_e32 v42, v42, v43
	v_add_f32_e32 v58, v58, v59
	v_mov_b32_e32 v31, 0
	v_mov_b32_e32 v47, 0
	v_mov_b32_e32 v63, 0
	v_add_f32_e32 v26, v26, v30
	v_add_f32_e32 v42, v42, v46
	v_add_f32_e32 v58, v58, v62
	v_mov_b32_e32 v32, 0
	v_mov_b32_e32 v48, 0
	v_mov_b32_e32 v64, 0
	v_add_f32_dpp v26, v26, v26 quad_perm:[1,0,3,2] row_mask:0xf bank_mask:0xf bound_ctrl:1
	v_add_f32_dpp v42, v42, v42 quad_perm:[1,0,3,2] row_mask:0xf bank_mask:0xf bound_ctrl:1
	v_add_f32_dpp v58, v58, v58 quad_perm:[1,0,3,2] row_mask:0xf bank_mask:0xf bound_ctrl:1
	v_add_f32_dpp v26, v26, v26 quad_perm:[2,3,0,1] row_mask:0xf bank_mask:0xf bound_ctrl:1
	v_add_f32_dpp v42, v42, v42 quad_perm:[2,3,0,1] row_mask:0xf bank_mask:0xf bound_ctrl:1
	v_add_f32_dpp v58, v58, v58 quad_perm:[2,3,0,1] row_mask:0xf bank_mask:0xf bound_ctrl:1
	v_add_f32_dpp v26, v26, v26 row_half_mirror row_mask:0xf bank_mask:0xf bound_ctrl:1
	v_add_f32_dpp v42, v42, v42 row_half_mirror row_mask:0xf bank_mask:0xf bound_ctrl:1
	v_add_f32_dpp v58, v58, v58 row_half_mirror row_mask:0xf bank_mask:0xf bound_ctrl:1
	v_add_f32_dpp v26, v26, v26 row_mirror row_mask:0xf bank_mask:0xf bound_ctrl:1
	v_add_f32_dpp v42, v42, v42 row_mirror row_mask:0xf bank_mask:0xf bound_ctrl:1
	v_add_f32_dpp v58, v58, v58 row_mirror row_mask:0xf bank_mask:0xf bound_ctrl:1
	v_mov_b32_dpp v31, v26 row_bcast:15 row_mask:0xa bank_mask:0xf
	v_mov_b32_dpp v47, v42 row_bcast:15 row_mask:0xa bank_mask:0xf
	v_mov_b32_dpp v63, v58 row_bcast:15 row_mask:0xa bank_mask:0xf
	v_add_f32_e32 v26, v26, v31
	v_add_f32_e32 v42, v42, v47
	v_add_f32_e32 v58, v58, v63
	v_mov_b32_dpp v32, v26 row_bcast:31 row_mask:0xc bank_mask:0xf
	v_mov_b32_dpp v48, v42 row_bcast:31 row_mask:0xc bank_mask:0xf
	v_mov_b32_dpp v64, v58 row_bcast:31 row_mask:0xc bank_mask:0xf
	v_add_f32_e32 v26, v26, v32
	v_add_f32_e32 v42, v42, v48
	v_add_f32_e32 v58, v58, v64
	s_nop 0
	v_readlane_b32 s16, v26, 63
	v_readlane_b32 s17, v42, 63
	v_readlane_b32 s18, v58, 63
	v_writelane_b32 v1, s16, 9
	v_writelane_b32 v1, s17, 10
	v_writelane_b32 v1, s18, 11
	s_mov_b64 s[26:27], exec
	s_mov_b32 exec_lo, 0xfff
	s_mov_b32 exec_hi, 0
	global_store_dword v25, v1, s[42:43]
	s_mov_b64 exec, s[26:27]
	s_add_u32 s40, s40, 0x400000
	s_addc_u32 s41, s41, 0
	s_add_u32 s42, s42, 0x20000
	s_addc_u32 s43, s43, 0
	s_waitcnt vmcnt(38)
	v_pk_mul_f32 v[50:51], v[194:195], v[194:195]
	v_pk_mul_f32 v[52:53], v[192:193], v[192:193]
	v_pk_mul_f32 v[54:55], v[198:199], v[198:199]
	v_pk_mul_f32 v[56:57], v[196:197], v[196:197]
	v_mul_f32_e32 v58, v201, v201
	v_mul_f32_e32 v60, v203, v203
	v_pk_mul_f32 v[64:65], v[204:205], v[204:205]
	v_pk_mul_f32 v[66:67], v[206:207], v[206:207]
	v_add_f32_e32 v52, v53, v52
	v_add_f32_e32 v50, v50, v51
	v_add_f32_e32 v56, v57, v56
	v_add_f32_e32 v54, v54, v55
	v_fma_f32 v58, v200, v200, v58
	v_fma_f32 v60, v202, v202, v60
	v_add_f32_e32 v64, v64, v65
	v_add_f32_e32 v66, v66, v67
	v_add_f32_e32 v52, v52, v50
	v_add_f32_e32 v56, v56, v54
	v_add_f32_e32 v58, v58, v60
	v_add_f32_e32 v64, v64, v66
	v_add_f32_e32 v50, v52, v56
	v_mov_b32_e32 v61, 0
	v_mov_b32_e32 v62, 0
	v_add_f32_e32 v50, v50, v58
	s_nop 0
	v_add_f32_e32 v50, v50, v64
	s_nop 1
	v_add_f32_dpp v50, v50, v50 quad_perm:[1,0,3,2] row_mask:0xf bank_mask:0xf bound_ctrl:1
	s_nop 1
	v_add_f32_dpp v50, v50, v50 quad_perm:[2,3,0,1] row_mask:0xf bank_mask:0xf bound_ctrl:1
	s_nop 1
	v_add_f32_dpp v50, v50, v50 row_half_mirror row_mask:0xf bank_mask:0xf bound_ctrl:1
	s_nop 1
	v_add_f32_dpp v50, v50, v50 row_mirror row_mask:0xf bank_mask:0xf bound_ctrl:1
	s_nop 1
	v_mov_b32_dpp v61, v50 row_bcast:15 row_mask:0xa bank_mask:0xf
	s_nop 1
	v_add_f32_e32 v50, v50, v61
	s_nop 1
	v_mov_b32_dpp v62, v50 row_bcast:31 row_mask:0xc bank_mask:0xf
	s_nop 1
	v_add_f32_e32 v50, v50, v62
	s_nop 0
	v_readlane_b32 s15, v50, 63
	s_nop 1
	v_fma_f32 v50, s15, v24, v23
	v_mul_f32_e32 v51, 0x4b800000, v50
	v_cmp_gt_f32_e32 vcc, s5, v50
	s_nop 1
	v_cndmask_b32_e32 v50, v50, v51, vcc
	v_rsq_f32_e32 v52, v50
	s_nop 0
	v_mul_f32_e32 v53, 0x45800000, v52
	v_cndmask_b32_e32 v52, v52, v53, vcc
	v_pk_mul_f32 v[6:7], v[192:193], v[52:53] op_sel_hi:[1,0]
	v_pk_mul_f32 v[8:9], v[194:195], v[52:53] op_sel_hi:[1,0]
	v_pk_mul_f32 v[10:11], v[196:197], v[52:53] op_sel_hi:[1,0]
	v_pk_mul_f32 v[12:13], v[198:199], v[52:53] op_sel_hi:[1,0]
	v_pk_mul_f32 v[14:15], v[200:201], v[52:53] op_sel_hi:[1,0]
	v_pk_mul_f32 v[16:17], v[202:203], v[52:53] op_sel_hi:[1,0]
	v_pk_mul_f32 v[18:19], v[204:205], v[52:53] op_sel_hi:[1,0]
	v_pk_mul_f32 v[20:21], v[206:207], v[52:53] op_sel_hi:[1,0]
	v_pk_mul_f32 v[6:7], v[80:81], v[6:7]
	v_pk_mul_f32 v[8:9], v[82:83], v[8:9]
	v_pk_mul_f32 v[10:11], v[84:85], v[10:11]
	v_pk_mul_f32 v[12:13], v[86:87], v[12:13]
	v_pk_mul_f32 v[14:15], v[88:89], v[14:15]
	v_pk_mul_f32 v[16:17], v[90:91], v[16:17]
	v_pk_mul_f32 v[18:19], v[92:93], v[18:19]
	v_pk_mul_f32 v[20:21], v[94:95], v[20:21]
	v_cvt_pk_bf16_f32 v240, v6, v7
	v_cvt_pk_bf16_f32 v241, v8, v9
	v_cvt_pk_bf16_f32 v242, v10, v11
	v_cvt_pk_bf16_f32 v243, v12, v13
	v_cvt_pk_bf16_f32 v244, v14, v15
	v_cvt_pk_bf16_f32 v245, v16, v17
	v_cvt_pk_bf16_f32 v246, v18, v19
	v_cvt_pk_bf16_f32 v247, v20, v21
	global_store_dwordx2 v2, v[240:241], s[40:41] offset:0
	global_store_dwordx2 v2, v[242:243], s[40:41] offset:512
	global_store_dwordx2 v2, v[244:245], s[40:41] offset:1024
	global_store_dwordx2 v2, v[246:247], s[40:41] offset:1536
	ds_read_b128 v[26:29], v5 offset:0
	ds_read_b128 v[30:33], v5 offset:1024
	ds_read_b128 v[34:37], v5 offset:2048
	ds_read_b128 v[38:41], v5 offset:3072
	ds_read_b128 v[42:45], v5 offset:4096
	ds_read_b128 v[46:49], v5 offset:5120
	ds_read_b128 v[50:53], v5 offset:6144
	ds_read_b128 v[54:57], v5 offset:7168
	ds_read_b128 v[58:61], v5 offset:8192
	ds_read_b128 v[62:65], v5 offset:9216
	ds_read_b128 v[66:69], v5 offset:10240
	ds_read_b128 v[70:73], v5 offset:11264
	s_waitcnt lgkmcnt(8)
	v_pk_fma_f32 v[28:29], v[8:9], v[28:29], 0 op_sel_hi:[1,1,0]
	v_pk_fma_f32 v[26:27], v[6:7], v[26:27], 0 op_sel_hi:[1,1,0]
	v_pk_fma_f32 v[28:29], v[12:13], v[32:33], v[28:29]
	v_pk_fma_f32 v[26:27], v[10:11], v[30:31], v[26:27]
	v_pk_fma_f32 v[28:29], v[16:17], v[36:37], v[28:29]
	v_pk_fma_f32 v[26:27], v[14:15], v[34:35], v[26:27]
	v_pk_fma_f32 v[28:29], v[20:21], v[40:41], v[28:29]
	v_pk_fma_f32 v[26:27], v[18:19], v[38:39], v[26:27]
	s_waitcnt lgkmcnt(4)
	v_pk_fma_f32 v[44:45], v[8:9], v[44:45], 0 op_sel_hi:[1,1,0]
	v_pk_fma_f32 v[42:43], v[6:7], v[42:43], 0 op_sel_hi:[1,1,0]
	v_pk_fma_f32 v[44:45], v[12:13], v[48:49], v[44:45]
	v_pk_fma_f32 v[42:43], v[10:11], v[46:47], v[42:43]
	v_pk_fma_f32 v[44:45], v[16:17], v[52:53], v[44:45]
	v_pk_fma_f32 v[42:43], v[14:15], v[50:51], v[42:43]
	v_pk_fma_f32 v[44:45], v[20:21], v[56:57], v[44:45]
	v_pk_fma_f32 v[42:43], v[18:19], v[54:55], v[42:43]
	s_waitcnt lgkmcnt(0)
	v_pk_fma_f32 v[60:61], v[8:9], v[60:61], 0 op_sel_hi:[1,1,0]
	v_pk_fma_f32 v[58:59], v[6:7], v[58:59], 0 op_sel_hi:[1,1,0]
	v_pk_fma_f32 v[60:61], v[12:13], v[64:65], v[60:61]
	v_pk_fma_f32 v[58:59], v[10:11], v[62:63], v[58:59]
	v_pk_fma_f32 v[60:61], v[16:17], v[68:69], v[60:61]
	v_pk_fma_f32 v[58:59], v[14:15], v[66:67], v[58:59]
	v_pk_fma_f32 v[60:61], v[20:21], v[72:73], v[60:61]
	v_pk_fma_f32 v[58:59], v[18:19], v[70:71], v[58:59]
	v_add_f32_e32 v30, v28, v29
	v_add_f32_e32 v46, v44, v45
	v_add_f32_e32 v62, v60, v61
	v_add_f32_e32 v26, v26, v27
	v_add_f32_e32 v42, v42, v43
	v_add_f32_e32 v58, v58, v59
	v_mov_b32_e32 v31, 0
	v_mov_b32_e32 v47, 0
	v_mov_b32_e32 v63, 0
	v_add_f32_e32 v26, v26, v30
	v_add_f32_e32 v42, v42, v46
	v_add_f32_e32 v58, v58, v62
	v_mov_b32_e32 v32, 0
	v_mov_b32_e32 v48, 0
	v_mov_b32_e32 v64, 0
	v_add_f32_dpp v26, v26, v26 quad_perm:[1,0,3,2] row_mask:0xf bank_mask:0xf bound_ctrl:1
	v_add_f32_dpp v42, v42, v42 quad_perm:[1,0,3,2] row_mask:0xf bank_mask:0xf bound_ctrl:1
	v_add_f32_dpp v58, v58, v58 quad_perm:[1,0,3,2] row_mask:0xf bank_mask:0xf bound_ctrl:1
	v_add_f32_dpp v26, v26, v26 quad_perm:[2,3,0,1] row_mask:0xf bank_mask:0xf bound_ctrl:1
	v_add_f32_dpp v42, v42, v42 quad_perm:[2,3,0,1] row_mask:0xf bank_mask:0xf bound_ctrl:1
	v_add_f32_dpp v58, v58, v58 quad_perm:[2,3,0,1] row_mask:0xf bank_mask:0xf bound_ctrl:1
	v_add_f32_dpp v26, v26, v26 row_half_mirror row_mask:0xf bank_mask:0xf bound_ctrl:1
	v_add_f32_dpp v42, v42, v42 row_half_mirror row_mask:0xf bank_mask:0xf bound_ctrl:1
	v_add_f32_dpp v58, v58, v58 row_half_mirror row_mask:0xf bank_mask:0xf bound_ctrl:1
	v_add_f32_dpp v26, v26, v26 row_mirror row_mask:0xf bank_mask:0xf bound_ctrl:1
	v_add_f32_dpp v42, v42, v42 row_mirror row_mask:0xf bank_mask:0xf bound_ctrl:1
	v_add_f32_dpp v58, v58, v58 row_mirror row_mask:0xf bank_mask:0xf bound_ctrl:1
	v_mov_b32_dpp v31, v26 row_bcast:15 row_mask:0xa bank_mask:0xf
	v_mov_b32_dpp v47, v42 row_bcast:15 row_mask:0xa bank_mask:0xf
	v_mov_b32_dpp v63, v58 row_bcast:15 row_mask:0xa bank_mask:0xf
	v_add_f32_e32 v26, v26, v31
	v_add_f32_e32 v42, v42, v47
	v_add_f32_e32 v58, v58, v63
	v_mov_b32_dpp v32, v26 row_bcast:31 row_mask:0xc bank_mask:0xf
	v_mov_b32_dpp v48, v42 row_bcast:31 row_mask:0xc bank_mask:0xf
	v_mov_b32_dpp v64, v58 row_bcast:31 row_mask:0xc bank_mask:0xf
	v_add_f32_e32 v26, v26, v32
	v_add_f32_e32 v42, v42, v48
	v_add_f32_e32 v58, v58, v64
	s_nop 0
	v_readlane_b32 s16, v26, 63
	v_readlane_b32 s17, v42, 63
	v_readlane_b32 s18, v58, 63
	v_writelane_b32 v1, s16, 0
	v_writelane_b32 v1, s17, 1
	v_writelane_b32 v1, s18, 2
	ds_read_b128 v[26:29], v5 offset:12288
	ds_read_b128 v[30:33], v5 offset:13312
	ds_read_b128 v[34:37], v5 offset:14336
	ds_read_b128 v[38:41], v5 offset:15360
	ds_read_b128 v[42:45], v5 offset:16384
	ds_read_b128 v[46:49], v5 offset:17408
	ds_read_b128 v[50:53], v5 offset:18432
	ds_read_b128 v[54:57], v5 offset:19456
	ds_read_b128 v[58:61], v5 offset:20480
	ds_read_b128 v[62:65], v5 offset:21504
	ds_read_b128 v[66:69], v5 offset:22528
	ds_read_b128 v[70:73], v5 offset:23552
	s_waitcnt lgkmcnt(8)
	v_pk_fma_f32 v[28:29], v[8:9], v[28:29], 0 op_sel_hi:[1,1,0]
	v_pk_fma_f32 v[26:27], v[6:7], v[26:27], 0 op_sel_hi:[1,1,0]
	v_pk_fma_f32 v[28:29], v[12:13], v[32:33], v[28:29]
	v_pk_fma_f32 v[26:27], v[10:11], v[30:31], v[26:27]
	v_pk_fma_f32 v[28:29], v[16:17], v[36:37], v[28:29]
	v_pk_fma_f32 v[26:27], v[14:15], v[34:35], v[26:27]
	v_pk_fma_f32 v[28:29], v[20:21], v[40:41], v[28:29]
	v_pk_fma_f32 v[26:27], v[18:19], v[38:39], v[26:27]
	s_waitcnt lgkmcnt(4)
	v_pk_fma_f32 v[44:45], v[8:9], v[44:45], 0 op_sel_hi:[1,1,0]
	v_pk_fma_f32 v[42:43], v[6:7], v[42:43], 0 op_sel_hi:[1,1,0]
	v_pk_fma_f32 v[44:45], v[12:13], v[48:49], v[44:45]
	v_pk_fma_f32 v[42:43], v[10:11], v[46:47], v[42:43]
	v_pk_fma_f32 v[44:45], v[16:17], v[52:53], v[44:45]
	v_pk_fma_f32 v[42:43], v[14:15], v[50:51], v[42:43]
	v_pk_fma_f32 v[44:45], v[20:21], v[56:57], v[44:45]
	v_pk_fma_f32 v[42:43], v[18:19], v[54:55], v[42:43]
	s_waitcnt lgkmcnt(0)
	v_pk_fma_f32 v[60:61], v[8:9], v[60:61], 0 op_sel_hi:[1,1,0]
	v_pk_fma_f32 v[58:59], v[6:7], v[58:59], 0 op_sel_hi:[1,1,0]
	v_pk_fma_f32 v[60:61], v[12:13], v[64:65], v[60:61]
	v_pk_fma_f32 v[58:59], v[10:11], v[62:63], v[58:59]
	v_pk_fma_f32 v[60:61], v[16:17], v[68:69], v[60:61]
	v_pk_fma_f32 v[58:59], v[14:15], v[66:67], v[58:59]
	v_pk_fma_f32 v[60:61], v[20:21], v[72:73], v[60:61]
	v_pk_fma_f32 v[58:59], v[18:19], v[70:71], v[58:59]
	v_add_f32_e32 v30, v28, v29
	v_add_f32_e32 v46, v44, v45
	v_add_f32_e32 v62, v60, v61
	v_add_f32_e32 v26, v26, v27
	v_add_f32_e32 v42, v42, v43
	v_add_f32_e32 v58, v58, v59
	v_mov_b32_e32 v31, 0
	v_mov_b32_e32 v47, 0
	v_mov_b32_e32 v63, 0
	v_add_f32_e32 v26, v26, v30
	v_add_f32_e32 v42, v42, v46
	v_add_f32_e32 v58, v58, v62
	v_mov_b32_e32 v32, 0
	v_mov_b32_e32 v48, 0
	v_mov_b32_e32 v64, 0
	v_add_f32_dpp v26, v26, v26 quad_perm:[1,0,3,2] row_mask:0xf bank_mask:0xf bound_ctrl:1
	v_add_f32_dpp v42, v42, v42 quad_perm:[1,0,3,2] row_mask:0xf bank_mask:0xf bound_ctrl:1
	v_add_f32_dpp v58, v58, v58 quad_perm:[1,0,3,2] row_mask:0xf bank_mask:0xf bound_ctrl:1
	v_add_f32_dpp v26, v26, v26 quad_perm:[2,3,0,1] row_mask:0xf bank_mask:0xf bound_ctrl:1
	v_add_f32_dpp v42, v42, v42 quad_perm:[2,3,0,1] row_mask:0xf bank_mask:0xf bound_ctrl:1
	v_add_f32_dpp v58, v58, v58 quad_perm:[2,3,0,1] row_mask:0xf bank_mask:0xf bound_ctrl:1
	v_add_f32_dpp v26, v26, v26 row_half_mirror row_mask:0xf bank_mask:0xf bound_ctrl:1
	v_add_f32_dpp v42, v42, v42 row_half_mirror row_mask:0xf bank_mask:0xf bound_ctrl:1
	v_add_f32_dpp v58, v58, v58 row_half_mirror row_mask:0xf bank_mask:0xf bound_ctrl:1
	v_add_f32_dpp v26, v26, v26 row_mirror row_mask:0xf bank_mask:0xf bound_ctrl:1
	v_add_f32_dpp v42, v42, v42 row_mirror row_mask:0xf bank_mask:0xf bound_ctrl:1
	v_add_f32_dpp v58, v58, v58 row_mirror row_mask:0xf bank_mask:0xf bound_ctrl:1
	v_mov_b32_dpp v31, v26 row_bcast:15 row_mask:0xa bank_mask:0xf
	v_mov_b32_dpp v47, v42 row_bcast:15 row_mask:0xa bank_mask:0xf
	v_mov_b32_dpp v63, v58 row_bcast:15 row_mask:0xa bank_mask:0xf
	v_add_f32_e32 v26, v26, v31
	v_add_f32_e32 v42, v42, v47
	v_add_f32_e32 v58, v58, v63
	v_mov_b32_dpp v32, v26 row_bcast:31 row_mask:0xc bank_mask:0xf
	v_mov_b32_dpp v48, v42 row_bcast:31 row_mask:0xc bank_mask:0xf
	v_mov_b32_dpp v64, v58 row_bcast:31 row_mask:0xc bank_mask:0xf
	v_add_f32_e32 v26, v26, v32
	v_add_f32_e32 v42, v42, v48
	v_add_f32_e32 v58, v58, v64
	s_nop 0
	v_readlane_b32 s16, v26, 63
	v_readlane_b32 s17, v42, 63
	v_readlane_b32 s18, v58, 63
	v_writelane_b32 v1, s16, 3
	v_writelane_b32 v1, s17, 4
	v_writelane_b32 v1, s18, 5
	ds_read_b128 v[26:29], v5 offset:24576
	ds_read_b128 v[30:33], v5 offset:25600
	ds_read_b128 v[34:37], v5 offset:26624
	ds_read_b128 v[38:41], v5 offset:27648
	ds_read_b128 v[42:45], v5 offset:28672
	ds_read_b128 v[46:49], v5 offset:29696
	ds_read_b128 v[50:53], v5 offset:30720
	ds_read_b128 v[54:57], v5 offset:31744
	ds_read_b128 v[58:61], v5 offset:32768
	ds_read_b128 v[62:65], v5 offset:33792
	ds_read_b128 v[66:69], v5 offset:34816
	ds_read_b128 v[70:73], v5 offset:35840
	s_waitcnt lgkmcnt(8)
	v_pk_fma_f32 v[28:29], v[8:9], v[28:29], 0 op_sel_hi:[1,1,0]
	v_pk_fma_f32 v[26:27], v[6:7], v[26:27], 0 op_sel_hi:[1,1,0]
	v_pk_fma_f32 v[28:29], v[12:13], v[32:33], v[28:29]
	v_pk_fma_f32 v[26:27], v[10:11], v[30:31], v[26:27]
	v_pk_fma_f32 v[28:29], v[16:17], v[36:37], v[28:29]
	v_pk_fma_f32 v[26:27], v[14:15], v[34:35], v[26:27]
	v_pk_fma_f32 v[28:29], v[20:21], v[40:41], v[28:29]
	v_pk_fma_f32 v[26:27], v[18:19], v[38:39], v[26:27]
	s_waitcnt lgkmcnt(4)
	v_pk_fma_f32 v[44:45], v[8:9], v[44:45], 0 op_sel_hi:[1,1,0]
	v_pk_fma_f32 v[42:43], v[6:7], v[42:43], 0 op_sel_hi:[1,1,0]
	v_pk_fma_f32 v[44:45], v[12:13], v[48:49], v[44:45]
	v_pk_fma_f32 v[42:43], v[10:11], v[46:47], v[42:43]
	v_pk_fma_f32 v[44:45], v[16:17], v[52:53], v[44:45]
	v_pk_fma_f32 v[42:43], v[14:15], v[50:51], v[42:43]
	v_pk_fma_f32 v[44:45], v[20:21], v[56:57], v[44:45]
	v_pk_fma_f32 v[42:43], v[18:19], v[54:55], v[42:43]
	s_waitcnt lgkmcnt(0)
	v_pk_fma_f32 v[60:61], v[8:9], v[60:61], 0 op_sel_hi:[1,1,0]
	v_pk_fma_f32 v[58:59], v[6:7], v[58:59], 0 op_sel_hi:[1,1,0]
	v_pk_fma_f32 v[60:61], v[12:13], v[64:65], v[60:61]
	v_pk_fma_f32 v[58:59], v[10:11], v[62:63], v[58:59]
	v_pk_fma_f32 v[60:61], v[16:17], v[68:69], v[60:61]
	v_pk_fma_f32 v[58:59], v[14:15], v[66:67], v[58:59]
	v_pk_fma_f32 v[60:61], v[20:21], v[72:73], v[60:61]
	v_pk_fma_f32 v[58:59], v[18:19], v[70:71], v[58:59]
	v_add_f32_e32 v30, v28, v29
	v_add_f32_e32 v46, v44, v45
	v_add_f32_e32 v62, v60, v61
	v_add_f32_e32 v26, v26, v27
	v_add_f32_e32 v42, v42, v43
	v_add_f32_e32 v58, v58, v59
	v_mov_b32_e32 v31, 0
	v_mov_b32_e32 v47, 0
	v_mov_b32_e32 v63, 0
	v_add_f32_e32 v26, v26, v30
	v_add_f32_e32 v42, v42, v46
	v_add_f32_e32 v58, v58, v62
	v_mov_b32_e32 v32, 0
	v_mov_b32_e32 v48, 0
	v_mov_b32_e32 v64, 0
	v_add_f32_dpp v26, v26, v26 quad_perm:[1,0,3,2] row_mask:0xf bank_mask:0xf bound_ctrl:1
	v_add_f32_dpp v42, v42, v42 quad_perm:[1,0,3,2] row_mask:0xf bank_mask:0xf bound_ctrl:1
	v_add_f32_dpp v58, v58, v58 quad_perm:[1,0,3,2] row_mask:0xf bank_mask:0xf bound_ctrl:1
	v_add_f32_dpp v26, v26, v26 quad_perm:[2,3,0,1] row_mask:0xf bank_mask:0xf bound_ctrl:1
	v_add_f32_dpp v42, v42, v42 quad_perm:[2,3,0,1] row_mask:0xf bank_mask:0xf bound_ctrl:1
	v_add_f32_dpp v58, v58, v58 quad_perm:[2,3,0,1] row_mask:0xf bank_mask:0xf bound_ctrl:1
	v_add_f32_dpp v26, v26, v26 row_half_mirror row_mask:0xf bank_mask:0xf bound_ctrl:1
	v_add_f32_dpp v42, v42, v42 row_half_mirror row_mask:0xf bank_mask:0xf bound_ctrl:1
	v_add_f32_dpp v58, v58, v58 row_half_mirror row_mask:0xf bank_mask:0xf bound_ctrl:1
	v_add_f32_dpp v26, v26, v26 row_mirror row_mask:0xf bank_mask:0xf bound_ctrl:1
	v_add_f32_dpp v42, v42, v42 row_mirror row_mask:0xf bank_mask:0xf bound_ctrl:1
	v_add_f32_dpp v58, v58, v58 row_mirror row_mask:0xf bank_mask:0xf bound_ctrl:1
	v_mov_b32_dpp v31, v26 row_bcast:15 row_mask:0xa bank_mask:0xf
	v_mov_b32_dpp v47, v42 row_bcast:15 row_mask:0xa bank_mask:0xf
	v_mov_b32_dpp v63, v58 row_bcast:15 row_mask:0xa bank_mask:0xf
	v_add_f32_e32 v26, v26, v31
	v_add_f32_e32 v42, v42, v47
	v_add_f32_e32 v58, v58, v63
	v_mov_b32_dpp v32, v26 row_bcast:31 row_mask:0xc bank_mask:0xf
	v_mov_b32_dpp v48, v42 row_bcast:31 row_mask:0xc bank_mask:0xf
	v_mov_b32_dpp v64, v58 row_bcast:31 row_mask:0xc bank_mask:0xf
	v_add_f32_e32 v26, v26, v32
	v_add_f32_e32 v42, v42, v48
	v_add_f32_e32 v58, v58, v64
	s_nop 0
	v_readlane_b32 s16, v26, 63
	v_readlane_b32 s17, v42, 63
	v_readlane_b32 s18, v58, 63
	v_writelane_b32 v1, s16, 6
	v_writelane_b32 v1, s17, 7
	v_writelane_b32 v1, s18, 8
	ds_read_b128 v[26:29], v5 offset:36864
	ds_read_b128 v[30:33], v5 offset:37888
	ds_read_b128 v[34:37], v5 offset:38912
	ds_read_b128 v[38:41], v5 offset:39936
	ds_read_b128 v[42:45], v5 offset:40960
	ds_read_b128 v[46:49], v5 offset:41984
	ds_read_b128 v[50:53], v5 offset:43008
	ds_read_b128 v[54:57], v5 offset:44032
	ds_read_b128 v[58:61], v5 offset:45056
	ds_read_b128 v[62:65], v5 offset:46080
	ds_read_b128 v[66:69], v5 offset:47104
	ds_read_b128 v[70:73], v5 offset:48128
	s_waitcnt lgkmcnt(8)
	v_pk_fma_f32 v[28:29], v[8:9], v[28:29], 0 op_sel_hi:[1,1,0]
	v_pk_fma_f32 v[26:27], v[6:7], v[26:27], 0 op_sel_hi:[1,1,0]
	v_pk_fma_f32 v[28:29], v[12:13], v[32:33], v[28:29]
	v_pk_fma_f32 v[26:27], v[10:11], v[30:31], v[26:27]
	v_pk_fma_f32 v[28:29], v[16:17], v[36:37], v[28:29]
	v_pk_fma_f32 v[26:27], v[14:15], v[34:35], v[26:27]
	v_pk_fma_f32 v[28:29], v[20:21], v[40:41], v[28:29]
	v_pk_fma_f32 v[26:27], v[18:19], v[38:39], v[26:27]
	s_waitcnt lgkmcnt(4)
	v_pk_fma_f32 v[44:45], v[8:9], v[44:45], 0 op_sel_hi:[1,1,0]
	v_pk_fma_f32 v[42:43], v[6:7], v[42:43], 0 op_sel_hi:[1,1,0]
	v_pk_fma_f32 v[44:45], v[12:13], v[48:49], v[44:45]
	v_pk_fma_f32 v[42:43], v[10:11], v[46:47], v[42:43]
	v_pk_fma_f32 v[44:45], v[16:17], v[52:53], v[44:45]
	v_pk_fma_f32 v[42:43], v[14:15], v[50:51], v[42:43]
	v_pk_fma_f32 v[44:45], v[20:21], v[56:57], v[44:45]
	v_pk_fma_f32 v[42:43], v[18:19], v[54:55], v[42:43]
	s_waitcnt lgkmcnt(0)
	v_pk_fma_f32 v[60:61], v[8:9], v[60:61], 0 op_sel_hi:[1,1,0]
	v_pk_fma_f32 v[58:59], v[6:7], v[58:59], 0 op_sel_hi:[1,1,0]
	v_pk_fma_f32 v[60:61], v[12:13], v[64:65], v[60:61]
	v_pk_fma_f32 v[58:59], v[10:11], v[62:63], v[58:59]
	v_pk_fma_f32 v[60:61], v[16:17], v[68:69], v[60:61]
	v_pk_fma_f32 v[58:59], v[14:15], v[66:67], v[58:59]
	v_pk_fma_f32 v[60:61], v[20:21], v[72:73], v[60:61]
	v_pk_fma_f32 v[58:59], v[18:19], v[70:71], v[58:59]
	v_add_f32_e32 v30, v28, v29
	v_add_f32_e32 v46, v44, v45
	v_add_f32_e32 v62, v60, v61
	v_add_f32_e32 v26, v26, v27
	v_add_f32_e32 v42, v42, v43
	v_add_f32_e32 v58, v58, v59
	v_mov_b32_e32 v31, 0
	v_mov_b32_e32 v47, 0
	v_mov_b32_e32 v63, 0
	v_add_f32_e32 v26, v26, v30
	v_add_f32_e32 v42, v42, v46
	v_add_f32_e32 v58, v58, v62
	v_mov_b32_e32 v32, 0
	v_mov_b32_e32 v48, 0
	v_mov_b32_e32 v64, 0
	v_add_f32_dpp v26, v26, v26 quad_perm:[1,0,3,2] row_mask:0xf bank_mask:0xf bound_ctrl:1
	v_add_f32_dpp v42, v42, v42 quad_perm:[1,0,3,2] row_mask:0xf bank_mask:0xf bound_ctrl:1
	v_add_f32_dpp v58, v58, v58 quad_perm:[1,0,3,2] row_mask:0xf bank_mask:0xf bound_ctrl:1
	v_add_f32_dpp v26, v26, v26 quad_perm:[2,3,0,1] row_mask:0xf bank_mask:0xf bound_ctrl:1
	v_add_f32_dpp v42, v42, v42 quad_perm:[2,3,0,1] row_mask:0xf bank_mask:0xf bound_ctrl:1
	v_add_f32_dpp v58, v58, v58 quad_perm:[2,3,0,1] row_mask:0xf bank_mask:0xf bound_ctrl:1
	v_add_f32_dpp v26, v26, v26 row_half_mirror row_mask:0xf bank_mask:0xf bound_ctrl:1
	v_add_f32_dpp v42, v42, v42 row_half_mirror row_mask:0xf bank_mask:0xf bound_ctrl:1
	v_add_f32_dpp v58, v58, v58 row_half_mirror row_mask:0xf bank_mask:0xf bound_ctrl:1
	v_add_f32_dpp v26, v26, v26 row_mirror row_mask:0xf bank_mask:0xf bound_ctrl:1
	v_add_f32_dpp v42, v42, v42 row_mirror row_mask:0xf bank_mask:0xf bound_ctrl:1
	v_add_f32_dpp v58, v58, v58 row_mirror row_mask:0xf bank_mask:0xf bound_ctrl:1
	v_mov_b32_dpp v31, v26 row_bcast:15 row_mask:0xa bank_mask:0xf
	v_mov_b32_dpp v47, v42 row_bcast:15 row_mask:0xa bank_mask:0xf
	v_mov_b32_dpp v63, v58 row_bcast:15 row_mask:0xa bank_mask:0xf
	v_add_f32_e32 v26, v26, v31
	v_add_f32_e32 v42, v42, v47
	v_add_f32_e32 v58, v58, v63
	v_mov_b32_dpp v32, v26 row_bcast:31 row_mask:0xc bank_mask:0xf
	v_mov_b32_dpp v48, v42 row_bcast:31 row_mask:0xc bank_mask:0xf
	v_mov_b32_dpp v64, v58 row_bcast:31 row_mask:0xc bank_mask:0xf
	v_add_f32_e32 v26, v26, v32
	v_add_f32_e32 v42, v42, v48
	v_add_f32_e32 v58, v58, v64
	s_nop 0
	v_readlane_b32 s16, v26, 63
	v_readlane_b32 s17, v42, 63
	v_readlane_b32 s18, v58, 63
	v_writelane_b32 v1, s16, 9
	v_writelane_b32 v1, s17, 10
	v_writelane_b32 v1, s18, 11
	s_mov_b64 s[26:27], exec
	s_mov_b32 exec_lo, 0xfff
	s_mov_b32 exec_hi, 0
	global_store_dword v25, v1, s[42:43]
	s_mov_b64 exec, s[26:27]
	s_add_u32 s40, s40, 0x400000
	s_addc_u32 s41, s41, 0
	s_add_u32 s42, s42, 0x20000
	s_addc_u32 s43, s43, 0
	s_waitcnt vmcnt(39)
	v_pk_mul_f32 v[50:51], v[210:211], v[210:211]
	v_pk_mul_f32 v[52:53], v[208:209], v[208:209]
	v_pk_mul_f32 v[54:55], v[214:215], v[214:215]
	v_pk_mul_f32 v[56:57], v[212:213], v[212:213]
	v_mul_f32_e32 v58, v217, v217
	v_mul_f32_e32 v60, v219, v219
	v_pk_mul_f32 v[64:65], v[220:221], v[220:221]
	v_pk_mul_f32 v[66:67], v[222:223], v[222:223]
	v_add_f32_e32 v52, v53, v52
	v_add_f32_e32 v50, v50, v51
	v_add_f32_e32 v56, v57, v56
	v_add_f32_e32 v54, v54, v55
	v_fma_f32 v58, v216, v216, v58
	v_fma_f32 v60, v218, v218, v60
	v_add_f32_e32 v64, v64, v65
	v_add_f32_e32 v66, v66, v67
	v_add_f32_e32 v52, v52, v50
	v_add_f32_e32 v56, v56, v54
	v_add_f32_e32 v58, v58, v60
	v_add_f32_e32 v64, v64, v66
	v_add_f32_e32 v50, v52, v56
	v_mov_b32_e32 v61, 0
	v_mov_b32_e32 v62, 0
	v_add_f32_e32 v50, v50, v58
	s_nop 0
	v_add_f32_e32 v50, v50, v64
	s_nop 1
	v_add_f32_dpp v50, v50, v50 quad_perm:[1,0,3,2] row_mask:0xf bank_mask:0xf bound_ctrl:1
	s_nop 1
	v_add_f32_dpp v50, v50, v50 quad_perm:[2,3,0,1] row_mask:0xf bank_mask:0xf bound_ctrl:1
	s_nop 1
	v_add_f32_dpp v50, v50, v50 row_half_mirror row_mask:0xf bank_mask:0xf bound_ctrl:1
	s_nop 1
	v_add_f32_dpp v50, v50, v50 row_mirror row_mask:0xf bank_mask:0xf bound_ctrl:1
	s_nop 1
	v_mov_b32_dpp v61, v50 row_bcast:15 row_mask:0xa bank_mask:0xf
	s_nop 1
	v_add_f32_e32 v50, v50, v61
	s_nop 1
	v_mov_b32_dpp v62, v50 row_bcast:31 row_mask:0xc bank_mask:0xf
	s_nop 1
	v_add_f32_e32 v50, v50, v62
	s_nop 0
	v_readlane_b32 s15, v50, 63
	s_nop 1
	v_fma_f32 v50, s15, v24, v23
	v_mul_f32_e32 v51, 0x4b800000, v50
	v_cmp_gt_f32_e32 vcc, s5, v50
	s_nop 1
	v_cndmask_b32_e32 v50, v50, v51, vcc
	v_rsq_f32_e32 v52, v50
	s_nop 0
	v_mul_f32_e32 v53, 0x45800000, v52
	v_cndmask_b32_e32 v52, v52, v53, vcc
	v_pk_mul_f32 v[6:7], v[208:209], v[52:53] op_sel_hi:[1,0]
	v_pk_mul_f32 v[8:9], v[210:211], v[52:53] op_sel_hi:[1,0]
	v_pk_mul_f32 v[10:11], v[212:213], v[52:53] op_sel_hi:[1,0]
	v_pk_mul_f32 v[12:13], v[214:215], v[52:53] op_sel_hi:[1,0]
	v_pk_mul_f32 v[14:15], v[216:217], v[52:53] op_sel_hi:[1,0]
	v_pk_mul_f32 v[16:17], v[218:219], v[52:53] op_sel_hi:[1,0]
	v_pk_mul_f32 v[18:19], v[220:221], v[52:53] op_sel_hi:[1,0]
	v_pk_mul_f32 v[20:21], v[222:223], v[52:53] op_sel_hi:[1,0]
	v_pk_mul_f32 v[6:7], v[80:81], v[6:7]
	v_pk_mul_f32 v[8:9], v[82:83], v[8:9]
	v_pk_mul_f32 v[10:11], v[84:85], v[10:11]
	v_pk_mul_f32 v[12:13], v[86:87], v[12:13]
	v_pk_mul_f32 v[14:15], v[88:89], v[14:15]
	v_pk_mul_f32 v[16:17], v[90:91], v[16:17]
	v_pk_mul_f32 v[18:19], v[92:93], v[18:19]
	v_pk_mul_f32 v[20:21], v[94:95], v[20:21]
	v_cvt_pk_bf16_f32 v240, v6, v7
	v_cvt_pk_bf16_f32 v241, v8, v9
	v_cvt_pk_bf16_f32 v242, v10, v11
	v_cvt_pk_bf16_f32 v243, v12, v13
	v_cvt_pk_bf16_f32 v244, v14, v15
	v_cvt_pk_bf16_f32 v245, v16, v17
	v_cvt_pk_bf16_f32 v246, v18, v19
	v_cvt_pk_bf16_f32 v247, v20, v21
	global_store_dwordx2 v2, v[240:241], s[40:41] offset:0
	global_store_dwordx2 v2, v[242:243], s[40:41] offset:512
	global_store_dwordx2 v2, v[244:245], s[40:41] offset:1024
	global_store_dwordx2 v2, v[246:247], s[40:41] offset:1536
	ds_read_b128 v[26:29], v5 offset:0
	ds_read_b128 v[30:33], v5 offset:1024
	ds_read_b128 v[34:37], v5 offset:2048
	ds_read_b128 v[38:41], v5 offset:3072
	ds_read_b128 v[42:45], v5 offset:4096
	ds_read_b128 v[46:49], v5 offset:5120
	ds_read_b128 v[50:53], v5 offset:6144
	ds_read_b128 v[54:57], v5 offset:7168
	ds_read_b128 v[58:61], v5 offset:8192
	ds_read_b128 v[62:65], v5 offset:9216
	ds_read_b128 v[66:69], v5 offset:10240
	ds_read_b128 v[70:73], v5 offset:11264
	s_waitcnt lgkmcnt(8)
	v_pk_fma_f32 v[28:29], v[8:9], v[28:29], 0 op_sel_hi:[1,1,0]
	v_pk_fma_f32 v[26:27], v[6:7], v[26:27], 0 op_sel_hi:[1,1,0]
	v_pk_fma_f32 v[28:29], v[12:13], v[32:33], v[28:29]
	v_pk_fma_f32 v[26:27], v[10:11], v[30:31], v[26:27]
	v_pk_fma_f32 v[28:29], v[16:17], v[36:37], v[28:29]
	v_pk_fma_f32 v[26:27], v[14:15], v[34:35], v[26:27]
	v_pk_fma_f32 v[28:29], v[20:21], v[40:41], v[28:29]
	v_pk_fma_f32 v[26:27], v[18:19], v[38:39], v[26:27]
	s_waitcnt lgkmcnt(4)
	v_pk_fma_f32 v[44:45], v[8:9], v[44:45], 0 op_sel_hi:[1,1,0]
	v_pk_fma_f32 v[42:43], v[6:7], v[42:43], 0 op_sel_hi:[1,1,0]
	v_pk_fma_f32 v[44:45], v[12:13], v[48:49], v[44:45]
	v_pk_fma_f32 v[42:43], v[10:11], v[46:47], v[42:43]
	v_pk_fma_f32 v[44:45], v[16:17], v[52:53], v[44:45]
	v_pk_fma_f32 v[42:43], v[14:15], v[50:51], v[42:43]
	v_pk_fma_f32 v[44:45], v[20:21], v[56:57], v[44:45]
	v_pk_fma_f32 v[42:43], v[18:19], v[54:55], v[42:43]
	s_waitcnt lgkmcnt(0)
	v_pk_fma_f32 v[60:61], v[8:9], v[60:61], 0 op_sel_hi:[1,1,0]
	v_pk_fma_f32 v[58:59], v[6:7], v[58:59], 0 op_sel_hi:[1,1,0]
	v_pk_fma_f32 v[60:61], v[12:13], v[64:65], v[60:61]
	v_pk_fma_f32 v[58:59], v[10:11], v[62:63], v[58:59]
	v_pk_fma_f32 v[60:61], v[16:17], v[68:69], v[60:61]
	v_pk_fma_f32 v[58:59], v[14:15], v[66:67], v[58:59]
	v_pk_fma_f32 v[60:61], v[20:21], v[72:73], v[60:61]
	v_pk_fma_f32 v[58:59], v[18:19], v[70:71], v[58:59]
	v_add_f32_e32 v30, v28, v29
	v_add_f32_e32 v46, v44, v45
	v_add_f32_e32 v62, v60, v61
	v_add_f32_e32 v26, v26, v27
	v_add_f32_e32 v42, v42, v43
	v_add_f32_e32 v58, v58, v59
	v_mov_b32_e32 v31, 0
	v_mov_b32_e32 v47, 0
	v_mov_b32_e32 v63, 0
	v_add_f32_e32 v26, v26, v30
	v_add_f32_e32 v42, v42, v46
	v_add_f32_e32 v58, v58, v62
	v_mov_b32_e32 v32, 0
	v_mov_b32_e32 v48, 0
	v_mov_b32_e32 v64, 0
	v_add_f32_dpp v26, v26, v26 quad_perm:[1,0,3,2] row_mask:0xf bank_mask:0xf bound_ctrl:1
	v_add_f32_dpp v42, v42, v42 quad_perm:[1,0,3,2] row_mask:0xf bank_mask:0xf bound_ctrl:1
	v_add_f32_dpp v58, v58, v58 quad_perm:[1,0,3,2] row_mask:0xf bank_mask:0xf bound_ctrl:1
	v_add_f32_dpp v26, v26, v26 quad_perm:[2,3,0,1] row_mask:0xf bank_mask:0xf bound_ctrl:1
	v_add_f32_dpp v42, v42, v42 quad_perm:[2,3,0,1] row_mask:0xf bank_mask:0xf bound_ctrl:1
	v_add_f32_dpp v58, v58, v58 quad_perm:[2,3,0,1] row_mask:0xf bank_mask:0xf bound_ctrl:1
	v_add_f32_dpp v26, v26, v26 row_half_mirror row_mask:0xf bank_mask:0xf bound_ctrl:1
	v_add_f32_dpp v42, v42, v42 row_half_mirror row_mask:0xf bank_mask:0xf bound_ctrl:1
	v_add_f32_dpp v58, v58, v58 row_half_mirror row_mask:0xf bank_mask:0xf bound_ctrl:1
	v_add_f32_dpp v26, v26, v26 row_mirror row_mask:0xf bank_mask:0xf bound_ctrl:1
	v_add_f32_dpp v42, v42, v42 row_mirror row_mask:0xf bank_mask:0xf bound_ctrl:1
	v_add_f32_dpp v58, v58, v58 row_mirror row_mask:0xf bank_mask:0xf bound_ctrl:1
	v_mov_b32_dpp v31, v26 row_bcast:15 row_mask:0xa bank_mask:0xf
	v_mov_b32_dpp v47, v42 row_bcast:15 row_mask:0xa bank_mask:0xf
	v_mov_b32_dpp v63, v58 row_bcast:15 row_mask:0xa bank_mask:0xf
	v_add_f32_e32 v26, v26, v31
	v_add_f32_e32 v42, v42, v47
	v_add_f32_e32 v58, v58, v63
	v_mov_b32_dpp v32, v26 row_bcast:31 row_mask:0xc bank_mask:0xf
	v_mov_b32_dpp v48, v42 row_bcast:31 row_mask:0xc bank_mask:0xf
	v_mov_b32_dpp v64, v58 row_bcast:31 row_mask:0xc bank_mask:0xf
	v_add_f32_e32 v26, v26, v32
	v_add_f32_e32 v42, v42, v48
	v_add_f32_e32 v58, v58, v64
	s_nop 0
	v_readlane_b32 s16, v26, 63
	v_readlane_b32 s17, v42, 63
	v_readlane_b32 s18, v58, 63
	v_writelane_b32 v1, s16, 0
	v_writelane_b32 v1, s17, 1
	v_writelane_b32 v1, s18, 2
	ds_read_b128 v[26:29], v5 offset:12288
	ds_read_b128 v[30:33], v5 offset:13312
	ds_read_b128 v[34:37], v5 offset:14336
	ds_read_b128 v[38:41], v5 offset:15360
	ds_read_b128 v[42:45], v5 offset:16384
	ds_read_b128 v[46:49], v5 offset:17408
	ds_read_b128 v[50:53], v5 offset:18432
	ds_read_b128 v[54:57], v5 offset:19456
	ds_read_b128 v[58:61], v5 offset:20480
	ds_read_b128 v[62:65], v5 offset:21504
	ds_read_b128 v[66:69], v5 offset:22528
	ds_read_b128 v[70:73], v5 offset:23552
	s_waitcnt lgkmcnt(8)
	v_pk_fma_f32 v[28:29], v[8:9], v[28:29], 0 op_sel_hi:[1,1,0]
	v_pk_fma_f32 v[26:27], v[6:7], v[26:27], 0 op_sel_hi:[1,1,0]
	v_pk_fma_f32 v[28:29], v[12:13], v[32:33], v[28:29]
	v_pk_fma_f32 v[26:27], v[10:11], v[30:31], v[26:27]
	v_pk_fma_f32 v[28:29], v[16:17], v[36:37], v[28:29]
	v_pk_fma_f32 v[26:27], v[14:15], v[34:35], v[26:27]
	v_pk_fma_f32 v[28:29], v[20:21], v[40:41], v[28:29]
	v_pk_fma_f32 v[26:27], v[18:19], v[38:39], v[26:27]
	s_waitcnt lgkmcnt(4)
	v_pk_fma_f32 v[44:45], v[8:9], v[44:45], 0 op_sel_hi:[1,1,0]
	v_pk_fma_f32 v[42:43], v[6:7], v[42:43], 0 op_sel_hi:[1,1,0]
	v_pk_fma_f32 v[44:45], v[12:13], v[48:49], v[44:45]
	v_pk_fma_f32 v[42:43], v[10:11], v[46:47], v[42:43]
	v_pk_fma_f32 v[44:45], v[16:17], v[52:53], v[44:45]
	v_pk_fma_f32 v[42:43], v[14:15], v[50:51], v[42:43]
	v_pk_fma_f32 v[44:45], v[20:21], v[56:57], v[44:45]
	v_pk_fma_f32 v[42:43], v[18:19], v[54:55], v[42:43]
	s_waitcnt lgkmcnt(0)
	v_pk_fma_f32 v[60:61], v[8:9], v[60:61], 0 op_sel_hi:[1,1,0]
	v_pk_fma_f32 v[58:59], v[6:7], v[58:59], 0 op_sel_hi:[1,1,0]
	v_pk_fma_f32 v[60:61], v[12:13], v[64:65], v[60:61]
	v_pk_fma_f32 v[58:59], v[10:11], v[62:63], v[58:59]
	v_pk_fma_f32 v[60:61], v[16:17], v[68:69], v[60:61]
	v_pk_fma_f32 v[58:59], v[14:15], v[66:67], v[58:59]
	v_pk_fma_f32 v[60:61], v[20:21], v[72:73], v[60:61]
	v_pk_fma_f32 v[58:59], v[18:19], v[70:71], v[58:59]
	v_add_f32_e32 v30, v28, v29
	v_add_f32_e32 v46, v44, v45
	v_add_f32_e32 v62, v60, v61
	v_add_f32_e32 v26, v26, v27
	v_add_f32_e32 v42, v42, v43
	v_add_f32_e32 v58, v58, v59
	v_mov_b32_e32 v31, 0
	v_mov_b32_e32 v47, 0
	v_mov_b32_e32 v63, 0
	v_add_f32_e32 v26, v26, v30
	v_add_f32_e32 v42, v42, v46
	v_add_f32_e32 v58, v58, v62
	v_mov_b32_e32 v32, 0
	v_mov_b32_e32 v48, 0
	v_mov_b32_e32 v64, 0
	v_add_f32_dpp v26, v26, v26 quad_perm:[1,0,3,2] row_mask:0xf bank_mask:0xf bound_ctrl:1
	v_add_f32_dpp v42, v42, v42 quad_perm:[1,0,3,2] row_mask:0xf bank_mask:0xf bound_ctrl:1
	v_add_f32_dpp v58, v58, v58 quad_perm:[1,0,3,2] row_mask:0xf bank_mask:0xf bound_ctrl:1
	v_add_f32_dpp v26, v26, v26 quad_perm:[2,3,0,1] row_mask:0xf bank_mask:0xf bound_ctrl:1
	v_add_f32_dpp v42, v42, v42 quad_perm:[2,3,0,1] row_mask:0xf bank_mask:0xf bound_ctrl:1
	v_add_f32_dpp v58, v58, v58 quad_perm:[2,3,0,1] row_mask:0xf bank_mask:0xf bound_ctrl:1
	v_add_f32_dpp v26, v26, v26 row_half_mirror row_mask:0xf bank_mask:0xf bound_ctrl:1
	v_add_f32_dpp v42, v42, v42 row_half_mirror row_mask:0xf bank_mask:0xf bound_ctrl:1
	v_add_f32_dpp v58, v58, v58 row_half_mirror row_mask:0xf bank_mask:0xf bound_ctrl:1
	v_add_f32_dpp v26, v26, v26 row_mirror row_mask:0xf bank_mask:0xf bound_ctrl:1
	v_add_f32_dpp v42, v42, v42 row_mirror row_mask:0xf bank_mask:0xf bound_ctrl:1
	v_add_f32_dpp v58, v58, v58 row_mirror row_mask:0xf bank_mask:0xf bound_ctrl:1
	v_mov_b32_dpp v31, v26 row_bcast:15 row_mask:0xa bank_mask:0xf
	v_mov_b32_dpp v47, v42 row_bcast:15 row_mask:0xa bank_mask:0xf
	v_mov_b32_dpp v63, v58 row_bcast:15 row_mask:0xa bank_mask:0xf
	v_add_f32_e32 v26, v26, v31
	v_add_f32_e32 v42, v42, v47
	v_add_f32_e32 v58, v58, v63
	v_mov_b32_dpp v32, v26 row_bcast:31 row_mask:0xc bank_mask:0xf
	v_mov_b32_dpp v48, v42 row_bcast:31 row_mask:0xc bank_mask:0xf
	v_mov_b32_dpp v64, v58 row_bcast:31 row_mask:0xc bank_mask:0xf
	v_add_f32_e32 v26, v26, v32
	v_add_f32_e32 v42, v42, v48
	v_add_f32_e32 v58, v58, v64
	s_nop 0
	v_readlane_b32 s16, v26, 63
	v_readlane_b32 s17, v42, 63
	v_readlane_b32 s18, v58, 63
	v_writelane_b32 v1, s16, 3
	v_writelane_b32 v1, s17, 4
	v_writelane_b32 v1, s18, 5
	ds_read_b128 v[26:29], v5 offset:24576
	ds_read_b128 v[30:33], v5 offset:25600
	ds_read_b128 v[34:37], v5 offset:26624
	ds_read_b128 v[38:41], v5 offset:27648
	ds_read_b128 v[42:45], v5 offset:28672
	ds_read_b128 v[46:49], v5 offset:29696
	ds_read_b128 v[50:53], v5 offset:30720
	ds_read_b128 v[54:57], v5 offset:31744
	ds_read_b128 v[58:61], v5 offset:32768
	ds_read_b128 v[62:65], v5 offset:33792
	ds_read_b128 v[66:69], v5 offset:34816
	ds_read_b128 v[70:73], v5 offset:35840
	s_waitcnt lgkmcnt(8)
	v_pk_fma_f32 v[28:29], v[8:9], v[28:29], 0 op_sel_hi:[1,1,0]
	v_pk_fma_f32 v[26:27], v[6:7], v[26:27], 0 op_sel_hi:[1,1,0]
	v_pk_fma_f32 v[28:29], v[12:13], v[32:33], v[28:29]
	v_pk_fma_f32 v[26:27], v[10:11], v[30:31], v[26:27]
	v_pk_fma_f32 v[28:29], v[16:17], v[36:37], v[28:29]
	v_pk_fma_f32 v[26:27], v[14:15], v[34:35], v[26:27]
	v_pk_fma_f32 v[28:29], v[20:21], v[40:41], v[28:29]
	v_pk_fma_f32 v[26:27], v[18:19], v[38:39], v[26:27]
	s_waitcnt lgkmcnt(4)
	v_pk_fma_f32 v[44:45], v[8:9], v[44:45], 0 op_sel_hi:[1,1,0]
	v_pk_fma_f32 v[42:43], v[6:7], v[42:43], 0 op_sel_hi:[1,1,0]
	v_pk_fma_f32 v[44:45], v[12:13], v[48:49], v[44:45]
	v_pk_fma_f32 v[42:43], v[10:11], v[46:47], v[42:43]
	v_pk_fma_f32 v[44:45], v[16:17], v[52:53], v[44:45]
	v_pk_fma_f32 v[42:43], v[14:15], v[50:51], v[42:43]
	v_pk_fma_f32 v[44:45], v[20:21], v[56:57], v[44:45]
	v_pk_fma_f32 v[42:43], v[18:19], v[54:55], v[42:43]
	s_waitcnt lgkmcnt(0)
	v_pk_fma_f32 v[60:61], v[8:9], v[60:61], 0 op_sel_hi:[1,1,0]
	v_pk_fma_f32 v[58:59], v[6:7], v[58:59], 0 op_sel_hi:[1,1,0]
	v_pk_fma_f32 v[60:61], v[12:13], v[64:65], v[60:61]
	v_pk_fma_f32 v[58:59], v[10:11], v[62:63], v[58:59]
	v_pk_fma_f32 v[60:61], v[16:17], v[68:69], v[60:61]
	v_pk_fma_f32 v[58:59], v[14:15], v[66:67], v[58:59]
	v_pk_fma_f32 v[60:61], v[20:21], v[72:73], v[60:61]
	v_pk_fma_f32 v[58:59], v[18:19], v[70:71], v[58:59]
	v_add_f32_e32 v30, v28, v29
	v_add_f32_e32 v46, v44, v45
	v_add_f32_e32 v62, v60, v61
	v_add_f32_e32 v26, v26, v27
	v_add_f32_e32 v42, v42, v43
	v_add_f32_e32 v58, v58, v59
	v_mov_b32_e32 v31, 0
	v_mov_b32_e32 v47, 0
	v_mov_b32_e32 v63, 0
	v_add_f32_e32 v26, v26, v30
	v_add_f32_e32 v42, v42, v46
	v_add_f32_e32 v58, v58, v62
	v_mov_b32_e32 v32, 0
	v_mov_b32_e32 v48, 0
	v_mov_b32_e32 v64, 0
	v_add_f32_dpp v26, v26, v26 quad_perm:[1,0,3,2] row_mask:0xf bank_mask:0xf bound_ctrl:1
	v_add_f32_dpp v42, v42, v42 quad_perm:[1,0,3,2] row_mask:0xf bank_mask:0xf bound_ctrl:1
	v_add_f32_dpp v58, v58, v58 quad_perm:[1,0,3,2] row_mask:0xf bank_mask:0xf bound_ctrl:1
	v_add_f32_dpp v26, v26, v26 quad_perm:[2,3,0,1] row_mask:0xf bank_mask:0xf bound_ctrl:1
	v_add_f32_dpp v42, v42, v42 quad_perm:[2,3,0,1] row_mask:0xf bank_mask:0xf bound_ctrl:1
	v_add_f32_dpp v58, v58, v58 quad_perm:[2,3,0,1] row_mask:0xf bank_mask:0xf bound_ctrl:1
	v_add_f32_dpp v26, v26, v26 row_half_mirror row_mask:0xf bank_mask:0xf bound_ctrl:1
	v_add_f32_dpp v42, v42, v42 row_half_mirror row_mask:0xf bank_mask:0xf bound_ctrl:1
	v_add_f32_dpp v58, v58, v58 row_half_mirror row_mask:0xf bank_mask:0xf bound_ctrl:1
	v_add_f32_dpp v26, v26, v26 row_mirror row_mask:0xf bank_mask:0xf bound_ctrl:1
	v_add_f32_dpp v42, v42, v42 row_mirror row_mask:0xf bank_mask:0xf bound_ctrl:1
	v_add_f32_dpp v58, v58, v58 row_mirror row_mask:0xf bank_mask:0xf bound_ctrl:1
	v_mov_b32_dpp v31, v26 row_bcast:15 row_mask:0xa bank_mask:0xf
	v_mov_b32_dpp v47, v42 row_bcast:15 row_mask:0xa bank_mask:0xf
	v_mov_b32_dpp v63, v58 row_bcast:15 row_mask:0xa bank_mask:0xf
	v_add_f32_e32 v26, v26, v31
	v_add_f32_e32 v42, v42, v47
	v_add_f32_e32 v58, v58, v63
	v_mov_b32_dpp v32, v26 row_bcast:31 row_mask:0xc bank_mask:0xf
	v_mov_b32_dpp v48, v42 row_bcast:31 row_mask:0xc bank_mask:0xf
	v_mov_b32_dpp v64, v58 row_bcast:31 row_mask:0xc bank_mask:0xf
	v_add_f32_e32 v26, v26, v32
	v_add_f32_e32 v42, v42, v48
	v_add_f32_e32 v58, v58, v64
	s_nop 0
	v_readlane_b32 s16, v26, 63
	v_readlane_b32 s17, v42, 63
	v_readlane_b32 s18, v58, 63
	v_writelane_b32 v1, s16, 6
	v_writelane_b32 v1, s17, 7
	v_writelane_b32 v1, s18, 8
	ds_read_b128 v[26:29], v5 offset:36864
	ds_read_b128 v[30:33], v5 offset:37888
	ds_read_b128 v[34:37], v5 offset:38912
	ds_read_b128 v[38:41], v5 offset:39936
	ds_read_b128 v[42:45], v5 offset:40960
	ds_read_b128 v[46:49], v5 offset:41984
	ds_read_b128 v[50:53], v5 offset:43008
	ds_read_b128 v[54:57], v5 offset:44032
	ds_read_b128 v[58:61], v5 offset:45056
	ds_read_b128 v[62:65], v5 offset:46080
	ds_read_b128 v[66:69], v5 offset:47104
	ds_read_b128 v[70:73], v5 offset:48128
	s_waitcnt lgkmcnt(8)
	v_pk_fma_f32 v[28:29], v[8:9], v[28:29], 0 op_sel_hi:[1,1,0]
	v_pk_fma_f32 v[26:27], v[6:7], v[26:27], 0 op_sel_hi:[1,1,0]
	v_pk_fma_f32 v[28:29], v[12:13], v[32:33], v[28:29]
	v_pk_fma_f32 v[26:27], v[10:11], v[30:31], v[26:27]
	v_pk_fma_f32 v[28:29], v[16:17], v[36:37], v[28:29]
	v_pk_fma_f32 v[26:27], v[14:15], v[34:35], v[26:27]
	v_pk_fma_f32 v[28:29], v[20:21], v[40:41], v[28:29]
	v_pk_fma_f32 v[26:27], v[18:19], v[38:39], v[26:27]
	s_waitcnt lgkmcnt(4)
	v_pk_fma_f32 v[44:45], v[8:9], v[44:45], 0 op_sel_hi:[1,1,0]
	v_pk_fma_f32 v[42:43], v[6:7], v[42:43], 0 op_sel_hi:[1,1,0]
	v_pk_fma_f32 v[44:45], v[12:13], v[48:49], v[44:45]
	v_pk_fma_f32 v[42:43], v[10:11], v[46:47], v[42:43]
	v_pk_fma_f32 v[44:45], v[16:17], v[52:53], v[44:45]
	v_pk_fma_f32 v[42:43], v[14:15], v[50:51], v[42:43]
	v_pk_fma_f32 v[44:45], v[20:21], v[56:57], v[44:45]
	v_pk_fma_f32 v[42:43], v[18:19], v[54:55], v[42:43]
	s_waitcnt lgkmcnt(0)
	v_pk_fma_f32 v[60:61], v[8:9], v[60:61], 0 op_sel_hi:[1,1,0]
	v_pk_fma_f32 v[58:59], v[6:7], v[58:59], 0 op_sel_hi:[1,1,0]
	v_pk_fma_f32 v[60:61], v[12:13], v[64:65], v[60:61]
	v_pk_fma_f32 v[58:59], v[10:11], v[62:63], v[58:59]
	v_pk_fma_f32 v[60:61], v[16:17], v[68:69], v[60:61]
	v_pk_fma_f32 v[58:59], v[14:15], v[66:67], v[58:59]
	v_pk_fma_f32 v[60:61], v[20:21], v[72:73], v[60:61]
	v_pk_fma_f32 v[58:59], v[18:19], v[70:71], v[58:59]
	v_add_f32_e32 v30, v28, v29
	v_add_f32_e32 v46, v44, v45
	v_add_f32_e32 v62, v60, v61
	v_add_f32_e32 v26, v26, v27
	v_add_f32_e32 v42, v42, v43
	v_add_f32_e32 v58, v58, v59
	v_mov_b32_e32 v31, 0
	v_mov_b32_e32 v47, 0
	v_mov_b32_e32 v63, 0
	v_add_f32_e32 v26, v26, v30
	v_add_f32_e32 v42, v42, v46
	v_add_f32_e32 v58, v58, v62
	v_mov_b32_e32 v32, 0
	v_mov_b32_e32 v48, 0
	v_mov_b32_e32 v64, 0
	v_add_f32_dpp v26, v26, v26 quad_perm:[1,0,3,2] row_mask:0xf bank_mask:0xf bound_ctrl:1
	v_add_f32_dpp v42, v42, v42 quad_perm:[1,0,3,2] row_mask:0xf bank_mask:0xf bound_ctrl:1
	v_add_f32_dpp v58, v58, v58 quad_perm:[1,0,3,2] row_mask:0xf bank_mask:0xf bound_ctrl:1
	v_add_f32_dpp v26, v26, v26 quad_perm:[2,3,0,1] row_mask:0xf bank_mask:0xf bound_ctrl:1
	v_add_f32_dpp v42, v42, v42 quad_perm:[2,3,0,1] row_mask:0xf bank_mask:0xf bound_ctrl:1
	v_add_f32_dpp v58, v58, v58 quad_perm:[2,3,0,1] row_mask:0xf bank_mask:0xf bound_ctrl:1
	v_add_f32_dpp v26, v26, v26 row_half_mirror row_mask:0xf bank_mask:0xf bound_ctrl:1
	v_add_f32_dpp v42, v42, v42 row_half_mirror row_mask:0xf bank_mask:0xf bound_ctrl:1
	v_add_f32_dpp v58, v58, v58 row_half_mirror row_mask:0xf bank_mask:0xf bound_ctrl:1
	v_add_f32_dpp v26, v26, v26 row_mirror row_mask:0xf bank_mask:0xf bound_ctrl:1
	v_add_f32_dpp v42, v42, v42 row_mirror row_mask:0xf bank_mask:0xf bound_ctrl:1
	v_add_f32_dpp v58, v58, v58 row_mirror row_mask:0xf bank_mask:0xf bound_ctrl:1
	v_mov_b32_dpp v31, v26 row_bcast:15 row_mask:0xa bank_mask:0xf
	v_mov_b32_dpp v47, v42 row_bcast:15 row_mask:0xa bank_mask:0xf
	v_mov_b32_dpp v63, v58 row_bcast:15 row_mask:0xa bank_mask:0xf
	v_add_f32_e32 v26, v26, v31
	v_add_f32_e32 v42, v42, v47
	v_add_f32_e32 v58, v58, v63
	v_mov_b32_dpp v32, v26 row_bcast:31 row_mask:0xc bank_mask:0xf
	v_mov_b32_dpp v48, v42 row_bcast:31 row_mask:0xc bank_mask:0xf
	v_mov_b32_dpp v64, v58 row_bcast:31 row_mask:0xc bank_mask:0xf
	v_add_f32_e32 v26, v26, v32
	v_add_f32_e32 v42, v42, v48
	v_add_f32_e32 v58, v58, v64
	s_nop 0
	v_readlane_b32 s16, v26, 63
	v_readlane_b32 s17, v42, 63
	v_readlane_b32 s18, v58, 63
	v_writelane_b32 v1, s16, 9
	v_writelane_b32 v1, s17, 10
	v_writelane_b32 v1, s18, 11
	s_mov_b64 s[26:27], exec
	s_mov_b32 exec_lo, 0xfff
	s_mov_b32 exec_hi, 0
	global_store_dword v25, v1, s[42:43]
	s_mov_b64 exec, s[26:27]
	s_add_u32 s40, s40, 0x400000
	s_addc_u32 s41, s41, 0
	s_add_u32 s42, s42, 0x20000
	s_addc_u32 s43, s43, 0
	s_cmp_ge_u32 s6, 0x420
	s_cbranch_scc1 .Lp0n_done
	s_waitcnt vmcnt(40)
	v_pk_mul_f32 v[50:51], v[226:227], v[226:227]
	v_pk_mul_f32 v[52:53], v[224:225], v[224:225]
	v_pk_mul_f32 v[54:55], v[230:231], v[230:231]
	v_pk_mul_f32 v[56:57], v[228:229], v[228:229]
	v_mul_f32_e32 v58, v233, v233
	v_mul_f32_e32 v60, v235, v235
	v_pk_mul_f32 v[64:65], v[236:237], v[236:237]
	v_pk_mul_f32 v[66:67], v[238:239], v[238:239]
	v_add_f32_e32 v52, v53, v52
	v_add_f32_e32 v50, v50, v51
	v_add_f32_e32 v56, v57, v56
	v_add_f32_e32 v54, v54, v55
	v_fma_f32 v58, v232, v232, v58
	v_fma_f32 v60, v234, v234, v60
	v_add_f32_e32 v64, v64, v65
	v_add_f32_e32 v66, v66, v67
	v_add_f32_e32 v52, v52, v50
	v_add_f32_e32 v56, v56, v54
	v_add_f32_e32 v58, v58, v60
	v_add_f32_e32 v64, v64, v66
	v_add_f32_e32 v50, v52, v56
	v_mov_b32_e32 v61, 0
	v_mov_b32_e32 v62, 0
	v_add_f32_e32 v50, v50, v58
	s_nop 0
	v_add_f32_e32 v50, v50, v64
	s_nop 1
	v_add_f32_dpp v50, v50, v50 quad_perm:[1,0,3,2] row_mask:0xf bank_mask:0xf bound_ctrl:1
	s_nop 1
	v_add_f32_dpp v50, v50, v50 quad_perm:[2,3,0,1] row_mask:0xf bank_mask:0xf bound_ctrl:1
	s_nop 1
	v_add_f32_dpp v50, v50, v50 row_half_mirror row_mask:0xf bank_mask:0xf bound_ctrl:1
	s_nop 1
	v_add_f32_dpp v50, v50, v50 row_mirror row_mask:0xf bank_mask:0xf bound_ctrl:1
	s_nop 1
	v_mov_b32_dpp v61, v50 row_bcast:15 row_mask:0xa bank_mask:0xf
	s_nop 1
	v_add_f32_e32 v50, v50, v61
	s_nop 1
	v_mov_b32_dpp v62, v50 row_bcast:31 row_mask:0xc bank_mask:0xf
	s_nop 1
	v_add_f32_e32 v50, v50, v62
	s_nop 0
	v_readlane_b32 s15, v50, 63
	s_nop 1
	v_fma_f32 v50, s15, v24, v23
	v_mul_f32_e32 v51, 0x4b800000, v50
	v_cmp_gt_f32_e32 vcc, s5, v50
	s_nop 1
	v_cndmask_b32_e32 v50, v50, v51, vcc
	v_rsq_f32_e32 v52, v50
	s_nop 0
	v_mul_f32_e32 v53, 0x45800000, v52
	v_cndmask_b32_e32 v52, v52, v53, vcc
	v_pk_mul_f32 v[6:7], v[224:225], v[52:53] op_sel_hi:[1,0]
	v_pk_mul_f32 v[8:9], v[226:227], v[52:53] op_sel_hi:[1,0]
	v_pk_mul_f32 v[10:11], v[228:229], v[52:53] op_sel_hi:[1,0]
	v_pk_mul_f32 v[12:13], v[230:231], v[52:53] op_sel_hi:[1,0]
	v_pk_mul_f32 v[14:15], v[232:233], v[52:53] op_sel_hi:[1,0]
	v_pk_mul_f32 v[16:17], v[234:235], v[52:53] op_sel_hi:[1,0]
	v_pk_mul_f32 v[18:19], v[236:237], v[52:53] op_sel_hi:[1,0]
	v_pk_mul_f32 v[20:21], v[238:239], v[52:53] op_sel_hi:[1,0]
	v_pk_mul_f32 v[6:7], v[80:81], v[6:7]
	v_pk_mul_f32 v[8:9], v[82:83], v[8:9]
	v_pk_mul_f32 v[10:11], v[84:85], v[10:11]
	v_pk_mul_f32 v[12:13], v[86:87], v[12:13]
	v_pk_mul_f32 v[14:15], v[88:89], v[14:15]
	v_pk_mul_f32 v[16:17], v[90:91], v[16:17]
	v_pk_mul_f32 v[18:19], v[92:93], v[18:19]
	v_pk_mul_f32 v[20:21], v[94:95], v[20:21]
	v_cvt_pk_bf16_f32 v240, v6, v7
	v_cvt_pk_bf16_f32 v241, v8, v9
	v_cvt_pk_bf16_f32 v242, v10, v11
	v_cvt_pk_bf16_f32 v243, v12, v13
	v_cvt_pk_bf16_f32 v244, v14, v15
	v_cvt_pk_bf16_f32 v245, v16, v17
	v_cvt_pk_bf16_f32 v246, v18, v19
	v_cvt_pk_bf16_f32 v247, v20, v21
	global_store_dwordx2 v2, v[240:241], s[40:41] offset:0
	global_store_dwordx2 v2, v[242:243], s[40:41] offset:512
	global_store_dwordx2 v2, v[244:245], s[40:41] offset:1024
	global_store_dwordx2 v2, v[246:247], s[40:41] offset:1536
	ds_read_b128 v[26:29], v5 offset:0
	ds_read_b128 v[30:33], v5 offset:1024
	ds_read_b128 v[34:37], v5 offset:2048
	ds_read_b128 v[38:41], v5 offset:3072
	ds_read_b128 v[42:45], v5 offset:4096
	ds_read_b128 v[46:49], v5 offset:5120
	ds_read_b128 v[50:53], v5 offset:6144
	ds_read_b128 v[54:57], v5 offset:7168
	ds_read_b128 v[58:61], v5 offset:8192
	ds_read_b128 v[62:65], v5 offset:9216
	ds_read_b128 v[66:69], v5 offset:10240
	ds_read_b128 v[70:73], v5 offset:11264
	s_waitcnt lgkmcnt(8)
	v_pk_fma_f32 v[28:29], v[8:9], v[28:29], 0 op_sel_hi:[1,1,0]
	v_pk_fma_f32 v[26:27], v[6:7], v[26:27], 0 op_sel_hi:[1,1,0]
	v_pk_fma_f32 v[28:29], v[12:13], v[32:33], v[28:29]
	v_pk_fma_f32 v[26:27], v[10:11], v[30:31], v[26:27]
	v_pk_fma_f32 v[28:29], v[16:17], v[36:37], v[28:29]
	v_pk_fma_f32 v[26:27], v[14:15], v[34:35], v[26:27]
	v_pk_fma_f32 v[28:29], v[20:21], v[40:41], v[28:29]
	v_pk_fma_f32 v[26:27], v[18:19], v[38:39], v[26:27]
	s_waitcnt lgkmcnt(4)
	v_pk_fma_f32 v[44:45], v[8:9], v[44:45], 0 op_sel_hi:[1,1,0]
	v_pk_fma_f32 v[42:43], v[6:7], v[42:43], 0 op_sel_hi:[1,1,0]
	v_pk_fma_f32 v[44:45], v[12:13], v[48:49], v[44:45]
	v_pk_fma_f32 v[42:43], v[10:11], v[46:47], v[42:43]
	v_pk_fma_f32 v[44:45], v[16:17], v[52:53], v[44:45]
	v_pk_fma_f32 v[42:43], v[14:15], v[50:51], v[42:43]
	v_pk_fma_f32 v[44:45], v[20:21], v[56:57], v[44:45]
	v_pk_fma_f32 v[42:43], v[18:19], v[54:55], v[42:43]
	s_waitcnt lgkmcnt(0)
	v_pk_fma_f32 v[60:61], v[8:9], v[60:61], 0 op_sel_hi:[1,1,0]
	v_pk_fma_f32 v[58:59], v[6:7], v[58:59], 0 op_sel_hi:[1,1,0]
	v_pk_fma_f32 v[60:61], v[12:13], v[64:65], v[60:61]
	v_pk_fma_f32 v[58:59], v[10:11], v[62:63], v[58:59]
	v_pk_fma_f32 v[60:61], v[16:17], v[68:69], v[60:61]
	v_pk_fma_f32 v[58:59], v[14:15], v[66:67], v[58:59]
	v_pk_fma_f32 v[60:61], v[20:21], v[72:73], v[60:61]
	v_pk_fma_f32 v[58:59], v[18:19], v[70:71], v[58:59]
	v_add_f32_e32 v30, v28, v29
	v_add_f32_e32 v46, v44, v45
	v_add_f32_e32 v62, v60, v61
	v_add_f32_e32 v26, v26, v27
	v_add_f32_e32 v42, v42, v43
	v_add_f32_e32 v58, v58, v59
	v_mov_b32_e32 v31, 0
	v_mov_b32_e32 v47, 0
	v_mov_b32_e32 v63, 0
	v_add_f32_e32 v26, v26, v30
	v_add_f32_e32 v42, v42, v46
	v_add_f32_e32 v58, v58, v62
	v_mov_b32_e32 v32, 0
	v_mov_b32_e32 v48, 0
	v_mov_b32_e32 v64, 0
	v_add_f32_dpp v26, v26, v26 quad_perm:[1,0,3,2] row_mask:0xf bank_mask:0xf bound_ctrl:1
	v_add_f32_dpp v42, v42, v42 quad_perm:[1,0,3,2] row_mask:0xf bank_mask:0xf bound_ctrl:1
	v_add_f32_dpp v58, v58, v58 quad_perm:[1,0,3,2] row_mask:0xf bank_mask:0xf bound_ctrl:1
	v_add_f32_dpp v26, v26, v26 quad_perm:[2,3,0,1] row_mask:0xf bank_mask:0xf bound_ctrl:1
	v_add_f32_dpp v42, v42, v42 quad_perm:[2,3,0,1] row_mask:0xf bank_mask:0xf bound_ctrl:1
	v_add_f32_dpp v58, v58, v58 quad_perm:[2,3,0,1] row_mask:0xf bank_mask:0xf bound_ctrl:1
	v_add_f32_dpp v26, v26, v26 row_half_mirror row_mask:0xf bank_mask:0xf bound_ctrl:1
	v_add_f32_dpp v42, v42, v42 row_half_mirror row_mask:0xf bank_mask:0xf bound_ctrl:1
	v_add_f32_dpp v58, v58, v58 row_half_mirror row_mask:0xf bank_mask:0xf bound_ctrl:1
	v_add_f32_dpp v26, v26, v26 row_mirror row_mask:0xf bank_mask:0xf bound_ctrl:1
	v_add_f32_dpp v42, v42, v42 row_mirror row_mask:0xf bank_mask:0xf bound_ctrl:1
	v_add_f32_dpp v58, v58, v58 row_mirror row_mask:0xf bank_mask:0xf bound_ctrl:1
	v_mov_b32_dpp v31, v26 row_bcast:15 row_mask:0xa bank_mask:0xf
	v_mov_b32_dpp v47, v42 row_bcast:15 row_mask:0xa bank_mask:0xf
	v_mov_b32_dpp v63, v58 row_bcast:15 row_mask:0xa bank_mask:0xf
	v_add_f32_e32 v26, v26, v31
	v_add_f32_e32 v42, v42, v47
	v_add_f32_e32 v58, v58, v63
	v_mov_b32_dpp v32, v26 row_bcast:31 row_mask:0xc bank_mask:0xf
	v_mov_b32_dpp v48, v42 row_bcast:31 row_mask:0xc bank_mask:0xf
	v_mov_b32_dpp v64, v58 row_bcast:31 row_mask:0xc bank_mask:0xf
	v_add_f32_e32 v26, v26, v32
	v_add_f32_e32 v42, v42, v48
	v_add_f32_e32 v58, v58, v64
	s_nop 0
	v_readlane_b32 s16, v26, 63
	v_readlane_b32 s17, v42, 63
	v_readlane_b32 s18, v58, 63
	v_writelane_b32 v1, s16, 0
	v_writelane_b32 v1, s17, 1
	v_writelane_b32 v1, s18, 2
	ds_read_b128 v[26:29], v5 offset:12288
	ds_read_b128 v[30:33], v5 offset:13312
	ds_read_b128 v[34:37], v5 offset:14336
	ds_read_b128 v[38:41], v5 offset:15360
	ds_read_b128 v[42:45], v5 offset:16384
	ds_read_b128 v[46:49], v5 offset:17408
	ds_read_b128 v[50:53], v5 offset:18432
	ds_read_b128 v[54:57], v5 offset:19456
	ds_read_b128 v[58:61], v5 offset:20480
	ds_read_b128 v[62:65], v5 offset:21504
	ds_read_b128 v[66:69], v5 offset:22528
	ds_read_b128 v[70:73], v5 offset:23552
	s_waitcnt lgkmcnt(8)
	v_pk_fma_f32 v[28:29], v[8:9], v[28:29], 0 op_sel_hi:[1,1,0]
	v_pk_fma_f32 v[26:27], v[6:7], v[26:27], 0 op_sel_hi:[1,1,0]
	v_pk_fma_f32 v[28:29], v[12:13], v[32:33], v[28:29]
	v_pk_fma_f32 v[26:27], v[10:11], v[30:31], v[26:27]
	v_pk_fma_f32 v[28:29], v[16:17], v[36:37], v[28:29]
	v_pk_fma_f32 v[26:27], v[14:15], v[34:35], v[26:27]
	v_pk_fma_f32 v[28:29], v[20:21], v[40:41], v[28:29]
	v_pk_fma_f32 v[26:27], v[18:19], v[38:39], v[26:27]
	s_waitcnt lgkmcnt(4)
	v_pk_fma_f32 v[44:45], v[8:9], v[44:45], 0 op_sel_hi:[1,1,0]
	v_pk_fma_f32 v[42:43], v[6:7], v[42:43], 0 op_sel_hi:[1,1,0]
	v_pk_fma_f32 v[44:45], v[12:13], v[48:49], v[44:45]
	v_pk_fma_f32 v[42:43], v[10:11], v[46:47], v[42:43]
	v_pk_fma_f32 v[44:45], v[16:17], v[52:53], v[44:45]
	v_pk_fma_f32 v[42:43], v[14:15], v[50:51], v[42:43]
	v_pk_fma_f32 v[44:45], v[20:21], v[56:57], v[44:45]
	v_pk_fma_f32 v[42:43], v[18:19], v[54:55], v[42:43]
	s_waitcnt lgkmcnt(0)
	v_pk_fma_f32 v[60:61], v[8:9], v[60:61], 0 op_sel_hi:[1,1,0]
	v_pk_fma_f32 v[58:59], v[6:7], v[58:59], 0 op_sel_hi:[1,1,0]
	v_pk_fma_f32 v[60:61], v[12:13], v[64:65], v[60:61]
	v_pk_fma_f32 v[58:59], v[10:11], v[62:63], v[58:59]
	v_pk_fma_f32 v[60:61], v[16:17], v[68:69], v[60:61]
	v_pk_fma_f32 v[58:59], v[14:15], v[66:67], v[58:59]
	v_pk_fma_f32 v[60:61], v[20:21], v[72:73], v[60:61]
	v_pk_fma_f32 v[58:59], v[18:19], v[70:71], v[58:59]
	v_add_f32_e32 v30, v28, v29
	v_add_f32_e32 v46, v44, v45
	v_add_f32_e32 v62, v60, v61
	v_add_f32_e32 v26, v26, v27
	v_add_f32_e32 v42, v42, v43
	v_add_f32_e32 v58, v58, v59
	v_mov_b32_e32 v31, 0
	v_mov_b32_e32 v47, 0
	v_mov_b32_e32 v63, 0
	v_add_f32_e32 v26, v26, v30
	v_add_f32_e32 v42, v42, v46
	v_add_f32_e32 v58, v58, v62
	v_mov_b32_e32 v32, 0
	v_mov_b32_e32 v48, 0
	v_mov_b32_e32 v64, 0
	v_add_f32_dpp v26, v26, v26 quad_perm:[1,0,3,2] row_mask:0xf bank_mask:0xf bound_ctrl:1
	v_add_f32_dpp v42, v42, v42 quad_perm:[1,0,3,2] row_mask:0xf bank_mask:0xf bound_ctrl:1
	v_add_f32_dpp v58, v58, v58 quad_perm:[1,0,3,2] row_mask:0xf bank_mask:0xf bound_ctrl:1
	v_add_f32_dpp v26, v26, v26 quad_perm:[2,3,0,1] row_mask:0xf bank_mask:0xf bound_ctrl:1
	v_add_f32_dpp v42, v42, v42 quad_perm:[2,3,0,1] row_mask:0xf bank_mask:0xf bound_ctrl:1
	v_add_f32_dpp v58, v58, v58 quad_perm:[2,3,0,1] row_mask:0xf bank_mask:0xf bound_ctrl:1
	v_add_f32_dpp v26, v26, v26 row_half_mirror row_mask:0xf bank_mask:0xf bound_ctrl:1
	v_add_f32_dpp v42, v42, v42 row_half_mirror row_mask:0xf bank_mask:0xf bound_ctrl:1
	v_add_f32_dpp v58, v58, v58 row_half_mirror row_mask:0xf bank_mask:0xf bound_ctrl:1
	v_add_f32_dpp v26, v26, v26 row_mirror row_mask:0xf bank_mask:0xf bound_ctrl:1
	v_add_f32_dpp v42, v42, v42 row_mirror row_mask:0xf bank_mask:0xf bound_ctrl:1
	v_add_f32_dpp v58, v58, v58 row_mirror row_mask:0xf bank_mask:0xf bound_ctrl:1
	v_mov_b32_dpp v31, v26 row_bcast:15 row_mask:0xa bank_mask:0xf
	v_mov_b32_dpp v47, v42 row_bcast:15 row_mask:0xa bank_mask:0xf
	v_mov_b32_dpp v63, v58 row_bcast:15 row_mask:0xa bank_mask:0xf
	v_add_f32_e32 v26, v26, v31
	v_add_f32_e32 v42, v42, v47
	v_add_f32_e32 v58, v58, v63
	v_mov_b32_dpp v32, v26 row_bcast:31 row_mask:0xc bank_mask:0xf
	v_mov_b32_dpp v48, v42 row_bcast:31 row_mask:0xc bank_mask:0xf
	v_mov_b32_dpp v64, v58 row_bcast:31 row_mask:0xc bank_mask:0xf
	v_add_f32_e32 v26, v26, v32
	v_add_f32_e32 v42, v42, v48
	v_add_f32_e32 v58, v58, v64
	s_nop 0
	v_readlane_b32 s16, v26, 63
	v_readlane_b32 s17, v42, 63
	v_readlane_b32 s18, v58, 63
	v_writelane_b32 v1, s16, 3
	v_writelane_b32 v1, s17, 4
	v_writelane_b32 v1, s18, 5
	ds_read_b128 v[26:29], v5 offset:24576
	ds_read_b128 v[30:33], v5 offset:25600
	ds_read_b128 v[34:37], v5 offset:26624
	ds_read_b128 v[38:41], v5 offset:27648
	ds_read_b128 v[42:45], v5 offset:28672
	ds_read_b128 v[46:49], v5 offset:29696
	ds_read_b128 v[50:53], v5 offset:30720
	ds_read_b128 v[54:57], v5 offset:31744
	ds_read_b128 v[58:61], v5 offset:32768
	ds_read_b128 v[62:65], v5 offset:33792
	ds_read_b128 v[66:69], v5 offset:34816
	ds_read_b128 v[70:73], v5 offset:35840
	s_waitcnt lgkmcnt(8)
	v_pk_fma_f32 v[28:29], v[8:9], v[28:29], 0 op_sel_hi:[1,1,0]
	v_pk_fma_f32 v[26:27], v[6:7], v[26:27], 0 op_sel_hi:[1,1,0]
	v_pk_fma_f32 v[28:29], v[12:13], v[32:33], v[28:29]
	v_pk_fma_f32 v[26:27], v[10:11], v[30:31], v[26:27]
	v_pk_fma_f32 v[28:29], v[16:17], v[36:37], v[28:29]
	v_pk_fma_f32 v[26:27], v[14:15], v[34:35], v[26:27]
	v_pk_fma_f32 v[28:29], v[20:21], v[40:41], v[28:29]
	v_pk_fma_f32 v[26:27], v[18:19], v[38:39], v[26:27]
	s_waitcnt lgkmcnt(4)
	v_pk_fma_f32 v[44:45], v[8:9], v[44:45], 0 op_sel_hi:[1,1,0]
	v_pk_fma_f32 v[42:43], v[6:7], v[42:43], 0 op_sel_hi:[1,1,0]
	v_pk_fma_f32 v[44:45], v[12:13], v[48:49], v[44:45]
	v_pk_fma_f32 v[42:43], v[10:11], v[46:47], v[42:43]
	v_pk_fma_f32 v[44:45], v[16:17], v[52:53], v[44:45]
	v_pk_fma_f32 v[42:43], v[14:15], v[50:51], v[42:43]
	v_pk_fma_f32 v[44:45], v[20:21], v[56:57], v[44:45]
	v_pk_fma_f32 v[42:43], v[18:19], v[54:55], v[42:43]
	s_waitcnt lgkmcnt(0)
	v_pk_fma_f32 v[60:61], v[8:9], v[60:61], 0 op_sel_hi:[1,1,0]
	v_pk_fma_f32 v[58:59], v[6:7], v[58:59], 0 op_sel_hi:[1,1,0]
	v_pk_fma_f32 v[60:61], v[12:13], v[64:65], v[60:61]
	v_pk_fma_f32 v[58:59], v[10:11], v[62:63], v[58:59]
	v_pk_fma_f32 v[60:61], v[16:17], v[68:69], v[60:61]
	v_pk_fma_f32 v[58:59], v[14:15], v[66:67], v[58:59]
	v_pk_fma_f32 v[60:61], v[20:21], v[72:73], v[60:61]
	v_pk_fma_f32 v[58:59], v[18:19], v[70:71], v[58:59]
	v_add_f32_e32 v30, v28, v29
	v_add_f32_e32 v46, v44, v45
	v_add_f32_e32 v62, v60, v61
	v_add_f32_e32 v26, v26, v27
	v_add_f32_e32 v42, v42, v43
	v_add_f32_e32 v58, v58, v59
	v_mov_b32_e32 v31, 0
	v_mov_b32_e32 v47, 0
	v_mov_b32_e32 v63, 0
	v_add_f32_e32 v26, v26, v30
	v_add_f32_e32 v42, v42, v46
	v_add_f32_e32 v58, v58, v62
	v_mov_b32_e32 v32, 0
	v_mov_b32_e32 v48, 0
	v_mov_b32_e32 v64, 0
	v_add_f32_dpp v26, v26, v26 quad_perm:[1,0,3,2] row_mask:0xf bank_mask:0xf bound_ctrl:1
	v_add_f32_dpp v42, v42, v42 quad_perm:[1,0,3,2] row_mask:0xf bank_mask:0xf bound_ctrl:1
	v_add_f32_dpp v58, v58, v58 quad_perm:[1,0,3,2] row_mask:0xf bank_mask:0xf bound_ctrl:1
	v_add_f32_dpp v26, v26, v26 quad_perm:[2,3,0,1] row_mask:0xf bank_mask:0xf bound_ctrl:1
	v_add_f32_dpp v42, v42, v42 quad_perm:[2,3,0,1] row_mask:0xf bank_mask:0xf bound_ctrl:1
	v_add_f32_dpp v58, v58, v58 quad_perm:[2,3,0,1] row_mask:0xf bank_mask:0xf bound_ctrl:1
	v_add_f32_dpp v26, v26, v26 row_half_mirror row_mask:0xf bank_mask:0xf bound_ctrl:1
	v_add_f32_dpp v42, v42, v42 row_half_mirror row_mask:0xf bank_mask:0xf bound_ctrl:1
	v_add_f32_dpp v58, v58, v58 row_half_mirror row_mask:0xf bank_mask:0xf bound_ctrl:1
	v_add_f32_dpp v26, v26, v26 row_mirror row_mask:0xf bank_mask:0xf bound_ctrl:1
	v_add_f32_dpp v42, v42, v42 row_mirror row_mask:0xf bank_mask:0xf bound_ctrl:1
	v_add_f32_dpp v58, v58, v58 row_mirror row_mask:0xf bank_mask:0xf bound_ctrl:1
	v_mov_b32_dpp v31, v26 row_bcast:15 row_mask:0xa bank_mask:0xf
	v_mov_b32_dpp v47, v42 row_bcast:15 row_mask:0xa bank_mask:0xf
	v_mov_b32_dpp v63, v58 row_bcast:15 row_mask:0xa bank_mask:0xf
	v_add_f32_e32 v26, v26, v31
	v_add_f32_e32 v42, v42, v47
	v_add_f32_e32 v58, v58, v63
	v_mov_b32_dpp v32, v26 row_bcast:31 row_mask:0xc bank_mask:0xf
	v_mov_b32_dpp v48, v42 row_bcast:31 row_mask:0xc bank_mask:0xf
	v_mov_b32_dpp v64, v58 row_bcast:31 row_mask:0xc bank_mask:0xf
	v_add_f32_e32 v26, v26, v32
	v_add_f32_e32 v42, v42, v48
	v_add_f32_e32 v58, v58, v64
	s_nop 0
	v_readlane_b32 s16, v26, 63
	v_readlane_b32 s17, v42, 63
	v_readlane_b32 s18, v58, 63
	v_writelane_b32 v1, s16, 6
	v_writelane_b32 v1, s17, 7
	v_writelane_b32 v1, s18, 8
	ds_read_b128 v[26:29], v5 offset:36864
	ds_read_b128 v[30:33], v5 offset:37888
	ds_read_b128 v[34:37], v5 offset:38912
	ds_read_b128 v[38:41], v5 offset:39936
	ds_read_b128 v[42:45], v5 offset:40960
	ds_read_b128 v[46:49], v5 offset:41984
	ds_read_b128 v[50:53], v5 offset:43008
	ds_read_b128 v[54:57], v5 offset:44032
	ds_read_b128 v[58:61], v5 offset:45056
	ds_read_b128 v[62:65], v5 offset:46080
	ds_read_b128 v[66:69], v5 offset:47104
	ds_read_b128 v[70:73], v5 offset:48128
	s_waitcnt lgkmcnt(8)
	v_pk_fma_f32 v[28:29], v[8:9], v[28:29], 0 op_sel_hi:[1,1,0]
	v_pk_fma_f32 v[26:27], v[6:7], v[26:27], 0 op_sel_hi:[1,1,0]
	v_pk_fma_f32 v[28:29], v[12:13], v[32:33], v[28:29]
	v_pk_fma_f32 v[26:27], v[10:11], v[30:31], v[26:27]
	v_pk_fma_f32 v[28:29], v[16:17], v[36:37], v[28:29]
	v_pk_fma_f32 v[26:27], v[14:15], v[34:35], v[26:27]
	v_pk_fma_f32 v[28:29], v[20:21], v[40:41], v[28:29]
	v_pk_fma_f32 v[26:27], v[18:19], v[38:39], v[26:27]
	s_waitcnt lgkmcnt(4)
	v_pk_fma_f32 v[44:45], v[8:9], v[44:45], 0 op_sel_hi:[1,1,0]
	v_pk_fma_f32 v[42:43], v[6:7], v[42:43], 0 op_sel_hi:[1,1,0]
	v_pk_fma_f32 v[44:45], v[12:13], v[48:49], v[44:45]
	v_pk_fma_f32 v[42:43], v[10:11], v[46:47], v[42:43]
	v_pk_fma_f32 v[44:45], v[16:17], v[52:53], v[44:45]
	v_pk_fma_f32 v[42:43], v[14:15], v[50:51], v[42:43]
	v_pk_fma_f32 v[44:45], v[20:21], v[56:57], v[44:45]
	v_pk_fma_f32 v[42:43], v[18:19], v[54:55], v[42:43]
	s_waitcnt lgkmcnt(0)
	v_pk_fma_f32 v[60:61], v[8:9], v[60:61], 0 op_sel_hi:[1,1,0]
	v_pk_fma_f32 v[58:59], v[6:7], v[58:59], 0 op_sel_hi:[1,1,0]
	v_pk_fma_f32 v[60:61], v[12:13], v[64:65], v[60:61]
	v_pk_fma_f32 v[58:59], v[10:11], v[62:63], v[58:59]
	v_pk_fma_f32 v[60:61], v[16:17], v[68:69], v[60:61]
	v_pk_fma_f32 v[58:59], v[14:15], v[66:67], v[58:59]
	v_pk_fma_f32 v[60:61], v[20:21], v[72:73], v[60:61]
	v_pk_fma_f32 v[58:59], v[18:19], v[70:71], v[58:59]
	v_add_f32_e32 v30, v28, v29
	v_add_f32_e32 v46, v44, v45
	v_add_f32_e32 v62, v60, v61
	v_add_f32_e32 v26, v26, v27
	v_add_f32_e32 v42, v42, v43
	v_add_f32_e32 v58, v58, v59
	v_mov_b32_e32 v31, 0
	v_mov_b32_e32 v47, 0
	v_mov_b32_e32 v63, 0
	v_add_f32_e32 v26, v26, v30
	v_add_f32_e32 v42, v42, v46
	v_add_f32_e32 v58, v58, v62
	v_mov_b32_e32 v32, 0
	v_mov_b32_e32 v48, 0
	v_mov_b32_e32 v64, 0
	v_add_f32_dpp v26, v26, v26 quad_perm:[1,0,3,2] row_mask:0xf bank_mask:0xf bound_ctrl:1
	v_add_f32_dpp v42, v42, v42 quad_perm:[1,0,3,2] row_mask:0xf bank_mask:0xf bound_ctrl:1
	v_add_f32_dpp v58, v58, v58 quad_perm:[1,0,3,2] row_mask:0xf bank_mask:0xf bound_ctrl:1
	v_add_f32_dpp v26, v26, v26 quad_perm:[2,3,0,1] row_mask:0xf bank_mask:0xf bound_ctrl:1
	v_add_f32_dpp v42, v42, v42 quad_perm:[2,3,0,1] row_mask:0xf bank_mask:0xf bound_ctrl:1
	v_add_f32_dpp v58, v58, v58 quad_perm:[2,3,0,1] row_mask:0xf bank_mask:0xf bound_ctrl:1
	v_add_f32_dpp v26, v26, v26 row_half_mirror row_mask:0xf bank_mask:0xf bound_ctrl:1
	v_add_f32_dpp v42, v42, v42 row_half_mirror row_mask:0xf bank_mask:0xf bound_ctrl:1
	v_add_f32_dpp v58, v58, v58 row_half_mirror row_mask:0xf bank_mask:0xf bound_ctrl:1
	v_add_f32_dpp v26, v26, v26 row_mirror row_mask:0xf bank_mask:0xf bound_ctrl:1
	v_add_f32_dpp v42, v42, v42 row_mirror row_mask:0xf bank_mask:0xf bound_ctrl:1
	v_add_f32_dpp v58, v58, v58 row_mirror row_mask:0xf bank_mask:0xf bound_ctrl:1
	v_mov_b32_dpp v31, v26 row_bcast:15 row_mask:0xa bank_mask:0xf
	v_mov_b32_dpp v47, v42 row_bcast:15 row_mask:0xa bank_mask:0xf
	v_mov_b32_dpp v63, v58 row_bcast:15 row_mask:0xa bank_mask:0xf
	v_add_f32_e32 v26, v26, v31
	v_add_f32_e32 v42, v42, v47
	v_add_f32_e32 v58, v58, v63
	v_mov_b32_dpp v32, v26 row_bcast:31 row_mask:0xc bank_mask:0xf
	v_mov_b32_dpp v48, v42 row_bcast:31 row_mask:0xc bank_mask:0xf
	v_mov_b32_dpp v64, v58 row_bcast:31 row_mask:0xc bank_mask:0xf
	v_add_f32_e32 v26, v26, v32
	v_add_f32_e32 v42, v42, v48
	v_add_f32_e32 v58, v58, v64
	s_nop 0
	v_readlane_b32 s16, v26, 63
	v_readlane_b32 s17, v42, 63
	v_readlane_b32 s18, v58, 63
	v_writelane_b32 v1, s16, 9
	v_writelane_b32 v1, s17, 10
	v_writelane_b32 v1, s18, 11
	s_mov_b64 s[26:27], exec
	s_mov_b32 exec_lo, 0xfff
	s_mov_b32 exec_hi, 0
	global_store_dword v25, v1, s[42:43]
	s_mov_b64 exec, s[26:27]
.Lp0n_done:
.LBB0_54:
	s_cmp_gt_i32 s89, 1
	s_barrier
	s_cbranch_scc0 .LBB0_100
	v_readlane_b32 s33, v254, 5
	s_mov_b64 s[34:35], s[84:85]
	s_waitcnt vmcnt(0)
	v_cmp_eq_u32_e32 vcc, 0, v4
	s_barrier
	s_and_saveexec_b64 s[0:1], vcc
	s_cbranch_execz .LBB0_99
	v_readlane_b32 s2, v254, 6
	s_waitcnt vmcnt(0) expcnt(0) lgkmcnt(0)
	s_nop 0
	v_mov_b32_e32 v0, s2
	ds_read_b32 v2, v0
	ds_read_b32 v0, v0 offset:4
	s_waitcnt lgkmcnt(1)
	v_cmp_ne_u32_e32 vcc, 0, v2
	s_cbranch_vccnz .LBB0_70
	v_readlane_b32 s4, v254, 1
	v_readlane_b32 s5, v254, 2
	s_load_dwordx2 s[2:3], s[4:5], 0x4
	s_add_u32 s4, s34, 0x1000
	s_addc_u32 s5, s35, 0
	s_add_u32 s6, s34, 0x1100
	s_addc_u32 s7, s35, 0
	s_add_u32 s8, s34, 0x1200
	s_addc_u32 s9, s35, 0
	s_add_u32 s10, s34, 0x1300
	s_waitcnt lgkmcnt(0)
	s_mul_i32 s20, s2, s90
	s_addc_u32 s11, s35, 0
	s_mul_i32 s20, s20, s3
	s_mov_b32 s21, 1
	s_mov_b64 s[2:3], 0
	v_mov_b64_e32 v[0:1], s[34:35]
	v_mov_b64_e32 v[2:3], s[4:5]
	v_mov_b64_e32 v[4:5], s[6:7]
	v_mov_b64_e32 v[6:7], s[8:9]
	v_mov_b64_e32 v[8:9], s[10:11]
	s_branch .LBB0_60
